# gdn_k1 forward substitution hand-written: packed f32 FMAs (v_pk_fma_f32) on the four partial sums, M rows prefetched one row ahead, column stores interleaved
# speedup vs baseline: 1.0104x; 1.0104x over previous
.LBB0_570:
	s_or_b64 exec, exec, s[42:43]
	s_waitcnt lgkmcnt(1)
	v_mul_f32_e32 v4, v4, v35
	v_cmp_lt_i32_e64 s[0:1], v61, v44
	v_mul_f32_e32 v4, v4, v60
	v_mul_f32_e32 v3, v3, v35
	v_cndmask_b32_e64 v4, 0, v4, s[0:1]
	v_cmp_lt_i32_e64 s[0:1], v59, v44
	v_mul_f32_e32 v3, v3, v25
	v_mul_f32_e32 v2, v2, v35
	v_cndmask_b32_e64 v3, 0, v3, s[0:1]
	v_cmp_lt_i32_e64 s[0:1], v24, v44
	v_mul_f32_e32 v2, v2, v58
	v_mul_f32_e32 v9, v9, v35
	v_cndmask_b32_e64 v2, 0, v2, s[0:1]
	v_cmp_lt_i32_e64 s[0:1], v56, v44
	v_mul_f32_e32 v9, v9, v57
	v_mul_f32_e32 v8, v8, v35
	v_cndmask_b32_e64 v9, 0, v9, s[0:1]
	v_cmp_lt_i32_e64 s[0:1], v55, v44
	v_mul_f32_e32 v8, v8, v29
	v_mul_f32_e32 v7, v7, v35
	v_cndmask_b32_e64 v8, 0, v8, s[0:1]
	v_cmp_lt_i32_e64 s[0:1], v27, v44
	v_mul_f32_e32 v7, v7, v28
	v_mul_f32_e32 v6, v6, v35
	v_cndmask_b32_e64 v7, 0, v7, s[0:1]
	v_cmp_lt_i32_e64 s[0:1], v26, v44
	v_mul_f32_e32 v6, v6, v54
	v_mul_f32_e32 v13, v13, v35
	v_cndmask_b32_e64 v6, 0, v6, s[0:1]
	v_cmp_lt_i32_e64 s[0:1], v52, v44
	v_mul_f32_e32 v13, v13, v53
	v_mul_f32_e32 v12, v12, v35
	v_cndmask_b32_e64 v13, 0, v13, s[0:1]
	v_cmp_lt_i32_e64 s[0:1], v51, v44
	v_mul_f32_e32 v12, v12, v50
	v_mul_f32_e32 v11, v11, v35
	v_cndmask_b32_e64 v12, 0, v12, s[0:1]
	v_cmp_lt_i32_e64 s[0:1], v32, v44
	v_mul_f32_e32 v11, v11, v33
	v_mul_f32_e32 v20, v20, v60
	v_cndmask_b32_e64 v11, 0, v11, s[0:1]
	v_cmp_lt_i32_e64 s[0:1], v0, v44
	v_mul_f32_e32 v0, v10, v35
	v_mul_f32_e32 v0, v0, v48
	v_cndmask_b32_e64 v10, 0, v0, s[0:1]
	v_mul_f32_e32 v0, v17, v35
	v_cmp_lt_i32_e64 s[0:1], v46, v44
	v_mul_f32_e32 v0, v0, v47
	v_mul_f32_e32 v19, v19, v25
	v_cndmask_b32_e64 v17, 0, v0, s[0:1]
	v_mul_f32_e32 v0, v16, v35
	v_cmp_lt_i32_e64 s[0:1], v45, v44
	v_mul_f32_e32 v0, v0, v38
	v_mul_f32_e32 v18, v18, v58
	v_cndmask_b32_e64 v16, 0, v0, s[0:1]
	v_or_b32_e32 v0, 1, v36
	v_cmp_lt_i32_e64 s[0:1], v0, v44
	v_mul_f32_e32 v0, v15, v35
	v_mul_f32_e32 v0, v0, v39
	v_cndmask_b32_e64 v15, 0, v0, s[0:1]
	v_mul_f32_e32 v0, v14, v35
	v_mul_f32_e32 v0, v0, v37
	v_cndmask_b32_e32 v14, 0, v0, vcc
	v_mul_f32_e32 v0, v5, v35
	v_cmp_lt_i32_e32 vcc, v23, v44
	v_mul_f32_e32 v0, v0, v22
	v_cvt_pk_bf16_f32 v18, v18, v19
	v_cndmask_b32_e32 v5, 0, v0, vcc
	v_mul_f32_e32 v0, v21, v22
	v_cvt_pk_bf16_f32 v19, v20, v0
	v_lshl_add_u32 v20, v43, 2, 0
	ds_read_b32 v0, v20 offset:52224
	v_readlane_b32 s4, v239, 2
	v_readlane_b32 s5, v239, 3
	global_store_dwordx2 v[30:31], v[18:19], off offset:96
	s_lshl_b32 s2, s2, 1
	s_waitcnt lgkmcnt(0)
	v_mul_f32_e32 v0, 0x3fb8aa3b, v0
	v_exp_f32_e32 v34, v0
	v_add_u32_e32 v0, s41, v43
	v_mov_b64_e32 v[18:19], s[4:5]
	v_mad_i64_i32 v[18:19], s[0:1], v0, s85, v[18:19]
	v_lshlrev_b32_e32 v0, 6, v40
	v_lshl_add_u64 v[18:19], v[18:19], 0, s[2:3]
	v_and_b32_e32 v0, 0xc0, v0
	s_movk_i32 s0, 0x10c
	v_lshl_add_u64 v[36:37], v[18:19], 0, v[0:1]
	v_mul_lo_u32 v18, v43, s0
	v_add3_u32 v0, v20, v18, v0
	ds_read_b128 v[18:21], v0
	ds_read_b128 v[22:25], v0 offset:16
	ds_read_b128 v[26:29], v0 offset:32
	ds_read_b128 v[30:33], v0 offset:48
	v_and_b32_e32 v0, 0x7f, v40
	s_waitcnt lgkmcnt(3)
	v_lshlrev_b32_e32 v38, 16, v18
	v_and_b32_e32 v39, 0xffff0000, v18
	v_pk_mul_f32 v[38:39], v[34:35], v[38:39] op_sel_hi:[0,1]
	v_cvt_pk_bf16_f32 v18, v38, v39
	v_lshlrev_b32_e32 v38, 16, v19
	v_and_b32_e32 v39, 0xffff0000, v19
	v_pk_mul_f32 v[38:39], v[34:35], v[38:39] op_sel_hi:[0,1]
	v_cvt_pk_bf16_f32 v19, v38, v39
	v_lshlrev_b32_e32 v38, 16, v20
	v_and_b32_e32 v39, 0xffff0000, v20
	v_pk_mul_f32 v[38:39], v[34:35], v[38:39] op_sel_hi:[0,1]
	v_cvt_pk_bf16_f32 v20, v38, v39
	v_lshlrev_b32_e32 v38, 16, v21
	v_and_b32_e32 v39, 0xffff0000, v21
	v_pk_mul_f32 v[38:39], v[34:35], v[38:39] op_sel_hi:[0,1]
	v_cvt_pk_bf16_f32 v21, v38, v39
	global_store_dwordx4 v[36:37], v[18:21], off
	s_movk_i32 s6, 0x110
	s_waitcnt lgkmcnt(2)
	v_lshlrev_b32_e32 v18, 16, v22
	v_and_b32_e32 v19, 0xffff0000, v22
	v_lshlrev_b32_e32 v20, 16, v23
	v_and_b32_e32 v21, 0xffff0000, v23
	v_pk_mul_f32 v[18:19], v[34:35], v[18:19] op_sel_hi:[0,1]
	v_pk_mul_f32 v[20:21], v[34:35], v[20:21] op_sel_hi:[0,1]
	v_cvt_pk_bf16_f32 v18, v18, v19
	v_cvt_pk_bf16_f32 v19, v20, v21
	v_lshlrev_b32_e32 v20, 16, v24
	v_and_b32_e32 v21, 0xffff0000, v24
	v_lshlrev_b32_e32 v22, 16, v25
	v_and_b32_e32 v23, 0xffff0000, v25
	v_pk_mul_f32 v[20:21], v[34:35], v[20:21] op_sel_hi:[0,1]
	v_pk_mul_f32 v[22:23], v[34:35], v[22:23] op_sel_hi:[0,1]
	v_cvt_pk_bf16_f32 v20, v20, v21
	v_cvt_pk_bf16_f32 v21, v22, v23
	global_store_dwordx4 v[36:37], v[18:21], off offset:16
	s_waitcnt lgkmcnt(1)
	v_lshlrev_b32_e32 v22, 16, v29
	v_and_b32_e32 v23, 0xffff0000, v29
	v_lshlrev_b32_e32 v18, 16, v26
	v_and_b32_e32 v19, 0xffff0000, v26
	v_lshlrev_b32_e32 v20, 16, v27
	v_and_b32_e32 v21, 0xffff0000, v27
	v_pk_mul_f32 v[18:19], v[34:35], v[18:19] op_sel_hi:[0,1]
	v_pk_mul_f32 v[20:21], v[34:35], v[20:21] op_sel_hi:[0,1]
	v_cvt_pk_bf16_f32 v18, v18, v19
	v_cvt_pk_bf16_f32 v19, v20, v21
	v_lshlrev_b32_e32 v20, 16, v28
	v_and_b32_e32 v21, 0xffff0000, v28
	v_pk_mul_f32 v[20:21], v[34:35], v[20:21] op_sel_hi:[0,1]
	v_pk_mul_f32 v[22:23], v[34:35], v[22:23] op_sel_hi:[0,1]
	v_cvt_pk_bf16_f32 v20, v20, v21
	v_cvt_pk_bf16_f32 v21, v22, v23
	global_store_dwordx4 v[36:37], v[18:21], off offset:32
	s_waitcnt lgkmcnt(0)
	v_lshlrev_b32_e32 v22, 16, v33
	v_and_b32_e32 v23, 0xffff0000, v33
	v_lshlrev_b32_e32 v18, 16, v30
	v_and_b32_e32 v19, 0xffff0000, v30
	v_lshlrev_b32_e32 v20, 16, v31
	v_and_b32_e32 v21, 0xffff0000, v31
	v_pk_mul_f32 v[18:19], v[34:35], v[18:19] op_sel_hi:[0,1]
	v_pk_mul_f32 v[20:21], v[34:35], v[20:21] op_sel_hi:[0,1]
	v_cvt_pk_bf16_f32 v18, v18, v19
	v_cvt_pk_bf16_f32 v19, v20, v21
	v_lshlrev_b32_e32 v20, 16, v32
	v_and_b32_e32 v21, 0xffff0000, v32
	v_pk_mul_f32 v[20:21], v[34:35], v[20:21] op_sel_hi:[0,1]
	v_pk_mul_f32 v[22:23], v[34:35], v[22:23] op_sel_hi:[0,1]
	v_cvt_pk_bf16_f32 v20, v20, v21
	v_cvt_pk_bf16_f32 v21, v22, v23
	v_and_b32_e32 v22, 0xffffffe0, v43
	v_lshlrev_b32_e32 v30, 1, v0
	v_lshlrev_b32_e32 v0, 7, v0
	global_store_dwordx4 v[36:37], v[18:21], off offset:48
	v_lshl_add_u64 v[24:25], s[38:39], 0, v[0:1]
	v_lshl_add_u32 v0, v22, 2, 0
	ds_read_b128 v[26:29], v0 offset:52224
	ds_read_b128 v[18:21], v0 offset:52240
	v_add_u32_e32 v34, 0, v30
	v_mad_u64_u32 v[32:33], s[0:1], v22, s6, v[34:35]
	s_waitcnt lgkmcnt(1)
	v_sub_f32_e32 v23, v41, v26
	v_mul_f32_e32 v23, 0x3fb8aa3b, v23
	v_exp_f32_e32 v26, v23
	v_sub_f32_e32 v23, v41, v27
	v_mul_f32_e32 v23, 0x3fb8aa3b, v23
	v_exp_f32_e32 v27, v23
	ds_read_u16 v23, v32 offset:17408
	ds_read_u16 v31, v32 offset:17680
	s_waitcnt lgkmcnt(2)
	v_sub_f32_e32 v18, v41, v18
	v_sub_f32_e32 v19, v41, v19
	v_mul_f32_e32 v18, 0x3fb8aa3b, v18
	s_waitcnt lgkmcnt(1)
	v_lshlrev_b32_e32 v36, 16, v23
	v_sub_f32_e32 v23, v41, v28
	v_mul_f32_e32 v23, 0x3fb8aa3b, v23
	v_exp_f32_e32 v28, v23
	v_sub_f32_e32 v23, v41, v29
	v_mul_f32_e32 v23, 0x3fb8aa3b, v23
	s_waitcnt lgkmcnt(0)
	v_lshlrev_b32_e32 v37, 16, v31
	v_exp_f32_e32 v29, v23
	ds_read_u16 v23, v32 offset:17952
	ds_read_u16 v31, v32 offset:18224
	v_pk_mul_f32 v[26:27], v[26:27], v[36:37]
	v_mul_f32_e32 v19, 0x3fb8aa3b, v19
	v_exp_f32_e32 v18, v18
	s_waitcnt lgkmcnt(1)
	v_lshlrev_b32_e32 v36, 16, v23
	s_waitcnt lgkmcnt(0)
	v_lshlrev_b32_e32 v37, 16, v31
	ds_read_u16 v23, v32 offset:18496
	ds_read_u16 v31, v32 offset:18768
	v_exp_f32_e32 v19, v19
	v_pk_mul_f32 v[28:29], v[28:29], v[36:37]
	s_mov_b64 s[0:1], 0x2000
	s_waitcnt lgkmcnt(1)
	v_lshlrev_b32_e32 v36, 16, v23
	s_waitcnt lgkmcnt(0)
	v_lshlrev_b32_e32 v37, 16, v31
	v_pk_mul_f32 v[36:37], v[18:19], v[36:37]
	v_sub_f32_e32 v18, v41, v20
	v_sub_f32_e32 v19, v41, v21
	ds_read_u16 v20, v32 offset:19040
	ds_read_u16 v21, v32 offset:19312
	v_mul_f32_e32 v18, 0x3fb8aa3b, v18
	v_mul_f32_e32 v19, 0x3fb8aa3b, v19
	v_exp_f32_e32 v18, v18
	v_exp_f32_e32 v19, v19
	v_ashrrev_i32_e32 v23, 31, v22
	s_waitcnt lgkmcnt(0)
	v_lshlrev_b32_e32 v21, 16, v21
	v_lshlrev_b32_e32 v20, 16, v20
	v_lshl_add_u64 v[22:23], v[22:23], 1, v[24:25]
	v_pk_mul_f32 v[38:39], v[18:19], v[20:21]
	v_cvt_pk_bf16_f32 v20, v36, v37
	v_lshl_add_u64 v[36:37], v[22:23], 0, s[0:1]
	v_add_co_u32_e32 v22, vcc, s94, v22
	v_cvt_pk_bf16_f32 v18, v26, v27
	v_cvt_pk_bf16_f32 v19, v28, v29
	v_cvt_pk_bf16_f32 v21, v38, v39
	v_addc_co_u32_e32 v23, vcc, 0, v23, vcc
	global_store_dwordx4 v[22:23], v[18:21], off
	ds_read_b128 v[46:49], v0 offset:52256
	ds_read_b128 v[26:29], v0 offset:52272
	ds_read_b128 v[22:25], v0 offset:52288
	ds_read_b128 v[18:21], v0 offset:52304
	s_waitcnt lgkmcnt(3)
	v_sub_f32_e32 v31, v41, v46
	v_mul_f32_e32 v31, 0x3fb8aa3b, v31
	v_exp_f32_e32 v38, v31
	v_sub_f32_e32 v31, v41, v47
	v_mul_f32_e32 v31, 0x3fb8aa3b, v31
	v_exp_f32_e32 v39, v31
	ds_read_u16 v31, v32 offset:19584
	ds_read_u16 v33, v32 offset:19856
	s_waitcnt lgkmcnt(4)
	v_sub_f32_e32 v26, v41, v26
	v_sub_f32_e32 v27, v41, v27
	v_mul_f32_e32 v26, 0x3fb8aa3b, v26
	s_waitcnt lgkmcnt(1)
	v_lshlrev_b32_e32 v46, 16, v31
	v_sub_f32_e32 v31, v41, v48
	s_waitcnt lgkmcnt(0)
	v_lshlrev_b32_e32 v47, 16, v33
	v_mul_f32_e32 v31, 0x3fb8aa3b, v31
	v_pk_mul_f32 v[38:39], v[38:39], v[46:47]
	v_exp_f32_e32 v46, v31
	v_sub_f32_e32 v31, v41, v49
	v_mul_f32_e32 v31, 0x3fb8aa3b, v31
	v_exp_f32_e32 v47, v31
	ds_read_u16 v31, v32 offset:20128
	ds_read_u16 v33, v32 offset:20400
	v_mul_f32_e32 v27, 0x3fb8aa3b, v27
	v_exp_f32_e32 v26, v26
	v_exp_f32_e32 v27, v27
	s_waitcnt lgkmcnt(1)
	v_lshlrev_b32_e32 v48, 16, v31
	s_waitcnt lgkmcnt(0)
	v_lshlrev_b32_e32 v49, 16, v33
	ds_read_u16 v31, v32 offset:20672
	ds_read_u16 v33, v32 offset:20944
	v_pk_mul_f32 v[46:47], v[46:47], v[48:49]
	v_sub_f32_e32 v22, v41, v22
	v_sub_f32_e32 v23, v41, v23
	s_waitcnt lgkmcnt(1)
	v_lshlrev_b32_e32 v48, 16, v31
	s_waitcnt lgkmcnt(0)
	v_lshlrev_b32_e32 v49, 16, v33
	v_pk_mul_f32 v[48:49], v[26:27], v[48:49]
	v_sub_f32_e32 v26, v41, v28
	v_sub_f32_e32 v27, v41, v29
	ds_read_u16 v28, v32 offset:21216
	ds_read_u16 v29, v32 offset:21488
	v_mul_f32_e32 v26, 0x3fb8aa3b, v26
	v_mul_f32_e32 v27, 0x3fb8aa3b, v27
	v_exp_f32_e32 v26, v26
	v_exp_f32_e32 v27, v27
	s_waitcnt lgkmcnt(0)
	v_lshlrev_b32_e32 v29, 16, v29
	v_lshlrev_b32_e32 v28, 16, v28
	v_mul_f32_e32 v22, 0x3fb8aa3b, v22
	v_pk_mul_f32 v[50:51], v[26:27], v[28:29]
	v_cvt_pk_bf16_f32 v26, v38, v39
	v_cvt_pk_bf16_f32 v27, v46, v47
	v_cvt_pk_bf16_f32 v28, v48, v49
	v_cvt_pk_bf16_f32 v29, v50, v51
	global_store_dwordx4 v[36:37], v[26:29], off offset:16
	ds_read_u16 v26, v32 offset:21760
	ds_read_u16 v27, v32 offset:22032
	v_mul_f32_e32 v23, 0x3fb8aa3b, v23
	v_exp_f32_e32 v22, v22
	v_exp_f32_e32 v23, v23
	s_waitcnt lgkmcnt(1)
	v_lshlrev_b32_e32 v26, 16, v26
	s_waitcnt lgkmcnt(0)
	v_lshlrev_b32_e32 v27, 16, v27
	v_sub_f32_e32 v24, v41, v24
	v_pk_mul_f32 v[22:23], v[22:23], v[26:27]
	v_sub_f32_e32 v25, v41, v25
	ds_read_u16 v26, v32 offset:22304
	ds_read_u16 v27, v32 offset:22576
	v_mul_f32_e32 v24, 0x3fb8aa3b, v24
	v_mul_f32_e32 v25, 0x3fb8aa3b, v25
	v_exp_f32_e32 v24, v24
	v_exp_f32_e32 v25, v25
	s_waitcnt lgkmcnt(0)
	v_lshlrev_b32_e32 v27, 16, v27
	v_lshlrev_b32_e32 v26, 16, v26
	v_sub_f32_e32 v18, v41, v18
	v_pk_mul_f32 v[24:25], v[24:25], v[26:27]
	v_sub_f32_e32 v19, v41, v19
	ds_read_u16 v26, v32 offset:22848
	ds_read_u16 v27, v32 offset:23120
	v_mul_f32_e32 v18, 0x3fb8aa3b, v18
	v_mul_f32_e32 v19, 0x3fb8aa3b, v19
	v_exp_f32_e32 v18, v18
	v_exp_f32_e32 v19, v19
	s_waitcnt lgkmcnt(0)
	v_lshlrev_b32_e32 v27, 16, v27
	v_lshlrev_b32_e32 v26, 16, v26
	v_pk_mul_f32 v[26:27], v[18:19], v[26:27]
	v_sub_f32_e32 v18, v41, v20
	v_sub_f32_e32 v19, v41, v21
	ds_read_u16 v20, v32 offset:23392
	ds_read_u16 v21, v32 offset:23664
	v_mul_f32_e32 v18, 0x3fb8aa3b, v18
	v_mul_f32_e32 v19, 0x3fb8aa3b, v19
	v_exp_f32_e32 v18, v18
	v_exp_f32_e32 v19, v19
	s_waitcnt lgkmcnt(0)
	v_lshlrev_b32_e32 v21, 16, v21
	v_lshlrev_b32_e32 v20, 16, v20
	v_pk_mul_f32 v[28:29], v[18:19], v[20:21]
	v_cvt_pk_bf16_f32 v18, v22, v23
	v_cvt_pk_bf16_f32 v19, v24, v25
	v_cvt_pk_bf16_f32 v20, v26, v27
	v_cvt_pk_bf16_f32 v21, v28, v29
	global_store_dwordx4 v[36:37], v[18:21], off offset:32
	ds_read_b128 v[22:25], v0 offset:52320
	ds_read_b96 v[18:20], v0 offset:52336
	s_waitcnt lgkmcnt(1)
	v_sub_f32_e32 v0, v41, v22
	v_mul_f32_e32 v0, 0x3fb8aa3b, v0
	v_exp_f32_e32 v22, v0
	v_sub_f32_e32 v0, v41, v23
	v_mul_f32_e32 v0, 0x3fb8aa3b, v0
	v_exp_f32_e32 v23, v0
	ds_read_u16 v0, v32 offset:23936
	ds_read_u16 v21, v32 offset:24208
	s_waitcnt lgkmcnt(1)
	v_lshlrev_b32_e32 v26, 16, v0
	v_sub_f32_e32 v0, v41, v24
	v_mul_f32_e32 v0, 0x3fb8aa3b, v0
	v_exp_f32_e32 v24, v0
	v_sub_f32_e32 v0, v41, v25
	v_mul_f32_e32 v0, 0x3fb8aa3b, v0
	s_waitcnt lgkmcnt(0)
	v_lshlrev_b32_e32 v27, 16, v21
	v_exp_f32_e32 v25, v0
	ds_read_u16 v0, v32 offset:24480
	ds_read_u16 v21, v32 offset:24752
	v_pk_mul_f32 v[22:23], v[22:23], v[26:27]
	s_waitcnt lgkmcnt(1)
	v_lshlrev_b32_e32 v26, 16, v0
	v_sub_f32_e32 v0, v41, v18
	v_mul_f32_e32 v0, 0x3fb8aa3b, v0
	v_exp_f32_e32 v18, v0
	v_sub_f32_e32 v0, v41, v19
	v_mul_f32_e32 v0, 0x3fb8aa3b, v0
	s_waitcnt lgkmcnt(0)
	v_lshlrev_b32_e32 v27, 16, v21
	v_exp_f32_e32 v19, v0
	ds_read_u16 v0, v32 offset:25024
	ds_read_u16 v21, v32 offset:25296
	v_pk_mul_f32 v[24:25], v[24:25], v[26:27]
	s_waitcnt lgkmcnt(1)
	v_lshlrev_b32_e32 v26, 16, v0
	v_sub_f32_e32 v0, v41, v20
	s_waitcnt lgkmcnt(0)
	v_lshlrev_b32_e32 v27, 16, v21
	v_mul_f32_e32 v0, 0x3fb8aa3b, v0
	v_pk_mul_f32 v[26:27], v[18:19], v[26:27]
	v_exp_f32_e32 v18, v0
	v_or_b32_e32 v0, 31, v43
	v_mad_u64_u32 v[20:21], s[0:1], v0, s6, v[34:35]
	v_lshl_add_u32 v0, v0, 2, 0
	ds_read_b32 v0, v0 offset:52224
	s_movk_i32 s0, 0x80
	v_cmp_gt_i32_e32 vcc, s0, v40
	s_add_i32 s0, 0, 0x8800
	s_add_i32 s1, 0, 0x4400
	s_waitcnt lgkmcnt(0)
	v_sub_f32_e32 v0, v41, v0
	v_mul_f32_e32 v0, 0x3fb8aa3b, v0
	v_exp_f32_e32 v19, v0
	ds_read_u16 v0, v32 offset:25568
	ds_read_u16 v20, v20 offset:17408
	s_waitcnt lgkmcnt(0)
	v_lshlrev_b32_e32 v21, 16, v20
	v_lshlrev_b32_e32 v20, 16, v0
	v_pk_mul_f32 v[28:29], v[18:19], v[20:21]
	v_mul_lo_u32 v0, v44, s6
	v_cvt_pk_bf16_f32 v18, v22, v23
	v_cvt_pk_bf16_f32 v19, v24, v25
	v_cvt_pk_bf16_f32 v20, v26, v27
	v_cvt_pk_bf16_f32 v21, v28, v29
	v_add3_u32 v0, 0, v0, v42
	global_store_dwordx4 v[36:37], v[18:21], off offset:48
	s_barrier
	ds_write_b128 v0, v[14:17]
	ds_write_b128 v0, v[10:13] offset:64
	ds_write_b128 v0, v[6:9] offset:128
	ds_write_b128 v0, v[2:5] offset:192
	v_cndmask_b32_e64 v0, v157, 0, vcc
	v_add_u32_e32 v2, 0, v0
	v_mov_b32_e32 v0, s1
	v_mov_b32_e32 v3, s0
	v_cndmask_b32_e32 v0, v0, v3, vcc
	s_waitcnt lgkmcnt(0)
	s_barrier
	v_cmp_gt_u32_e32 vcc, 0x80, v144
	v_and_b32_e32 v72, 0x7f, v144
	v_lshlrev_b32_e32 v72, 1, v72
	v_mov_b32_e32 v73, 0x4400
	v_mov_b32_e32 v74, 0x8800
	s_nop 1
	v_cndmask_b32_e32 v76, v73, v74, vcc
	v_add_u32_e32 v76, v76, v72
	v_mov_b32_e32 v73, 0xd000
	v_mov_b32_e32 v74, 0xcf00
	v_cndmask_b32_e32 v77, v73, v74, vcc
	v_mov_b32_e32 v73, 0x400
	v_mov_b32_e32 v74, 0x800
	v_cndmask_b32_e32 v78, v73, v74, vcc
	v_add_u32_e32 v78, v78, v72
	v_mov_b32_e32 v73, 0xbf800000
	v_mov_b32_e32 v74, 0x3f800000
	v_cndmask_b32_e32 v79, v73, v74, vcc
	s_lshr_b32 s0, s40, 7
	s_lshl_b32 s0, s0, 11
	s_and_b32 s1, s40, 31
	s_lshl_b32 s1, s1, 6
	s_add_u32 s0, s0, s1
	s_mul_i32 s0, s0, 0xc00
	s_bfe_u32 s1, s40, 0x20005
	s_lshl_b32 s1, s1, 8
	s_add_u32 s0, s0, s1
	s_add_u32 s0, s0, 0xc440000
	s_add_u32 s38, s26, s0
	s_addc_u32 s39, s27, 0
	ds_read_b128 v[164:167], v77 offset:0
	ds_read_b128 v[168:171], v77 offset:16
	ds_read_b128 v[172:175], v77 offset:32
	ds_read_b128 v[176:179], v77 offset:48
	ds_read_b128 v[180:183], v77 offset:64
	ds_read_b128 v[184:187], v77 offset:80
	ds_read_b128 v[188:191], v77 offset:96
	ds_read_b128 v[192:195], v77 offset:112
	ds_read_b128 v[196:199], v77 offset:128
	ds_read_b128 v[200:203], v77 offset:144
	ds_read_b128 v[204:207], v77 offset:160
	ds_read_b128 v[208:211], v77 offset:176
	ds_read_b128 v[212:215], v77 offset:192
	ds_read_b128 v[216:219], v77 offset:208
	ds_read_b128 v[220:223], v77 offset:224
	ds_read_b128 v[224:227], v77 offset:240
	ds_read_u16 v4, v76 offset:0
	ds_read_u16 v5, v76 offset:272
	ds_read_u16 v6, v76 offset:544
	ds_read_u16 v7, v76 offset:816
	ds_read_u16 v8, v76 offset:1088
	ds_read_u16 v9, v76 offset:1360
	ds_read_u16 v10, v76 offset:1632
	ds_read_u16 v11, v76 offset:1904
	s_waitcnt lgkmcnt(0)
	v_lshlrev_b32_e32 v4, 16, v4
	v_lshlrev_b32_e32 v5, 16, v5
	v_lshlrev_b32_e32 v6, 16, v6
	v_lshlrev_b32_e32 v7, 16, v7
	v_lshlrev_b32_e32 v8, 16, v8
	v_lshlrev_b32_e32 v9, 16, v9
	v_lshlrev_b32_e32 v10, 16, v10
	v_lshlrev_b32_e32 v11, 16, v11
	v_mul_f32_e32 v4, v164, v4
	v_mul_f32_e32 v5, v165, v5
	v_mul_f32_e32 v6, v166, v6
	v_mul_f32_e32 v7, v167, v7
	v_mul_f32_e32 v8, v168, v8
	v_mul_f32_e32 v9, v169, v9
	v_mul_f32_e32 v10, v170, v10
	v_mul_f32_e32 v11, v171, v11
	ds_read_u16 v12, v76 offset:2176
	ds_read_u16 v13, v76 offset:2448
	ds_read_u16 v14, v76 offset:2720
	ds_read_u16 v15, v76 offset:2992
	ds_read_u16 v16, v76 offset:3264
	ds_read_u16 v17, v76 offset:3536
	ds_read_u16 v18, v76 offset:3808
	ds_read_u16 v19, v76 offset:4080
	s_waitcnt lgkmcnt(0)
	v_lshlrev_b32_e32 v12, 16, v12
	v_lshlrev_b32_e32 v13, 16, v13
	v_lshlrev_b32_e32 v14, 16, v14
	v_lshlrev_b32_e32 v15, 16, v15
	v_lshlrev_b32_e32 v16, 16, v16
	v_lshlrev_b32_e32 v17, 16, v17
	v_lshlrev_b32_e32 v18, 16, v18
	v_lshlrev_b32_e32 v19, 16, v19
	v_mul_f32_e32 v12, v172, v12
	v_mul_f32_e32 v13, v173, v13
	v_mul_f32_e32 v14, v174, v14
	v_mul_f32_e32 v15, v175, v15
	v_mul_f32_e32 v16, v176, v16
	v_mul_f32_e32 v17, v177, v17
	v_mul_f32_e32 v18, v178, v18
	v_mul_f32_e32 v19, v179, v19
	ds_read_u16 v20, v76 offset:4352
	ds_read_u16 v21, v76 offset:4624
	ds_read_u16 v22, v76 offset:4896
	ds_read_u16 v23, v76 offset:5168
	ds_read_u16 v24, v76 offset:5440
	ds_read_u16 v25, v76 offset:5712
	ds_read_u16 v26, v76 offset:5984
	ds_read_u16 v27, v76 offset:6256
	s_waitcnt lgkmcnt(0)
	v_lshlrev_b32_e32 v20, 16, v20
	v_lshlrev_b32_e32 v21, 16, v21
	v_lshlrev_b32_e32 v22, 16, v22
	v_lshlrev_b32_e32 v23, 16, v23
	v_lshlrev_b32_e32 v24, 16, v24
	v_lshlrev_b32_e32 v25, 16, v25
	v_lshlrev_b32_e32 v26, 16, v26
	v_lshlrev_b32_e32 v27, 16, v27
	v_mul_f32_e32 v20, v180, v20
	v_mul_f32_e32 v21, v181, v21
	v_mul_f32_e32 v22, v182, v22
	v_mul_f32_e32 v23, v183, v23
	v_mul_f32_e32 v24, v184, v24
	v_mul_f32_e32 v25, v185, v25
	v_mul_f32_e32 v26, v186, v26
	v_mul_f32_e32 v27, v187, v27
	ds_read_u16 v28, v76 offset:6528
	ds_read_u16 v29, v76 offset:6800
	ds_read_u16 v30, v76 offset:7072
	ds_read_u16 v31, v76 offset:7344
	ds_read_u16 v32, v76 offset:7616
	ds_read_u16 v33, v76 offset:7888
	ds_read_u16 v34, v76 offset:8160
	ds_read_u16 v35, v76 offset:8432
	s_waitcnt lgkmcnt(0)
	v_lshlrev_b32_e32 v28, 16, v28
	v_lshlrev_b32_e32 v29, 16, v29
	v_lshlrev_b32_e32 v30, 16, v30
	v_lshlrev_b32_e32 v31, 16, v31
	v_lshlrev_b32_e32 v32, 16, v32
	v_lshlrev_b32_e32 v33, 16, v33
	v_lshlrev_b32_e32 v34, 16, v34
	v_lshlrev_b32_e32 v35, 16, v35
	v_mul_f32_e32 v28, v188, v28
	v_mul_f32_e32 v29, v189, v29
	v_mul_f32_e32 v30, v190, v30
	v_mul_f32_e32 v31, v191, v31
	v_mul_f32_e32 v32, v192, v32
	v_mul_f32_e32 v33, v193, v33
	v_mul_f32_e32 v34, v194, v34
	v_mul_f32_e32 v35, v195, v35
	ds_read_u16 v36, v76 offset:8704
	ds_read_u16 v37, v76 offset:8976
	ds_read_u16 v38, v76 offset:9248
	ds_read_u16 v39, v76 offset:9520
	ds_read_u16 v40, v76 offset:9792
	ds_read_u16 v41, v76 offset:10064
	ds_read_u16 v42, v76 offset:10336
	ds_read_u16 v43, v76 offset:10608
	s_waitcnt lgkmcnt(0)
	v_lshlrev_b32_e32 v36, 16, v36
	v_lshlrev_b32_e32 v37, 16, v37
	v_lshlrev_b32_e32 v38, 16, v38
	v_lshlrev_b32_e32 v39, 16, v39
	v_lshlrev_b32_e32 v40, 16, v40
	v_lshlrev_b32_e32 v41, 16, v41
	v_lshlrev_b32_e32 v42, 16, v42
	v_lshlrev_b32_e32 v43, 16, v43
	v_mul_f32_e32 v36, v196, v36
	v_mul_f32_e32 v37, v197, v37
	v_mul_f32_e32 v38, v198, v38
	v_mul_f32_e32 v39, v199, v39
	v_mul_f32_e32 v40, v200, v40
	v_mul_f32_e32 v41, v201, v41
	v_mul_f32_e32 v42, v202, v42
	v_mul_f32_e32 v43, v203, v43
	ds_read_u16 v44, v76 offset:10880
	ds_read_u16 v45, v76 offset:11152
	ds_read_u16 v46, v76 offset:11424
	ds_read_u16 v47, v76 offset:11696
	ds_read_u16 v48, v76 offset:11968
	ds_read_u16 v49, v76 offset:12240
	ds_read_u16 v50, v76 offset:12512
	ds_read_u16 v51, v76 offset:12784
	s_waitcnt lgkmcnt(0)
	v_lshlrev_b32_e32 v44, 16, v44
	v_lshlrev_b32_e32 v45, 16, v45
	v_lshlrev_b32_e32 v46, 16, v46
	v_lshlrev_b32_e32 v47, 16, v47
	v_lshlrev_b32_e32 v48, 16, v48
	v_lshlrev_b32_e32 v49, 16, v49
	v_lshlrev_b32_e32 v50, 16, v50
	v_lshlrev_b32_e32 v51, 16, v51
	v_mul_f32_e32 v44, v204, v44
	v_mul_f32_e32 v45, v205, v45
	v_mul_f32_e32 v46, v206, v46
	v_mul_f32_e32 v47, v207, v47
	v_mul_f32_e32 v48, v208, v48
	v_mul_f32_e32 v49, v209, v49
	v_mul_f32_e32 v50, v210, v50
	v_mul_f32_e32 v51, v211, v51
	ds_read_u16 v52, v76 offset:13056
	ds_read_u16 v53, v76 offset:13328
	ds_read_u16 v54, v76 offset:13600
	ds_read_u16 v55, v76 offset:13872
	ds_read_u16 v56, v76 offset:14144
	ds_read_u16 v57, v76 offset:14416
	ds_read_u16 v58, v76 offset:14688
	ds_read_u16 v59, v76 offset:14960
	s_waitcnt lgkmcnt(0)
	v_lshlrev_b32_e32 v52, 16, v52
	v_lshlrev_b32_e32 v53, 16, v53
	v_lshlrev_b32_e32 v54, 16, v54
	v_lshlrev_b32_e32 v55, 16, v55
	v_lshlrev_b32_e32 v56, 16, v56
	v_lshlrev_b32_e32 v57, 16, v57
	v_lshlrev_b32_e32 v58, 16, v58
	v_lshlrev_b32_e32 v59, 16, v59
	v_mul_f32_e32 v52, v212, v52
	v_mul_f32_e32 v53, v213, v53
	v_mul_f32_e32 v54, v214, v54
	v_mul_f32_e32 v55, v215, v55
	v_mul_f32_e32 v56, v216, v56
	v_mul_f32_e32 v57, v217, v57
	v_mul_f32_e32 v58, v218, v58
	v_mul_f32_e32 v59, v219, v59
	ds_read_u16 v60, v76 offset:15232
	ds_read_u16 v61, v76 offset:15504
	ds_read_u16 v62, v76 offset:15776
	ds_read_u16 v63, v76 offset:16048
	ds_read_u16 v64, v76 offset:16320
	ds_read_u16 v65, v76 offset:16592
	ds_read_u16 v66, v76 offset:16864
	ds_read_u16 v67, v76 offset:17136
	s_waitcnt lgkmcnt(0)
	v_lshlrev_b32_e32 v60, 16, v60
	v_lshlrev_b32_e32 v61, 16, v61
	v_lshlrev_b32_e32 v62, 16, v62
	v_lshlrev_b32_e32 v63, 16, v63
	v_lshlrev_b32_e32 v64, 16, v64
	v_lshlrev_b32_e32 v65, 16, v65
	v_lshlrev_b32_e32 v66, 16, v66
	v_lshlrev_b32_e32 v67, 16, v67
	v_mul_f32_e32 v60, v220, v60
	v_mul_f32_e32 v61, v221, v61
	v_mul_f32_e32 v62, v222, v62
	v_mul_f32_e32 v63, v223, v63
	v_mul_f32_e32 v64, v224, v64
	v_mul_f32_e32 v65, v225, v65
	v_mul_f32_e32 v66, v226, v66
	v_mul_f32_e32 v67, v227, v67
	v_mul_f32_e32 v72, v79, v4
	v_cvt_pk_bf16_f32 v72, v72, v72
	global_store_short v78, v72, s[38:39]
	v_add_u32_e32 v78, 0xc00, v78
	ds_read_b128 v[164:167], v1 offset:272
	v_mov_b32_e32 v68, v5
	v_mov_b32_e32 v69, 0
	v_mov_b32_e32 v70, 0
	v_mov_b32_e32 v71, 0
	s_waitcnt lgkmcnt(0)
	v_fma_f32 v68, -v164, v4, v68
	ds_read_b128 v[164:167], v1 offset:544
	v_add_f32_e32 v68, v68, v69
	v_add_f32_e32 v70, v70, v71
	v_add_f32_e32 v5, v68, v70
	v_mul_f32_e32 v72, v79, v5
	v_cvt_pk_bf16_f32 v72, v72, v72
	global_store_short v78, v72, s[38:39]
	v_add_u32_e32 v78, 0xc00, v78
	v_mov_b32_e32 v68, v6
	v_mov_b32_e32 v69, 0
	v_mov_b32_e32 v70, 0
	v_mov_b32_e32 v71, 0
	s_waitcnt lgkmcnt(0)
	v_pk_fma_f32 v[68:69], v[164:165], v[4:5], v[68:69] neg_lo:[1,0,0] neg_hi:[1,0,0]
	ds_read_b128 v[164:167], v1 offset:816
	v_add_f32_e32 v68, v68, v69
	v_add_f32_e32 v70, v70, v71
	v_add_f32_e32 v6, v68, v70
	v_mul_f32_e32 v72, v79, v6
	v_cvt_pk_bf16_f32 v72, v72, v72
	global_store_short v78, v72, s[38:39]
	v_add_u32_e32 v78, 0xc00, v78
	v_mov_b32_e32 v68, v7
	v_mov_b32_e32 v69, 0
	v_mov_b32_e32 v70, 0
	v_mov_b32_e32 v71, 0
	s_waitcnt lgkmcnt(0)
	v_pk_fma_f32 v[68:69], v[164:165], v[4:5], v[68:69] neg_lo:[1,0,0] neg_hi:[1,0,0]
	v_fma_f32 v70, -v166, v6, v70
	ds_read_b128 v[164:167], v1 offset:1088
	v_add_f32_e32 v68, v68, v69
	v_add_f32_e32 v70, v70, v71
	v_add_f32_e32 v7, v68, v70
	v_mul_f32_e32 v72, v79, v7
	v_cvt_pk_bf16_f32 v72, v72, v72
	global_store_short v78, v72, s[38:39]
	v_add_u32_e32 v78, 0xc00, v78
	v_mov_b32_e32 v68, v8
	v_mov_b32_e32 v69, 0
	v_mov_b32_e32 v70, 0
	v_mov_b32_e32 v71, 0
	s_waitcnt lgkmcnt(0)
	v_pk_fma_f32 v[68:69], v[164:165], v[4:5], v[68:69] neg_lo:[1,0,0] neg_hi:[1,0,0]
	v_pk_fma_f32 v[70:71], v[166:167], v[6:7], v[70:71] neg_lo:[1,0,0] neg_hi:[1,0,0]
	ds_read_b128 v[164:167], v1 offset:1360
	ds_read_b128 v[168:171], v1 offset:1376
	v_add_f32_e32 v68, v68, v69
	v_add_f32_e32 v70, v70, v71
	v_add_f32_e32 v8, v68, v70
	v_mul_f32_e32 v72, v79, v8
	v_cvt_pk_bf16_f32 v72, v72, v72
	global_store_short v78, v72, s[38:39]
	v_add_u32_e32 v78, 0xc00, v78
	v_mov_b32_e32 v68, v9
	v_mov_b32_e32 v69, 0
	v_mov_b32_e32 v70, 0
	v_mov_b32_e32 v71, 0
	s_waitcnt lgkmcnt(1)
	v_pk_fma_f32 v[68:69], v[164:165], v[4:5], v[68:69] neg_lo:[1,0,0] neg_hi:[1,0,0]
	v_pk_fma_f32 v[70:71], v[166:167], v[6:7], v[70:71] neg_lo:[1,0,0] neg_hi:[1,0,0]
	s_waitcnt lgkmcnt(0)
	v_fma_f32 v68, -v168, v8, v68
	ds_read_b128 v[164:167], v1 offset:1632
	ds_read_b128 v[168:171], v1 offset:1648
	v_add_f32_e32 v68, v68, v69
	v_add_f32_e32 v70, v70, v71
	v_add_f32_e32 v9, v68, v70
	v_mul_f32_e32 v72, v79, v9
	v_cvt_pk_bf16_f32 v72, v72, v72
	global_store_short v78, v72, s[38:39]
	v_add_u32_e32 v78, 0xc00, v78
	v_mov_b32_e32 v68, v10
	v_mov_b32_e32 v69, 0
	v_mov_b32_e32 v70, 0
	v_mov_b32_e32 v71, 0
	s_waitcnt lgkmcnt(1)
	v_pk_fma_f32 v[68:69], v[164:165], v[4:5], v[68:69] neg_lo:[1,0,0] neg_hi:[1,0,0]
	v_pk_fma_f32 v[70:71], v[166:167], v[6:7], v[70:71] neg_lo:[1,0,0] neg_hi:[1,0,0]
	s_waitcnt lgkmcnt(0)
	v_pk_fma_f32 v[68:69], v[168:169], v[8:9], v[68:69] neg_lo:[1,0,0] neg_hi:[1,0,0]
	ds_read_b128 v[164:167], v1 offset:1904
	ds_read_b128 v[168:171], v1 offset:1920
	v_add_f32_e32 v68, v68, v69
	v_add_f32_e32 v70, v70, v71
	v_add_f32_e32 v10, v68, v70
	v_mul_f32_e32 v72, v79, v10
	v_cvt_pk_bf16_f32 v72, v72, v72
	global_store_short v78, v72, s[38:39]
	v_add_u32_e32 v78, 0xc00, v78
	v_mov_b32_e32 v68, v11
	v_mov_b32_e32 v69, 0
	v_mov_b32_e32 v70, 0
	v_mov_b32_e32 v71, 0
	s_waitcnt lgkmcnt(1)
	v_pk_fma_f32 v[68:69], v[164:165], v[4:5], v[68:69] neg_lo:[1,0,0] neg_hi:[1,0,0]
	v_pk_fma_f32 v[70:71], v[166:167], v[6:7], v[70:71] neg_lo:[1,0,0] neg_hi:[1,0,0]
	s_waitcnt lgkmcnt(0)
	v_pk_fma_f32 v[68:69], v[168:169], v[8:9], v[68:69] neg_lo:[1,0,0] neg_hi:[1,0,0]
	v_fma_f32 v70, -v170, v10, v70
	ds_read_b128 v[164:167], v1 offset:2176
	ds_read_b128 v[168:171], v1 offset:2192
	v_add_f32_e32 v68, v68, v69
	v_add_f32_e32 v70, v70, v71
	v_add_f32_e32 v11, v68, v70
	v_mul_f32_e32 v72, v79, v11
	v_cvt_pk_bf16_f32 v72, v72, v72
	global_store_short v78, v72, s[38:39]
	v_add_u32_e32 v78, 0xc00, v78
	v_mov_b32_e32 v68, v12
	v_mov_b32_e32 v69, 0
	v_mov_b32_e32 v70, 0
	v_mov_b32_e32 v71, 0
	s_waitcnt lgkmcnt(1)
	v_pk_fma_f32 v[68:69], v[164:165], v[4:5], v[68:69] neg_lo:[1,0,0] neg_hi:[1,0,0]
	v_pk_fma_f32 v[70:71], v[166:167], v[6:7], v[70:71] neg_lo:[1,0,0] neg_hi:[1,0,0]
	s_waitcnt lgkmcnt(0)
	v_pk_fma_f32 v[68:69], v[168:169], v[8:9], v[68:69] neg_lo:[1,0,0] neg_hi:[1,0,0]
	v_pk_fma_f32 v[70:71], v[170:171], v[10:11], v[70:71] neg_lo:[1,0,0] neg_hi:[1,0,0]
	ds_read_b128 v[164:167], v1 offset:2448
	ds_read_b128 v[168:171], v1 offset:2464
	ds_read_b128 v[172:175], v1 offset:2480
	v_add_f32_e32 v68, v68, v69
	v_add_f32_e32 v70, v70, v71
	v_add_f32_e32 v12, v68, v70
	v_mul_f32_e32 v72, v79, v12
	v_cvt_pk_bf16_f32 v72, v72, v72
	global_store_short v78, v72, s[38:39]
	v_add_u32_e32 v78, 0xc00, v78
	v_mov_b32_e32 v68, v13
	v_mov_b32_e32 v69, 0
	v_mov_b32_e32 v70, 0
	v_mov_b32_e32 v71, 0
	s_waitcnt lgkmcnt(2)
	v_pk_fma_f32 v[68:69], v[164:165], v[4:5], v[68:69] neg_lo:[1,0,0] neg_hi:[1,0,0]
	v_pk_fma_f32 v[70:71], v[166:167], v[6:7], v[70:71] neg_lo:[1,0,0] neg_hi:[1,0,0]
	s_waitcnt lgkmcnt(1)
	v_pk_fma_f32 v[68:69], v[168:169], v[8:9], v[68:69] neg_lo:[1,0,0] neg_hi:[1,0,0]
	v_pk_fma_f32 v[70:71], v[170:171], v[10:11], v[70:71] neg_lo:[1,0,0] neg_hi:[1,0,0]
	ds_read_b128 v[164:167], v1 offset:2720
	s_waitcnt lgkmcnt(1)
	v_fma_f32 v68, -v172, v12, v68
	ds_read_b128 v[168:171], v1 offset:2736
	ds_read_b128 v[172:175], v1 offset:2752
	v_add_f32_e32 v68, v68, v69
	v_add_f32_e32 v70, v70, v71
	v_add_f32_e32 v13, v68, v70
	v_mul_f32_e32 v72, v79, v13
	v_cvt_pk_bf16_f32 v72, v72, v72
	global_store_short v78, v72, s[38:39]
	v_add_u32_e32 v78, 0xc00, v78
	v_mov_b32_e32 v68, v14
	v_mov_b32_e32 v69, 0
	v_mov_b32_e32 v70, 0
	v_mov_b32_e32 v71, 0
	s_waitcnt lgkmcnt(2)
	v_pk_fma_f32 v[68:69], v[164:165], v[4:5], v[68:69] neg_lo:[1,0,0] neg_hi:[1,0,0]
	v_pk_fma_f32 v[70:71], v[166:167], v[6:7], v[70:71] neg_lo:[1,0,0] neg_hi:[1,0,0]
	s_waitcnt lgkmcnt(1)
	v_pk_fma_f32 v[68:69], v[168:169], v[8:9], v[68:69] neg_lo:[1,0,0] neg_hi:[1,0,0]
	v_pk_fma_f32 v[70:71], v[170:171], v[10:11], v[70:71] neg_lo:[1,0,0] neg_hi:[1,0,0]
	ds_read_b128 v[164:167], v1 offset:2992
	s_waitcnt lgkmcnt(1)
	v_pk_fma_f32 v[68:69], v[172:173], v[12:13], v[68:69] neg_lo:[1,0,0] neg_hi:[1,0,0]
	ds_read_b128 v[168:171], v1 offset:3008
	ds_read_b128 v[172:175], v1 offset:3024
	v_add_f32_e32 v68, v68, v69
	v_add_f32_e32 v70, v70, v71
	v_add_f32_e32 v14, v68, v70
	v_mul_f32_e32 v72, v79, v14
	v_cvt_pk_bf16_f32 v72, v72, v72
	global_store_short v78, v72, s[38:39]
	v_add_u32_e32 v78, 0xc00, v78
	v_mov_b32_e32 v68, v15
	v_mov_b32_e32 v69, 0
	v_mov_b32_e32 v70, 0
	v_mov_b32_e32 v71, 0
	s_waitcnt lgkmcnt(2)
	v_pk_fma_f32 v[68:69], v[164:165], v[4:5], v[68:69] neg_lo:[1,0,0] neg_hi:[1,0,0]
	v_pk_fma_f32 v[70:71], v[166:167], v[6:7], v[70:71] neg_lo:[1,0,0] neg_hi:[1,0,0]
	s_waitcnt lgkmcnt(1)
	v_pk_fma_f32 v[68:69], v[168:169], v[8:9], v[68:69] neg_lo:[1,0,0] neg_hi:[1,0,0]
	v_pk_fma_f32 v[70:71], v[170:171], v[10:11], v[70:71] neg_lo:[1,0,0] neg_hi:[1,0,0]
	ds_read_b128 v[164:167], v1 offset:3264
	s_waitcnt lgkmcnt(1)
	v_pk_fma_f32 v[68:69], v[172:173], v[12:13], v[68:69] neg_lo:[1,0,0] neg_hi:[1,0,0]
	v_fma_f32 v70, -v174, v14, v70
	ds_read_b128 v[168:171], v1 offset:3280
	ds_read_b128 v[172:175], v1 offset:3296
	v_add_f32_e32 v68, v68, v69
	v_add_f32_e32 v70, v70, v71
	v_add_f32_e32 v15, v68, v70
	v_mul_f32_e32 v72, v79, v15
	v_cvt_pk_bf16_f32 v72, v72, v72
	global_store_short v78, v72, s[38:39]
	v_add_u32_e32 v78, 0xc00, v78
	v_mov_b32_e32 v68, v16
	v_mov_b32_e32 v69, 0
	v_mov_b32_e32 v70, 0
	v_mov_b32_e32 v71, 0
	s_waitcnt lgkmcnt(2)
	v_pk_fma_f32 v[68:69], v[164:165], v[4:5], v[68:69] neg_lo:[1,0,0] neg_hi:[1,0,0]
	v_pk_fma_f32 v[70:71], v[166:167], v[6:7], v[70:71] neg_lo:[1,0,0] neg_hi:[1,0,0]
	s_waitcnt lgkmcnt(1)
	v_pk_fma_f32 v[68:69], v[168:169], v[8:9], v[68:69] neg_lo:[1,0,0] neg_hi:[1,0,0]
	v_pk_fma_f32 v[70:71], v[170:171], v[10:11], v[70:71] neg_lo:[1,0,0] neg_hi:[1,0,0]
	ds_read_b128 v[164:167], v1 offset:3536
	s_waitcnt lgkmcnt(1)
	v_pk_fma_f32 v[68:69], v[172:173], v[12:13], v[68:69] neg_lo:[1,0,0] neg_hi:[1,0,0]
	v_pk_fma_f32 v[70:71], v[174:175], v[14:15], v[70:71] neg_lo:[1,0,0] neg_hi:[1,0,0]
	ds_read_b128 v[168:171], v1 offset:3552
	ds_read_b128 v[172:175], v1 offset:3568
	ds_read_b128 v[176:179], v1 offset:3584
	v_add_f32_e32 v68, v68, v69
	v_add_f32_e32 v70, v70, v71
	v_add_f32_e32 v16, v68, v70
	v_mul_f32_e32 v72, v79, v16
	v_cvt_pk_bf16_f32 v72, v72, v72
	global_store_short v78, v72, s[38:39]
	v_add_u32_e32 v78, 0xc00, v78
	v_mov_b32_e32 v68, v17
	v_mov_b32_e32 v69, 0
	v_mov_b32_e32 v70, 0
	v_mov_b32_e32 v71, 0
	s_waitcnt lgkmcnt(3)
	v_pk_fma_f32 v[68:69], v[164:165], v[4:5], v[68:69] neg_lo:[1,0,0] neg_hi:[1,0,0]
	v_pk_fma_f32 v[70:71], v[166:167], v[6:7], v[70:71] neg_lo:[1,0,0] neg_hi:[1,0,0]
	s_waitcnt lgkmcnt(2)
	v_pk_fma_f32 v[68:69], v[168:169], v[8:9], v[68:69] neg_lo:[1,0,0] neg_hi:[1,0,0]
	v_pk_fma_f32 v[70:71], v[170:171], v[10:11], v[70:71] neg_lo:[1,0,0] neg_hi:[1,0,0]
	ds_read_b128 v[164:167], v1 offset:3808
	s_waitcnt lgkmcnt(2)
	v_pk_fma_f32 v[68:69], v[172:173], v[12:13], v[68:69] neg_lo:[1,0,0] neg_hi:[1,0,0]
	v_pk_fma_f32 v[70:71], v[174:175], v[14:15], v[70:71] neg_lo:[1,0,0] neg_hi:[1,0,0]
	ds_read_b128 v[168:171], v1 offset:3824
	s_waitcnt lgkmcnt(2)
	v_fma_f32 v68, -v176, v16, v68
	ds_read_b128 v[172:175], v1 offset:3840
	ds_read_b128 v[176:179], v1 offset:3856
	v_add_f32_e32 v68, v68, v69
	v_add_f32_e32 v70, v70, v71
	v_add_f32_e32 v17, v68, v70
	v_mul_f32_e32 v72, v79, v17
	v_cvt_pk_bf16_f32 v72, v72, v72
	global_store_short v78, v72, s[38:39]
	v_add_u32_e32 v78, 0xc00, v78
	v_mov_b32_e32 v68, v18
	v_mov_b32_e32 v69, 0
	v_mov_b32_e32 v70, 0
	v_mov_b32_e32 v71, 0
	s_waitcnt lgkmcnt(3)
	v_pk_fma_f32 v[68:69], v[164:165], v[4:5], v[68:69] neg_lo:[1,0,0] neg_hi:[1,0,0]
	v_pk_fma_f32 v[70:71], v[166:167], v[6:7], v[70:71] neg_lo:[1,0,0] neg_hi:[1,0,0]
	s_waitcnt lgkmcnt(2)
	v_pk_fma_f32 v[68:69], v[168:169], v[8:9], v[68:69] neg_lo:[1,0,0] neg_hi:[1,0,0]
	v_pk_fma_f32 v[70:71], v[170:171], v[10:11], v[70:71] neg_lo:[1,0,0] neg_hi:[1,0,0]
	ds_read_b128 v[164:167], v1 offset:4080
	s_waitcnt lgkmcnt(2)
	v_pk_fma_f32 v[68:69], v[172:173], v[12:13], v[68:69] neg_lo:[1,0,0] neg_hi:[1,0,0]
	v_pk_fma_f32 v[70:71], v[174:175], v[14:15], v[70:71] neg_lo:[1,0,0] neg_hi:[1,0,0]
	ds_read_b128 v[168:171], v1 offset:4096
	s_waitcnt lgkmcnt(2)
	v_pk_fma_f32 v[68:69], v[176:177], v[16:17], v[68:69] neg_lo:[1,0,0] neg_hi:[1,0,0]
	ds_read_b128 v[172:175], v1 offset:4112
	ds_read_b128 v[176:179], v1 offset:4128
	v_add_f32_e32 v68, v68, v69
	v_add_f32_e32 v70, v70, v71
	v_add_f32_e32 v18, v68, v70
	v_mul_f32_e32 v72, v79, v18
	v_cvt_pk_bf16_f32 v72, v72, v72
	global_store_short v78, v72, s[38:39]
	v_add_u32_e32 v78, 0xc00, v78
	v_mov_b32_e32 v68, v19
	v_mov_b32_e32 v69, 0
	v_mov_b32_e32 v70, 0
	v_mov_b32_e32 v71, 0
	s_waitcnt lgkmcnt(3)
	v_pk_fma_f32 v[68:69], v[164:165], v[4:5], v[68:69] neg_lo:[1,0,0] neg_hi:[1,0,0]
	v_pk_fma_f32 v[70:71], v[166:167], v[6:7], v[70:71] neg_lo:[1,0,0] neg_hi:[1,0,0]
	s_waitcnt lgkmcnt(2)
	v_pk_fma_f32 v[68:69], v[168:169], v[8:9], v[68:69] neg_lo:[1,0,0] neg_hi:[1,0,0]
	v_pk_fma_f32 v[70:71], v[170:171], v[10:11], v[70:71] neg_lo:[1,0,0] neg_hi:[1,0,0]
	ds_read_b128 v[164:167], v1 offset:4352
	s_waitcnt lgkmcnt(2)
	v_pk_fma_f32 v[68:69], v[172:173], v[12:13], v[68:69] neg_lo:[1,0,0] neg_hi:[1,0,0]
	v_pk_fma_f32 v[70:71], v[174:175], v[14:15], v[70:71] neg_lo:[1,0,0] neg_hi:[1,0,0]
	ds_read_b128 v[168:171], v1 offset:4368
	s_waitcnt lgkmcnt(2)
	v_pk_fma_f32 v[68:69], v[176:177], v[16:17], v[68:69] neg_lo:[1,0,0] neg_hi:[1,0,0]
	v_fma_f32 v70, -v178, v18, v70
	ds_read_b128 v[172:175], v1 offset:4384
	ds_read_b128 v[176:179], v1 offset:4400
	v_add_f32_e32 v68, v68, v69
	v_add_f32_e32 v70, v70, v71
	v_add_f32_e32 v19, v68, v70
	v_mul_f32_e32 v72, v79, v19
	v_cvt_pk_bf16_f32 v72, v72, v72
	global_store_short v78, v72, s[38:39]
	v_add_u32_e32 v78, 0xc00, v78
	v_mov_b32_e32 v68, v20
	v_mov_b32_e32 v69, 0
	v_mov_b32_e32 v70, 0
	v_mov_b32_e32 v71, 0
	s_waitcnt lgkmcnt(3)
	v_pk_fma_f32 v[68:69], v[164:165], v[4:5], v[68:69] neg_lo:[1,0,0] neg_hi:[1,0,0]
	v_pk_fma_f32 v[70:71], v[166:167], v[6:7], v[70:71] neg_lo:[1,0,0] neg_hi:[1,0,0]
	s_waitcnt lgkmcnt(2)
	v_pk_fma_f32 v[68:69], v[168:169], v[8:9], v[68:69] neg_lo:[1,0,0] neg_hi:[1,0,0]
	v_pk_fma_f32 v[70:71], v[170:171], v[10:11], v[70:71] neg_lo:[1,0,0] neg_hi:[1,0,0]
	ds_read_b128 v[164:167], v1 offset:4624
	s_waitcnt lgkmcnt(2)
	v_pk_fma_f32 v[68:69], v[172:173], v[12:13], v[68:69] neg_lo:[1,0,0] neg_hi:[1,0,0]
	v_pk_fma_f32 v[70:71], v[174:175], v[14:15], v[70:71] neg_lo:[1,0,0] neg_hi:[1,0,0]
	ds_read_b128 v[168:171], v1 offset:4640
	s_waitcnt lgkmcnt(2)
	v_pk_fma_f32 v[68:69], v[176:177], v[16:17], v[68:69] neg_lo:[1,0,0] neg_hi:[1,0,0]
	v_pk_fma_f32 v[70:71], v[178:179], v[18:19], v[70:71] neg_lo:[1,0,0] neg_hi:[1,0,0]
	ds_read_b128 v[172:175], v1 offset:4656
	ds_read_b128 v[176:179], v1 offset:4672
	ds_read_b128 v[180:183], v1 offset:4688
	v_add_f32_e32 v68, v68, v69
	v_add_f32_e32 v70, v70, v71
	v_add_f32_e32 v20, v68, v70
	v_mul_f32_e32 v72, v79, v20
	v_cvt_pk_bf16_f32 v72, v72, v72
	global_store_short v78, v72, s[38:39]
	v_add_u32_e32 v78, 0xc00, v78
	v_mov_b32_e32 v68, v21
	v_mov_b32_e32 v69, 0
	v_mov_b32_e32 v70, 0
	v_mov_b32_e32 v71, 0
	s_waitcnt lgkmcnt(4)
	v_pk_fma_f32 v[68:69], v[164:165], v[4:5], v[68:69] neg_lo:[1,0,0] neg_hi:[1,0,0]
	v_pk_fma_f32 v[70:71], v[166:167], v[6:7], v[70:71] neg_lo:[1,0,0] neg_hi:[1,0,0]
	s_waitcnt lgkmcnt(3)
	v_pk_fma_f32 v[68:69], v[168:169], v[8:9], v[68:69] neg_lo:[1,0,0] neg_hi:[1,0,0]
	v_pk_fma_f32 v[70:71], v[170:171], v[10:11], v[70:71] neg_lo:[1,0,0] neg_hi:[1,0,0]
	ds_read_b128 v[164:167], v1 offset:4896
	s_waitcnt lgkmcnt(3)
	v_pk_fma_f32 v[68:69], v[172:173], v[12:13], v[68:69] neg_lo:[1,0,0] neg_hi:[1,0,0]
	v_pk_fma_f32 v[70:71], v[174:175], v[14:15], v[70:71] neg_lo:[1,0,0] neg_hi:[1,0,0]
	ds_read_b128 v[168:171], v1 offset:4912
	s_waitcnt lgkmcnt(3)
	v_pk_fma_f32 v[68:69], v[176:177], v[16:17], v[68:69] neg_lo:[1,0,0] neg_hi:[1,0,0]
	v_pk_fma_f32 v[70:71], v[178:179], v[18:19], v[70:71] neg_lo:[1,0,0] neg_hi:[1,0,0]
	ds_read_b128 v[172:175], v1 offset:4928
	s_waitcnt lgkmcnt(3)
	v_fma_f32 v68, -v180, v20, v68
	ds_read_b128 v[176:179], v1 offset:4944
	ds_read_b128 v[180:183], v1 offset:4960
	v_add_f32_e32 v68, v68, v69
	v_add_f32_e32 v70, v70, v71
	v_add_f32_e32 v21, v68, v70
	v_mul_f32_e32 v72, v79, v21
	v_cvt_pk_bf16_f32 v72, v72, v72
	global_store_short v78, v72, s[38:39]
	v_add_u32_e32 v78, 0xc00, v78
	v_mov_b32_e32 v68, v22
	v_mov_b32_e32 v69, 0
	v_mov_b32_e32 v70, 0
	v_mov_b32_e32 v71, 0
	s_waitcnt lgkmcnt(4)
	v_pk_fma_f32 v[68:69], v[164:165], v[4:5], v[68:69] neg_lo:[1,0,0] neg_hi:[1,0,0]
	v_pk_fma_f32 v[70:71], v[166:167], v[6:7], v[70:71] neg_lo:[1,0,0] neg_hi:[1,0,0]
	s_waitcnt lgkmcnt(3)
	v_pk_fma_f32 v[68:69], v[168:169], v[8:9], v[68:69] neg_lo:[1,0,0] neg_hi:[1,0,0]
	v_pk_fma_f32 v[70:71], v[170:171], v[10:11], v[70:71] neg_lo:[1,0,0] neg_hi:[1,0,0]
	ds_read_b128 v[164:167], v1 offset:5168
	s_waitcnt lgkmcnt(3)
	v_pk_fma_f32 v[68:69], v[172:173], v[12:13], v[68:69] neg_lo:[1,0,0] neg_hi:[1,0,0]
	v_pk_fma_f32 v[70:71], v[174:175], v[14:15], v[70:71] neg_lo:[1,0,0] neg_hi:[1,0,0]
	ds_read_b128 v[168:171], v1 offset:5184
	s_waitcnt lgkmcnt(3)
	v_pk_fma_f32 v[68:69], v[176:177], v[16:17], v[68:69] neg_lo:[1,0,0] neg_hi:[1,0,0]
	v_pk_fma_f32 v[70:71], v[178:179], v[18:19], v[70:71] neg_lo:[1,0,0] neg_hi:[1,0,0]
	ds_read_b128 v[172:175], v1 offset:5200
	s_waitcnt lgkmcnt(3)
	v_pk_fma_f32 v[68:69], v[180:181], v[20:21], v[68:69] neg_lo:[1,0,0] neg_hi:[1,0,0]
	ds_read_b128 v[176:179], v1 offset:5216
	ds_read_b128 v[180:183], v1 offset:5232
	v_add_f32_e32 v68, v68, v69
	v_add_f32_e32 v70, v70, v71
	v_add_f32_e32 v22, v68, v70
	v_mul_f32_e32 v72, v79, v22
	v_cvt_pk_bf16_f32 v72, v72, v72
	global_store_short v78, v72, s[38:39]
	v_add_u32_e32 v78, 0xc00, v78
	v_mov_b32_e32 v68, v23
	v_mov_b32_e32 v69, 0
	v_mov_b32_e32 v70, 0
	v_mov_b32_e32 v71, 0
	s_waitcnt lgkmcnt(4)
	v_pk_fma_f32 v[68:69], v[164:165], v[4:5], v[68:69] neg_lo:[1,0,0] neg_hi:[1,0,0]
	v_pk_fma_f32 v[70:71], v[166:167], v[6:7], v[70:71] neg_lo:[1,0,0] neg_hi:[1,0,0]
	s_waitcnt lgkmcnt(3)
	v_pk_fma_f32 v[68:69], v[168:169], v[8:9], v[68:69] neg_lo:[1,0,0] neg_hi:[1,0,0]
	v_pk_fma_f32 v[70:71], v[170:171], v[10:11], v[70:71] neg_lo:[1,0,0] neg_hi:[1,0,0]
	ds_read_b128 v[164:167], v1 offset:5440
	s_waitcnt lgkmcnt(3)
	v_pk_fma_f32 v[68:69], v[172:173], v[12:13], v[68:69] neg_lo:[1,0,0] neg_hi:[1,0,0]
	v_pk_fma_f32 v[70:71], v[174:175], v[14:15], v[70:71] neg_lo:[1,0,0] neg_hi:[1,0,0]
	ds_read_b128 v[168:171], v1 offset:5456
	s_waitcnt lgkmcnt(3)
	v_pk_fma_f32 v[68:69], v[176:177], v[16:17], v[68:69] neg_lo:[1,0,0] neg_hi:[1,0,0]
	v_pk_fma_f32 v[70:71], v[178:179], v[18:19], v[70:71] neg_lo:[1,0,0] neg_hi:[1,0,0]
	ds_read_b128 v[172:175], v1 offset:5472
	s_waitcnt lgkmcnt(3)
	v_pk_fma_f32 v[68:69], v[180:181], v[20:21], v[68:69] neg_lo:[1,0,0] neg_hi:[1,0,0]
	v_fma_f32 v70, -v182, v22, v70
	ds_read_b128 v[176:179], v1 offset:5488
	ds_read_b128 v[180:183], v1 offset:5504
	v_add_f32_e32 v68, v68, v69
	v_add_f32_e32 v70, v70, v71
	v_add_f32_e32 v23, v68, v70
	v_mul_f32_e32 v72, v79, v23
	v_cvt_pk_bf16_f32 v72, v72, v72
	global_store_short v78, v72, s[38:39]
	v_add_u32_e32 v78, 0xc00, v78
	v_mov_b32_e32 v68, v24
	v_mov_b32_e32 v69, 0
	v_mov_b32_e32 v70, 0
	v_mov_b32_e32 v71, 0
	s_waitcnt lgkmcnt(4)
	v_pk_fma_f32 v[68:69], v[164:165], v[4:5], v[68:69] neg_lo:[1,0,0] neg_hi:[1,0,0]
	v_pk_fma_f32 v[70:71], v[166:167], v[6:7], v[70:71] neg_lo:[1,0,0] neg_hi:[1,0,0]
	s_waitcnt lgkmcnt(3)
	v_pk_fma_f32 v[68:69], v[168:169], v[8:9], v[68:69] neg_lo:[1,0,0] neg_hi:[1,0,0]
	v_pk_fma_f32 v[70:71], v[170:171], v[10:11], v[70:71] neg_lo:[1,0,0] neg_hi:[1,0,0]
	ds_read_b128 v[164:167], v1 offset:5712
	s_waitcnt lgkmcnt(3)
	v_pk_fma_f32 v[68:69], v[172:173], v[12:13], v[68:69] neg_lo:[1,0,0] neg_hi:[1,0,0]
	v_pk_fma_f32 v[70:71], v[174:175], v[14:15], v[70:71] neg_lo:[1,0,0] neg_hi:[1,0,0]
	ds_read_b128 v[168:171], v1 offset:5728
	s_waitcnt lgkmcnt(3)
	v_pk_fma_f32 v[68:69], v[176:177], v[16:17], v[68:69] neg_lo:[1,0,0] neg_hi:[1,0,0]
	v_pk_fma_f32 v[70:71], v[178:179], v[18:19], v[70:71] neg_lo:[1,0,0] neg_hi:[1,0,0]
	ds_read_b128 v[172:175], v1 offset:5744
	s_waitcnt lgkmcnt(3)
	v_pk_fma_f32 v[68:69], v[180:181], v[20:21], v[68:69] neg_lo:[1,0,0] neg_hi:[1,0,0]
	v_pk_fma_f32 v[70:71], v[182:183], v[22:23], v[70:71] neg_lo:[1,0,0] neg_hi:[1,0,0]
	ds_read_b128 v[176:179], v1 offset:5760
	ds_read_b128 v[180:183], v1 offset:5776
	ds_read_b128 v[184:187], v1 offset:5792
	v_add_f32_e32 v68, v68, v69
	v_add_f32_e32 v70, v70, v71
	v_add_f32_e32 v24, v68, v70
	v_mul_f32_e32 v72, v79, v24
	v_cvt_pk_bf16_f32 v72, v72, v72
	global_store_short v78, v72, s[38:39]
	v_add_u32_e32 v78, 0xc00, v78
	v_mov_b32_e32 v68, v25
	v_mov_b32_e32 v69, 0
	v_mov_b32_e32 v70, 0
	v_mov_b32_e32 v71, 0
	s_waitcnt lgkmcnt(5)
	v_pk_fma_f32 v[68:69], v[164:165], v[4:5], v[68:69] neg_lo:[1,0,0] neg_hi:[1,0,0]
	v_pk_fma_f32 v[70:71], v[166:167], v[6:7], v[70:71] neg_lo:[1,0,0] neg_hi:[1,0,0]
	s_waitcnt lgkmcnt(4)
	v_pk_fma_f32 v[68:69], v[168:169], v[8:9], v[68:69] neg_lo:[1,0,0] neg_hi:[1,0,0]
	v_pk_fma_f32 v[70:71], v[170:171], v[10:11], v[70:71] neg_lo:[1,0,0] neg_hi:[1,0,0]
	ds_read_b128 v[164:167], v1 offset:5984
	s_waitcnt lgkmcnt(4)
	v_pk_fma_f32 v[68:69], v[172:173], v[12:13], v[68:69] neg_lo:[1,0,0] neg_hi:[1,0,0]
	v_pk_fma_f32 v[70:71], v[174:175], v[14:15], v[70:71] neg_lo:[1,0,0] neg_hi:[1,0,0]
	ds_read_b128 v[168:171], v1 offset:6000
	s_waitcnt lgkmcnt(4)
	v_pk_fma_f32 v[68:69], v[176:177], v[16:17], v[68:69] neg_lo:[1,0,0] neg_hi:[1,0,0]
	v_pk_fma_f32 v[70:71], v[178:179], v[18:19], v[70:71] neg_lo:[1,0,0] neg_hi:[1,0,0]
	ds_read_b128 v[172:175], v1 offset:6016
	s_waitcnt lgkmcnt(4)
	v_pk_fma_f32 v[68:69], v[180:181], v[20:21], v[68:69] neg_lo:[1,0,0] neg_hi:[1,0,0]
	v_pk_fma_f32 v[70:71], v[182:183], v[22:23], v[70:71] neg_lo:[1,0,0] neg_hi:[1,0,0]
	ds_read_b128 v[176:179], v1 offset:6032
	s_waitcnt lgkmcnt(4)
	v_fma_f32 v68, -v184, v24, v68
	ds_read_b128 v[180:183], v1 offset:6048
	ds_read_b128 v[184:187], v1 offset:6064
	v_add_f32_e32 v68, v68, v69
	v_add_f32_e32 v70, v70, v71
	v_add_f32_e32 v25, v68, v70
	v_mul_f32_e32 v72, v79, v25
	v_cvt_pk_bf16_f32 v72, v72, v72
	global_store_short v78, v72, s[38:39]
	v_add_u32_e32 v78, 0xc00, v78
	v_mov_b32_e32 v68, v26
	v_mov_b32_e32 v69, 0
	v_mov_b32_e32 v70, 0
	v_mov_b32_e32 v71, 0
	s_waitcnt lgkmcnt(5)
	v_pk_fma_f32 v[68:69], v[164:165], v[4:5], v[68:69] neg_lo:[1,0,0] neg_hi:[1,0,0]
	v_pk_fma_f32 v[70:71], v[166:167], v[6:7], v[70:71] neg_lo:[1,0,0] neg_hi:[1,0,0]
	s_waitcnt lgkmcnt(4)
	v_pk_fma_f32 v[68:69], v[168:169], v[8:9], v[68:69] neg_lo:[1,0,0] neg_hi:[1,0,0]
	v_pk_fma_f32 v[70:71], v[170:171], v[10:11], v[70:71] neg_lo:[1,0,0] neg_hi:[1,0,0]
	ds_read_b128 v[164:167], v1 offset:6256
	s_waitcnt lgkmcnt(4)
	v_pk_fma_f32 v[68:69], v[172:173], v[12:13], v[68:69] neg_lo:[1,0,0] neg_hi:[1,0,0]
	v_pk_fma_f32 v[70:71], v[174:175], v[14:15], v[70:71] neg_lo:[1,0,0] neg_hi:[1,0,0]
	ds_read_b128 v[168:171], v1 offset:6272
	s_waitcnt lgkmcnt(4)
	v_pk_fma_f32 v[68:69], v[176:177], v[16:17], v[68:69] neg_lo:[1,0,0] neg_hi:[1,0,0]
	v_pk_fma_f32 v[70:71], v[178:179], v[18:19], v[70:71] neg_lo:[1,0,0] neg_hi:[1,0,0]
	ds_read_b128 v[172:175], v1 offset:6288
	s_waitcnt lgkmcnt(4)
	v_pk_fma_f32 v[68:69], v[180:181], v[20:21], v[68:69] neg_lo:[1,0,0] neg_hi:[1,0,0]
	v_pk_fma_f32 v[70:71], v[182:183], v[22:23], v[70:71] neg_lo:[1,0,0] neg_hi:[1,0,0]
	ds_read_b128 v[176:179], v1 offset:6304
	s_waitcnt lgkmcnt(4)
	v_pk_fma_f32 v[68:69], v[184:185], v[24:25], v[68:69] neg_lo:[1,0,0] neg_hi:[1,0,0]
	ds_read_b128 v[180:183], v1 offset:6320
	ds_read_b128 v[184:187], v1 offset:6336
	v_add_f32_e32 v68, v68, v69
	v_add_f32_e32 v70, v70, v71
	v_add_f32_e32 v26, v68, v70
	v_mul_f32_e32 v72, v79, v26
	v_cvt_pk_bf16_f32 v72, v72, v72
	global_store_short v78, v72, s[38:39]
	v_add_u32_e32 v78, 0xc00, v78
	v_mov_b32_e32 v68, v27
	v_mov_b32_e32 v69, 0
	v_mov_b32_e32 v70, 0
	v_mov_b32_e32 v71, 0
	s_waitcnt lgkmcnt(5)
	v_pk_fma_f32 v[68:69], v[164:165], v[4:5], v[68:69] neg_lo:[1,0,0] neg_hi:[1,0,0]
	v_pk_fma_f32 v[70:71], v[166:167], v[6:7], v[70:71] neg_lo:[1,0,0] neg_hi:[1,0,0]
	s_waitcnt lgkmcnt(4)
	v_pk_fma_f32 v[68:69], v[168:169], v[8:9], v[68:69] neg_lo:[1,0,0] neg_hi:[1,0,0]
	v_pk_fma_f32 v[70:71], v[170:171], v[10:11], v[70:71] neg_lo:[1,0,0] neg_hi:[1,0,0]
	ds_read_b128 v[164:167], v1 offset:6528
	s_waitcnt lgkmcnt(4)
	v_pk_fma_f32 v[68:69], v[172:173], v[12:13], v[68:69] neg_lo:[1,0,0] neg_hi:[1,0,0]
	v_pk_fma_f32 v[70:71], v[174:175], v[14:15], v[70:71] neg_lo:[1,0,0] neg_hi:[1,0,0]
	ds_read_b128 v[168:171], v1 offset:6544
	s_waitcnt lgkmcnt(4)
	v_pk_fma_f32 v[68:69], v[176:177], v[16:17], v[68:69] neg_lo:[1,0,0] neg_hi:[1,0,0]
	v_pk_fma_f32 v[70:71], v[178:179], v[18:19], v[70:71] neg_lo:[1,0,0] neg_hi:[1,0,0]
	ds_read_b128 v[172:175], v1 offset:6560
	s_waitcnt lgkmcnt(4)
	v_pk_fma_f32 v[68:69], v[180:181], v[20:21], v[68:69] neg_lo:[1,0,0] neg_hi:[1,0,0]
	v_pk_fma_f32 v[70:71], v[182:183], v[22:23], v[70:71] neg_lo:[1,0,0] neg_hi:[1,0,0]
	ds_read_b128 v[176:179], v1 offset:6576
	s_waitcnt lgkmcnt(4)
	v_pk_fma_f32 v[68:69], v[184:185], v[24:25], v[68:69] neg_lo:[1,0,0] neg_hi:[1,0,0]
	v_fma_f32 v70, -v186, v26, v70
	ds_read_b128 v[180:183], v1 offset:6592
	ds_read_b128 v[184:187], v1 offset:6608
	v_add_f32_e32 v68, v68, v69
	v_add_f32_e32 v70, v70, v71
	v_add_f32_e32 v27, v68, v70
	v_mul_f32_e32 v72, v79, v27
	v_cvt_pk_bf16_f32 v72, v72, v72
	global_store_short v78, v72, s[38:39]
	v_add_u32_e32 v78, 0xc00, v78
	v_mov_b32_e32 v68, v28
	v_mov_b32_e32 v69, 0
	v_mov_b32_e32 v70, 0
	v_mov_b32_e32 v71, 0
	s_waitcnt lgkmcnt(5)
	v_pk_fma_f32 v[68:69], v[164:165], v[4:5], v[68:69] neg_lo:[1,0,0] neg_hi:[1,0,0]
	v_pk_fma_f32 v[70:71], v[166:167], v[6:7], v[70:71] neg_lo:[1,0,0] neg_hi:[1,0,0]
	s_waitcnt lgkmcnt(4)
	v_pk_fma_f32 v[68:69], v[168:169], v[8:9], v[68:69] neg_lo:[1,0,0] neg_hi:[1,0,0]
	v_pk_fma_f32 v[70:71], v[170:171], v[10:11], v[70:71] neg_lo:[1,0,0] neg_hi:[1,0,0]
	ds_read_b128 v[164:167], v1 offset:6800
	s_waitcnt lgkmcnt(4)
	v_pk_fma_f32 v[68:69], v[172:173], v[12:13], v[68:69] neg_lo:[1,0,0] neg_hi:[1,0,0]
	v_pk_fma_f32 v[70:71], v[174:175], v[14:15], v[70:71] neg_lo:[1,0,0] neg_hi:[1,0,0]
	ds_read_b128 v[168:171], v1 offset:6816
	s_waitcnt lgkmcnt(4)
	v_pk_fma_f32 v[68:69], v[176:177], v[16:17], v[68:69] neg_lo:[1,0,0] neg_hi:[1,0,0]
	v_pk_fma_f32 v[70:71], v[178:179], v[18:19], v[70:71] neg_lo:[1,0,0] neg_hi:[1,0,0]
	ds_read_b128 v[172:175], v1 offset:6832
	s_waitcnt lgkmcnt(4)
	v_pk_fma_f32 v[68:69], v[180:181], v[20:21], v[68:69] neg_lo:[1,0,0] neg_hi:[1,0,0]
	v_pk_fma_f32 v[70:71], v[182:183], v[22:23], v[70:71] neg_lo:[1,0,0] neg_hi:[1,0,0]
	ds_read_b128 v[176:179], v1 offset:6848
	s_waitcnt lgkmcnt(4)
	v_pk_fma_f32 v[68:69], v[184:185], v[24:25], v[68:69] neg_lo:[1,0,0] neg_hi:[1,0,0]
	v_pk_fma_f32 v[70:71], v[186:187], v[26:27], v[70:71] neg_lo:[1,0,0] neg_hi:[1,0,0]
	ds_read_b128 v[180:183], v1 offset:6864
	ds_read_b128 v[184:187], v1 offset:6880
	ds_read_b128 v[188:191], v1 offset:6896
	v_add_f32_e32 v68, v68, v69
	v_add_f32_e32 v70, v70, v71
	v_add_f32_e32 v28, v68, v70
	v_mul_f32_e32 v72, v79, v28
	v_cvt_pk_bf16_f32 v72, v72, v72
	global_store_short v78, v72, s[38:39]
	v_add_u32_e32 v78, 0xc00, v78
	v_mov_b32_e32 v68, v29
	v_mov_b32_e32 v69, 0
	v_mov_b32_e32 v70, 0
	v_mov_b32_e32 v71, 0
	s_waitcnt lgkmcnt(6)
	v_pk_fma_f32 v[68:69], v[164:165], v[4:5], v[68:69] neg_lo:[1,0,0] neg_hi:[1,0,0]
	v_pk_fma_f32 v[70:71], v[166:167], v[6:7], v[70:71] neg_lo:[1,0,0] neg_hi:[1,0,0]
	s_waitcnt lgkmcnt(5)
	v_pk_fma_f32 v[68:69], v[168:169], v[8:9], v[68:69] neg_lo:[1,0,0] neg_hi:[1,0,0]
	v_pk_fma_f32 v[70:71], v[170:171], v[10:11], v[70:71] neg_lo:[1,0,0] neg_hi:[1,0,0]
	ds_read_b128 v[164:167], v1 offset:7072
	s_waitcnt lgkmcnt(5)
	v_pk_fma_f32 v[68:69], v[172:173], v[12:13], v[68:69] neg_lo:[1,0,0] neg_hi:[1,0,0]
	v_pk_fma_f32 v[70:71], v[174:175], v[14:15], v[70:71] neg_lo:[1,0,0] neg_hi:[1,0,0]
	ds_read_b128 v[168:171], v1 offset:7088
	s_waitcnt lgkmcnt(5)
	v_pk_fma_f32 v[68:69], v[176:177], v[16:17], v[68:69] neg_lo:[1,0,0] neg_hi:[1,0,0]
	v_pk_fma_f32 v[70:71], v[178:179], v[18:19], v[70:71] neg_lo:[1,0,0] neg_hi:[1,0,0]
	ds_read_b128 v[172:175], v1 offset:7104
	s_waitcnt lgkmcnt(5)
	v_pk_fma_f32 v[68:69], v[180:181], v[20:21], v[68:69] neg_lo:[1,0,0] neg_hi:[1,0,0]
	v_pk_fma_f32 v[70:71], v[182:183], v[22:23], v[70:71] neg_lo:[1,0,0] neg_hi:[1,0,0]
	ds_read_b128 v[176:179], v1 offset:7120
	s_waitcnt lgkmcnt(5)
	v_pk_fma_f32 v[68:69], v[184:185], v[24:25], v[68:69] neg_lo:[1,0,0] neg_hi:[1,0,0]
	v_pk_fma_f32 v[70:71], v[186:187], v[26:27], v[70:71] neg_lo:[1,0,0] neg_hi:[1,0,0]
	ds_read_b128 v[180:183], v1 offset:7136
	s_waitcnt lgkmcnt(5)
	v_fma_f32 v68, -v188, v28, v68
	ds_read_b128 v[184:187], v1 offset:7152
	ds_read_b128 v[188:191], v1 offset:7168
	v_add_f32_e32 v68, v68, v69
	v_add_f32_e32 v70, v70, v71
	v_add_f32_e32 v29, v68, v70
	v_mul_f32_e32 v72, v79, v29
	v_cvt_pk_bf16_f32 v72, v72, v72
	global_store_short v78, v72, s[38:39]
	v_add_u32_e32 v78, 0xc00, v78
	v_mov_b32_e32 v68, v30
	v_mov_b32_e32 v69, 0
	v_mov_b32_e32 v70, 0
	v_mov_b32_e32 v71, 0
	s_waitcnt lgkmcnt(6)
	v_pk_fma_f32 v[68:69], v[164:165], v[4:5], v[68:69] neg_lo:[1,0,0] neg_hi:[1,0,0]
	v_pk_fma_f32 v[70:71], v[166:167], v[6:7], v[70:71] neg_lo:[1,0,0] neg_hi:[1,0,0]
	s_waitcnt lgkmcnt(5)
	v_pk_fma_f32 v[68:69], v[168:169], v[8:9], v[68:69] neg_lo:[1,0,0] neg_hi:[1,0,0]
	v_pk_fma_f32 v[70:71], v[170:171], v[10:11], v[70:71] neg_lo:[1,0,0] neg_hi:[1,0,0]
	ds_read_b128 v[164:167], v1 offset:7344
	s_waitcnt lgkmcnt(5)
	v_pk_fma_f32 v[68:69], v[172:173], v[12:13], v[68:69] neg_lo:[1,0,0] neg_hi:[1,0,0]
	v_pk_fma_f32 v[70:71], v[174:175], v[14:15], v[70:71] neg_lo:[1,0,0] neg_hi:[1,0,0]
	ds_read_b128 v[168:171], v1 offset:7360
	s_waitcnt lgkmcnt(5)
	v_pk_fma_f32 v[68:69], v[176:177], v[16:17], v[68:69] neg_lo:[1,0,0] neg_hi:[1,0,0]
	v_pk_fma_f32 v[70:71], v[178:179], v[18:19], v[70:71] neg_lo:[1,0,0] neg_hi:[1,0,0]
	ds_read_b128 v[172:175], v1 offset:7376
	s_waitcnt lgkmcnt(5)
	v_pk_fma_f32 v[68:69], v[180:181], v[20:21], v[68:69] neg_lo:[1,0,0] neg_hi:[1,0,0]
	v_pk_fma_f32 v[70:71], v[182:183], v[22:23], v[70:71] neg_lo:[1,0,0] neg_hi:[1,0,0]
	ds_read_b128 v[176:179], v1 offset:7392
	s_waitcnt lgkmcnt(5)
	v_pk_fma_f32 v[68:69], v[184:185], v[24:25], v[68:69] neg_lo:[1,0,0] neg_hi:[1,0,0]
	v_pk_fma_f32 v[70:71], v[186:187], v[26:27], v[70:71] neg_lo:[1,0,0] neg_hi:[1,0,0]
	ds_read_b128 v[180:183], v1 offset:7408
	s_waitcnt lgkmcnt(5)
	v_pk_fma_f32 v[68:69], v[188:189], v[28:29], v[68:69] neg_lo:[1,0,0] neg_hi:[1,0,0]
	ds_read_b128 v[184:187], v1 offset:7424
	ds_read_b128 v[188:191], v1 offset:7440
	v_add_f32_e32 v68, v68, v69
	v_add_f32_e32 v70, v70, v71
	v_add_f32_e32 v30, v68, v70
	v_mul_f32_e32 v72, v79, v30
	v_cvt_pk_bf16_f32 v72, v72, v72
	global_store_short v78, v72, s[38:39]
	v_add_u32_e32 v78, 0xc00, v78
	v_mov_b32_e32 v68, v31
	v_mov_b32_e32 v69, 0
	v_mov_b32_e32 v70, 0
	v_mov_b32_e32 v71, 0
	s_waitcnt lgkmcnt(6)
	v_pk_fma_f32 v[68:69], v[164:165], v[4:5], v[68:69] neg_lo:[1,0,0] neg_hi:[1,0,0]
	v_pk_fma_f32 v[70:71], v[166:167], v[6:7], v[70:71] neg_lo:[1,0,0] neg_hi:[1,0,0]
	s_waitcnt lgkmcnt(5)
	v_pk_fma_f32 v[68:69], v[168:169], v[8:9], v[68:69] neg_lo:[1,0,0] neg_hi:[1,0,0]
	v_pk_fma_f32 v[70:71], v[170:171], v[10:11], v[70:71] neg_lo:[1,0,0] neg_hi:[1,0,0]
	ds_read_b128 v[164:167], v1 offset:7616
	s_waitcnt lgkmcnt(5)
	v_pk_fma_f32 v[68:69], v[172:173], v[12:13], v[68:69] neg_lo:[1,0,0] neg_hi:[1,0,0]
	v_pk_fma_f32 v[70:71], v[174:175], v[14:15], v[70:71] neg_lo:[1,0,0] neg_hi:[1,0,0]
	ds_read_b128 v[168:171], v1 offset:7632
	s_waitcnt lgkmcnt(5)
	v_pk_fma_f32 v[68:69], v[176:177], v[16:17], v[68:69] neg_lo:[1,0,0] neg_hi:[1,0,0]
	v_pk_fma_f32 v[70:71], v[178:179], v[18:19], v[70:71] neg_lo:[1,0,0] neg_hi:[1,0,0]
	ds_read_b128 v[172:175], v1 offset:7648
	s_waitcnt lgkmcnt(5)
	v_pk_fma_f32 v[68:69], v[180:181], v[20:21], v[68:69] neg_lo:[1,0,0] neg_hi:[1,0,0]
	v_pk_fma_f32 v[70:71], v[182:183], v[22:23], v[70:71] neg_lo:[1,0,0] neg_hi:[1,0,0]
	ds_read_b128 v[176:179], v1 offset:7664
	s_waitcnt lgkmcnt(5)
	v_pk_fma_f32 v[68:69], v[184:185], v[24:25], v[68:69] neg_lo:[1,0,0] neg_hi:[1,0,0]
	v_pk_fma_f32 v[70:71], v[186:187], v[26:27], v[70:71] neg_lo:[1,0,0] neg_hi:[1,0,0]
	ds_read_b128 v[180:183], v1 offset:7680
	s_waitcnt lgkmcnt(5)
	v_pk_fma_f32 v[68:69], v[188:189], v[28:29], v[68:69] neg_lo:[1,0,0] neg_hi:[1,0,0]
	v_fma_f32 v70, -v190, v30, v70
	ds_read_b128 v[184:187], v1 offset:7696
	ds_read_b128 v[188:191], v1 offset:7712
	v_add_f32_e32 v68, v68, v69
	v_add_f32_e32 v70, v70, v71
	v_add_f32_e32 v31, v68, v70
	v_mul_f32_e32 v72, v79, v31
	v_cvt_pk_bf16_f32 v72, v72, v72
	global_store_short v78, v72, s[38:39]
	v_add_u32_e32 v78, 0xc00, v78
	v_mov_b32_e32 v68, v32
	v_mov_b32_e32 v69, 0
	v_mov_b32_e32 v70, 0
	v_mov_b32_e32 v71, 0
	s_waitcnt lgkmcnt(6)
	v_pk_fma_f32 v[68:69], v[164:165], v[4:5], v[68:69] neg_lo:[1,0,0] neg_hi:[1,0,0]
	v_pk_fma_f32 v[70:71], v[166:167], v[6:7], v[70:71] neg_lo:[1,0,0] neg_hi:[1,0,0]
	s_waitcnt lgkmcnt(5)
	v_pk_fma_f32 v[68:69], v[168:169], v[8:9], v[68:69] neg_lo:[1,0,0] neg_hi:[1,0,0]
	v_pk_fma_f32 v[70:71], v[170:171], v[10:11], v[70:71] neg_lo:[1,0,0] neg_hi:[1,0,0]
	ds_read_b128 v[164:167], v1 offset:7888
	s_waitcnt lgkmcnt(5)
	v_pk_fma_f32 v[68:69], v[172:173], v[12:13], v[68:69] neg_lo:[1,0,0] neg_hi:[1,0,0]
	v_pk_fma_f32 v[70:71], v[174:175], v[14:15], v[70:71] neg_lo:[1,0,0] neg_hi:[1,0,0]
	ds_read_b128 v[168:171], v1 offset:7904
	s_waitcnt lgkmcnt(5)
	v_pk_fma_f32 v[68:69], v[176:177], v[16:17], v[68:69] neg_lo:[1,0,0] neg_hi:[1,0,0]
	v_pk_fma_f32 v[70:71], v[178:179], v[18:19], v[70:71] neg_lo:[1,0,0] neg_hi:[1,0,0]
	ds_read_b128 v[172:175], v1 offset:7920
	s_waitcnt lgkmcnt(5)
	v_pk_fma_f32 v[68:69], v[180:181], v[20:21], v[68:69] neg_lo:[1,0,0] neg_hi:[1,0,0]
	v_pk_fma_f32 v[70:71], v[182:183], v[22:23], v[70:71] neg_lo:[1,0,0] neg_hi:[1,0,0]
	ds_read_b128 v[176:179], v1 offset:7936
	s_waitcnt lgkmcnt(5)
	v_pk_fma_f32 v[68:69], v[184:185], v[24:25], v[68:69] neg_lo:[1,0,0] neg_hi:[1,0,0]
	v_pk_fma_f32 v[70:71], v[186:187], v[26:27], v[70:71] neg_lo:[1,0,0] neg_hi:[1,0,0]
	ds_read_b128 v[180:183], v1 offset:7952
	s_waitcnt lgkmcnt(5)
	v_pk_fma_f32 v[68:69], v[188:189], v[28:29], v[68:69] neg_lo:[1,0,0] neg_hi:[1,0,0]
	v_pk_fma_f32 v[70:71], v[190:191], v[30:31], v[70:71] neg_lo:[1,0,0] neg_hi:[1,0,0]
	ds_read_b128 v[184:187], v1 offset:7968
	ds_read_b128 v[188:191], v1 offset:7984
	ds_read_b128 v[192:195], v1 offset:8000
	v_add_f32_e32 v68, v68, v69
	v_add_f32_e32 v70, v70, v71
	v_add_f32_e32 v32, v68, v70
	v_mul_f32_e32 v72, v79, v32
	v_cvt_pk_bf16_f32 v72, v72, v72
	global_store_short v78, v72, s[38:39]
	v_add_u32_e32 v78, 0xc00, v78
	v_mov_b32_e32 v68, v33
	v_mov_b32_e32 v69, 0
	v_mov_b32_e32 v70, 0
	v_mov_b32_e32 v71, 0
	s_waitcnt lgkmcnt(7)
	v_pk_fma_f32 v[68:69], v[164:165], v[4:5], v[68:69] neg_lo:[1,0,0] neg_hi:[1,0,0]
	v_pk_fma_f32 v[70:71], v[166:167], v[6:7], v[70:71] neg_lo:[1,0,0] neg_hi:[1,0,0]
	s_waitcnt lgkmcnt(6)
	v_pk_fma_f32 v[68:69], v[168:169], v[8:9], v[68:69] neg_lo:[1,0,0] neg_hi:[1,0,0]
	v_pk_fma_f32 v[70:71], v[170:171], v[10:11], v[70:71] neg_lo:[1,0,0] neg_hi:[1,0,0]
	ds_read_b128 v[164:167], v1 offset:8160
	s_waitcnt lgkmcnt(6)
	v_pk_fma_f32 v[68:69], v[172:173], v[12:13], v[68:69] neg_lo:[1,0,0] neg_hi:[1,0,0]
	v_pk_fma_f32 v[70:71], v[174:175], v[14:15], v[70:71] neg_lo:[1,0,0] neg_hi:[1,0,0]
	ds_read_b128 v[168:171], v1 offset:8176
	s_waitcnt lgkmcnt(6)
	v_pk_fma_f32 v[68:69], v[176:177], v[16:17], v[68:69] neg_lo:[1,0,0] neg_hi:[1,0,0]
	v_pk_fma_f32 v[70:71], v[178:179], v[18:19], v[70:71] neg_lo:[1,0,0] neg_hi:[1,0,0]
	ds_read_b128 v[172:175], v1 offset:8192
	s_waitcnt lgkmcnt(6)
	v_pk_fma_f32 v[68:69], v[180:181], v[20:21], v[68:69] neg_lo:[1,0,0] neg_hi:[1,0,0]
	v_pk_fma_f32 v[70:71], v[182:183], v[22:23], v[70:71] neg_lo:[1,0,0] neg_hi:[1,0,0]
	ds_read_b128 v[176:179], v1 offset:8208
	s_waitcnt lgkmcnt(6)
	v_pk_fma_f32 v[68:69], v[184:185], v[24:25], v[68:69] neg_lo:[1,0,0] neg_hi:[1,0,0]
	v_pk_fma_f32 v[70:71], v[186:187], v[26:27], v[70:71] neg_lo:[1,0,0] neg_hi:[1,0,0]
	ds_read_b128 v[180:183], v1 offset:8224
	s_waitcnt lgkmcnt(6)
	v_pk_fma_f32 v[68:69], v[188:189], v[28:29], v[68:69] neg_lo:[1,0,0] neg_hi:[1,0,0]
	v_pk_fma_f32 v[70:71], v[190:191], v[30:31], v[70:71] neg_lo:[1,0,0] neg_hi:[1,0,0]
	ds_read_b128 v[184:187], v1 offset:8240
	s_waitcnt lgkmcnt(6)
	v_fma_f32 v68, -v192, v32, v68
	ds_read_b128 v[188:191], v1 offset:8256
	ds_read_b128 v[192:195], v1 offset:8272
	v_add_f32_e32 v68, v68, v69
	v_add_f32_e32 v70, v70, v71
	v_add_f32_e32 v33, v68, v70
	v_mul_f32_e32 v72, v79, v33
	v_cvt_pk_bf16_f32 v72, v72, v72
	global_store_short v78, v72, s[38:39]
	v_add_u32_e32 v78, 0xc00, v78
	v_mov_b32_e32 v68, v34
	v_mov_b32_e32 v69, 0
	v_mov_b32_e32 v70, 0
	v_mov_b32_e32 v71, 0
	s_waitcnt lgkmcnt(7)
	v_pk_fma_f32 v[68:69], v[164:165], v[4:5], v[68:69] neg_lo:[1,0,0] neg_hi:[1,0,0]
	v_pk_fma_f32 v[70:71], v[166:167], v[6:7], v[70:71] neg_lo:[1,0,0] neg_hi:[1,0,0]
	s_waitcnt lgkmcnt(6)
	v_pk_fma_f32 v[68:69], v[168:169], v[8:9], v[68:69] neg_lo:[1,0,0] neg_hi:[1,0,0]
	v_pk_fma_f32 v[70:71], v[170:171], v[10:11], v[70:71] neg_lo:[1,0,0] neg_hi:[1,0,0]
	ds_read_b128 v[164:167], v1 offset:8432
	s_waitcnt lgkmcnt(6)
	v_pk_fma_f32 v[68:69], v[172:173], v[12:13], v[68:69] neg_lo:[1,0,0] neg_hi:[1,0,0]
	v_pk_fma_f32 v[70:71], v[174:175], v[14:15], v[70:71] neg_lo:[1,0,0] neg_hi:[1,0,0]
	ds_read_b128 v[168:171], v1 offset:8448
	s_waitcnt lgkmcnt(6)
	v_pk_fma_f32 v[68:69], v[176:177], v[16:17], v[68:69] neg_lo:[1,0,0] neg_hi:[1,0,0]
	v_pk_fma_f32 v[70:71], v[178:179], v[18:19], v[70:71] neg_lo:[1,0,0] neg_hi:[1,0,0]
	ds_read_b128 v[172:175], v1 offset:8464
	s_waitcnt lgkmcnt(6)
	v_pk_fma_f32 v[68:69], v[180:181], v[20:21], v[68:69] neg_lo:[1,0,0] neg_hi:[1,0,0]
	v_pk_fma_f32 v[70:71], v[182:183], v[22:23], v[70:71] neg_lo:[1,0,0] neg_hi:[1,0,0]
	ds_read_b128 v[176:179], v1 offset:8480
	s_waitcnt lgkmcnt(6)
	v_pk_fma_f32 v[68:69], v[184:185], v[24:25], v[68:69] neg_lo:[1,0,0] neg_hi:[1,0,0]
	v_pk_fma_f32 v[70:71], v[186:187], v[26:27], v[70:71] neg_lo:[1,0,0] neg_hi:[1,0,0]
	ds_read_b128 v[180:183], v1 offset:8496
	s_waitcnt lgkmcnt(6)
	v_pk_fma_f32 v[68:69], v[188:189], v[28:29], v[68:69] neg_lo:[1,0,0] neg_hi:[1,0,0]
	v_pk_fma_f32 v[70:71], v[190:191], v[30:31], v[70:71] neg_lo:[1,0,0] neg_hi:[1,0,0]
	ds_read_b128 v[184:187], v1 offset:8512
	s_waitcnt lgkmcnt(6)
	v_pk_fma_f32 v[68:69], v[192:193], v[32:33], v[68:69] neg_lo:[1,0,0] neg_hi:[1,0,0]
	ds_read_b128 v[188:191], v1 offset:8528
	ds_read_b128 v[192:195], v1 offset:8544
	v_add_f32_e32 v68, v68, v69
	v_add_f32_e32 v70, v70, v71
	v_add_f32_e32 v34, v68, v70
	v_mul_f32_e32 v72, v79, v34
	v_cvt_pk_bf16_f32 v72, v72, v72
	global_store_short v78, v72, s[38:39]
	v_add_u32_e32 v78, 0xc00, v78
	v_mov_b32_e32 v68, v35
	v_mov_b32_e32 v69, 0
	v_mov_b32_e32 v70, 0
	v_mov_b32_e32 v71, 0
	s_waitcnt lgkmcnt(7)
	v_pk_fma_f32 v[68:69], v[164:165], v[4:5], v[68:69] neg_lo:[1,0,0] neg_hi:[1,0,0]
	v_pk_fma_f32 v[70:71], v[166:167], v[6:7], v[70:71] neg_lo:[1,0,0] neg_hi:[1,0,0]
	s_waitcnt lgkmcnt(6)
	v_pk_fma_f32 v[68:69], v[168:169], v[8:9], v[68:69] neg_lo:[1,0,0] neg_hi:[1,0,0]
	v_pk_fma_f32 v[70:71], v[170:171], v[10:11], v[70:71] neg_lo:[1,0,0] neg_hi:[1,0,0]
	ds_read_b128 v[164:167], v1 offset:8704
	s_waitcnt lgkmcnt(6)
	v_pk_fma_f32 v[68:69], v[172:173], v[12:13], v[68:69] neg_lo:[1,0,0] neg_hi:[1,0,0]
	v_pk_fma_f32 v[70:71], v[174:175], v[14:15], v[70:71] neg_lo:[1,0,0] neg_hi:[1,0,0]
	ds_read_b128 v[168:171], v1 offset:8720
	s_waitcnt lgkmcnt(6)
	v_pk_fma_f32 v[68:69], v[176:177], v[16:17], v[68:69] neg_lo:[1,0,0] neg_hi:[1,0,0]
	v_pk_fma_f32 v[70:71], v[178:179], v[18:19], v[70:71] neg_lo:[1,0,0] neg_hi:[1,0,0]
	ds_read_b128 v[172:175], v1 offset:8736
	s_waitcnt lgkmcnt(6)
	v_pk_fma_f32 v[68:69], v[180:181], v[20:21], v[68:69] neg_lo:[1,0,0] neg_hi:[1,0,0]
	v_pk_fma_f32 v[70:71], v[182:183], v[22:23], v[70:71] neg_lo:[1,0,0] neg_hi:[1,0,0]
	ds_read_b128 v[176:179], v1 offset:8752
	s_waitcnt lgkmcnt(6)
	v_pk_fma_f32 v[68:69], v[184:185], v[24:25], v[68:69] neg_lo:[1,0,0] neg_hi:[1,0,0]
	v_pk_fma_f32 v[70:71], v[186:187], v[26:27], v[70:71] neg_lo:[1,0,0] neg_hi:[1,0,0]
	ds_read_b128 v[180:183], v1 offset:8768
	s_waitcnt lgkmcnt(6)
	v_pk_fma_f32 v[68:69], v[188:189], v[28:29], v[68:69] neg_lo:[1,0,0] neg_hi:[1,0,0]
	v_pk_fma_f32 v[70:71], v[190:191], v[30:31], v[70:71] neg_lo:[1,0,0] neg_hi:[1,0,0]
	ds_read_b128 v[184:187], v1 offset:8784
	s_waitcnt lgkmcnt(6)
	v_pk_fma_f32 v[68:69], v[192:193], v[32:33], v[68:69] neg_lo:[1,0,0] neg_hi:[1,0,0]
	v_fma_f32 v70, -v194, v34, v70
	ds_read_b128 v[188:191], v1 offset:8800
	ds_read_b128 v[192:195], v1 offset:8816
	v_add_f32_e32 v68, v68, v69
	v_add_f32_e32 v70, v70, v71
	v_add_f32_e32 v35, v68, v70
	v_mul_f32_e32 v72, v79, v35
	v_cvt_pk_bf16_f32 v72, v72, v72
	global_store_short v78, v72, s[38:39]
	v_add_u32_e32 v78, 0xc00, v78
	v_mov_b32_e32 v68, v36
	v_mov_b32_e32 v69, 0
	v_mov_b32_e32 v70, 0
	v_mov_b32_e32 v71, 0
	s_waitcnt lgkmcnt(7)
	v_pk_fma_f32 v[68:69], v[164:165], v[4:5], v[68:69] neg_lo:[1,0,0] neg_hi:[1,0,0]
	v_pk_fma_f32 v[70:71], v[166:167], v[6:7], v[70:71] neg_lo:[1,0,0] neg_hi:[1,0,0]
	s_waitcnt lgkmcnt(6)
	v_pk_fma_f32 v[68:69], v[168:169], v[8:9], v[68:69] neg_lo:[1,0,0] neg_hi:[1,0,0]
	v_pk_fma_f32 v[70:71], v[170:171], v[10:11], v[70:71] neg_lo:[1,0,0] neg_hi:[1,0,0]
	ds_read_b128 v[164:167], v1 offset:8976
	s_waitcnt lgkmcnt(6)
	v_pk_fma_f32 v[68:69], v[172:173], v[12:13], v[68:69] neg_lo:[1,0,0] neg_hi:[1,0,0]
	v_pk_fma_f32 v[70:71], v[174:175], v[14:15], v[70:71] neg_lo:[1,0,0] neg_hi:[1,0,0]
	ds_read_b128 v[168:171], v1 offset:8992
	s_waitcnt lgkmcnt(6)
	v_pk_fma_f32 v[68:69], v[176:177], v[16:17], v[68:69] neg_lo:[1,0,0] neg_hi:[1,0,0]
	v_pk_fma_f32 v[70:71], v[178:179], v[18:19], v[70:71] neg_lo:[1,0,0] neg_hi:[1,0,0]
	ds_read_b128 v[172:175], v1 offset:9008
	s_waitcnt lgkmcnt(6)
	v_pk_fma_f32 v[68:69], v[180:181], v[20:21], v[68:69] neg_lo:[1,0,0] neg_hi:[1,0,0]
	v_pk_fma_f32 v[70:71], v[182:183], v[22:23], v[70:71] neg_lo:[1,0,0] neg_hi:[1,0,0]
	ds_read_b128 v[176:179], v1 offset:9024
	s_waitcnt lgkmcnt(6)
	v_pk_fma_f32 v[68:69], v[184:185], v[24:25], v[68:69] neg_lo:[1,0,0] neg_hi:[1,0,0]
	v_pk_fma_f32 v[70:71], v[186:187], v[26:27], v[70:71] neg_lo:[1,0,0] neg_hi:[1,0,0]
	ds_read_b128 v[180:183], v1 offset:9040
	s_waitcnt lgkmcnt(6)
	v_pk_fma_f32 v[68:69], v[188:189], v[28:29], v[68:69] neg_lo:[1,0,0] neg_hi:[1,0,0]
	v_pk_fma_f32 v[70:71], v[190:191], v[30:31], v[70:71] neg_lo:[1,0,0] neg_hi:[1,0,0]
	ds_read_b128 v[184:187], v1 offset:9056
	s_waitcnt lgkmcnt(6)
	v_pk_fma_f32 v[68:69], v[192:193], v[32:33], v[68:69] neg_lo:[1,0,0] neg_hi:[1,0,0]
	v_pk_fma_f32 v[70:71], v[194:195], v[34:35], v[70:71] neg_lo:[1,0,0] neg_hi:[1,0,0]
	ds_read_b128 v[188:191], v1 offset:9072
	ds_read_b128 v[192:195], v1 offset:9088
	ds_read_b128 v[196:199], v1 offset:9104
	v_add_f32_e32 v68, v68, v69
	v_add_f32_e32 v70, v70, v71
	v_add_f32_e32 v36, v68, v70
	v_mul_f32_e32 v72, v79, v36
	v_cvt_pk_bf16_f32 v72, v72, v72
	global_store_short v78, v72, s[38:39]
	v_add_u32_e32 v78, 0xc00, v78
	v_mov_b32_e32 v68, v37
	v_mov_b32_e32 v69, 0
	v_mov_b32_e32 v70, 0
	v_mov_b32_e32 v71, 0
	s_waitcnt lgkmcnt(8)
	v_pk_fma_f32 v[68:69], v[164:165], v[4:5], v[68:69] neg_lo:[1,0,0] neg_hi:[1,0,0]
	v_pk_fma_f32 v[70:71], v[166:167], v[6:7], v[70:71] neg_lo:[1,0,0] neg_hi:[1,0,0]
	s_waitcnt lgkmcnt(7)
	v_pk_fma_f32 v[68:69], v[168:169], v[8:9], v[68:69] neg_lo:[1,0,0] neg_hi:[1,0,0]
	v_pk_fma_f32 v[70:71], v[170:171], v[10:11], v[70:71] neg_lo:[1,0,0] neg_hi:[1,0,0]
	ds_read_b128 v[164:167], v1 offset:9248
	s_waitcnt lgkmcnt(7)
	v_pk_fma_f32 v[68:69], v[172:173], v[12:13], v[68:69] neg_lo:[1,0,0] neg_hi:[1,0,0]
	v_pk_fma_f32 v[70:71], v[174:175], v[14:15], v[70:71] neg_lo:[1,0,0] neg_hi:[1,0,0]
	ds_read_b128 v[168:171], v1 offset:9264
	s_waitcnt lgkmcnt(7)
	v_pk_fma_f32 v[68:69], v[176:177], v[16:17], v[68:69] neg_lo:[1,0,0] neg_hi:[1,0,0]
	v_pk_fma_f32 v[70:71], v[178:179], v[18:19], v[70:71] neg_lo:[1,0,0] neg_hi:[1,0,0]
	ds_read_b128 v[172:175], v1 offset:9280
	s_waitcnt lgkmcnt(7)
	v_pk_fma_f32 v[68:69], v[180:181], v[20:21], v[68:69] neg_lo:[1,0,0] neg_hi:[1,0,0]
	v_pk_fma_f32 v[70:71], v[182:183], v[22:23], v[70:71] neg_lo:[1,0,0] neg_hi:[1,0,0]
	ds_read_b128 v[176:179], v1 offset:9296
	s_waitcnt lgkmcnt(7)
	v_pk_fma_f32 v[68:69], v[184:185], v[24:25], v[68:69] neg_lo:[1,0,0] neg_hi:[1,0,0]
	v_pk_fma_f32 v[70:71], v[186:187], v[26:27], v[70:71] neg_lo:[1,0,0] neg_hi:[1,0,0]
	ds_read_b128 v[180:183], v1 offset:9312
	s_waitcnt lgkmcnt(7)
	v_pk_fma_f32 v[68:69], v[188:189], v[28:29], v[68:69] neg_lo:[1,0,0] neg_hi:[1,0,0]
	v_pk_fma_f32 v[70:71], v[190:191], v[30:31], v[70:71] neg_lo:[1,0,0] neg_hi:[1,0,0]
	ds_read_b128 v[184:187], v1 offset:9328
	s_waitcnt lgkmcnt(7)
	v_pk_fma_f32 v[68:69], v[192:193], v[32:33], v[68:69] neg_lo:[1,0,0] neg_hi:[1,0,0]
	v_pk_fma_f32 v[70:71], v[194:195], v[34:35], v[70:71] neg_lo:[1,0,0] neg_hi:[1,0,0]
	ds_read_b128 v[188:191], v1 offset:9344
	s_waitcnt lgkmcnt(7)
	v_fma_f32 v68, -v196, v36, v68
	ds_read_b128 v[192:195], v1 offset:9360
	ds_read_b128 v[196:199], v1 offset:9376
	v_add_f32_e32 v68, v68, v69
	v_add_f32_e32 v70, v70, v71
	v_add_f32_e32 v37, v68, v70
	v_mul_f32_e32 v72, v79, v37
	v_cvt_pk_bf16_f32 v72, v72, v72
	global_store_short v78, v72, s[38:39]
	v_add_u32_e32 v78, 0xc00, v78
	v_mov_b32_e32 v68, v38
	v_mov_b32_e32 v69, 0
	v_mov_b32_e32 v70, 0
	v_mov_b32_e32 v71, 0
	s_waitcnt lgkmcnt(8)
	v_pk_fma_f32 v[68:69], v[164:165], v[4:5], v[68:69] neg_lo:[1,0,0] neg_hi:[1,0,0]
	v_pk_fma_f32 v[70:71], v[166:167], v[6:7], v[70:71] neg_lo:[1,0,0] neg_hi:[1,0,0]
	s_waitcnt lgkmcnt(7)
	v_pk_fma_f32 v[68:69], v[168:169], v[8:9], v[68:69] neg_lo:[1,0,0] neg_hi:[1,0,0]
	v_pk_fma_f32 v[70:71], v[170:171], v[10:11], v[70:71] neg_lo:[1,0,0] neg_hi:[1,0,0]
	ds_read_b128 v[164:167], v1 offset:9520
	s_waitcnt lgkmcnt(7)
	v_pk_fma_f32 v[68:69], v[172:173], v[12:13], v[68:69] neg_lo:[1,0,0] neg_hi:[1,0,0]
	v_pk_fma_f32 v[70:71], v[174:175], v[14:15], v[70:71] neg_lo:[1,0,0] neg_hi:[1,0,0]
	ds_read_b128 v[168:171], v1 offset:9536
	s_waitcnt lgkmcnt(7)
	v_pk_fma_f32 v[68:69], v[176:177], v[16:17], v[68:69] neg_lo:[1,0,0] neg_hi:[1,0,0]
	v_pk_fma_f32 v[70:71], v[178:179], v[18:19], v[70:71] neg_lo:[1,0,0] neg_hi:[1,0,0]
	ds_read_b128 v[172:175], v1 offset:9552
	s_waitcnt lgkmcnt(7)
	v_pk_fma_f32 v[68:69], v[180:181], v[20:21], v[68:69] neg_lo:[1,0,0] neg_hi:[1,0,0]
	v_pk_fma_f32 v[70:71], v[182:183], v[22:23], v[70:71] neg_lo:[1,0,0] neg_hi:[1,0,0]
	ds_read_b128 v[176:179], v1 offset:9568
	s_waitcnt lgkmcnt(7)
	v_pk_fma_f32 v[68:69], v[184:185], v[24:25], v[68:69] neg_lo:[1,0,0] neg_hi:[1,0,0]
	v_pk_fma_f32 v[70:71], v[186:187], v[26:27], v[70:71] neg_lo:[1,0,0] neg_hi:[1,0,0]
	ds_read_b128 v[180:183], v1 offset:9584
	s_waitcnt lgkmcnt(7)
	v_pk_fma_f32 v[68:69], v[188:189], v[28:29], v[68:69] neg_lo:[1,0,0] neg_hi:[1,0,0]
	v_pk_fma_f32 v[70:71], v[190:191], v[30:31], v[70:71] neg_lo:[1,0,0] neg_hi:[1,0,0]
	ds_read_b128 v[184:187], v1 offset:9600
	s_waitcnt lgkmcnt(7)
	v_pk_fma_f32 v[68:69], v[192:193], v[32:33], v[68:69] neg_lo:[1,0,0] neg_hi:[1,0,0]
	v_pk_fma_f32 v[70:71], v[194:195], v[34:35], v[70:71] neg_lo:[1,0,0] neg_hi:[1,0,0]
	ds_read_b128 v[188:191], v1 offset:9616
	s_waitcnt lgkmcnt(7)
	v_pk_fma_f32 v[68:69], v[196:197], v[36:37], v[68:69] neg_lo:[1,0,0] neg_hi:[1,0,0]
	ds_read_b128 v[192:195], v1 offset:9632
	ds_read_b128 v[196:199], v1 offset:9648
	v_add_f32_e32 v68, v68, v69
	v_add_f32_e32 v70, v70, v71
	v_add_f32_e32 v38, v68, v70
	v_mul_f32_e32 v72, v79, v38
	v_cvt_pk_bf16_f32 v72, v72, v72
	global_store_short v78, v72, s[38:39]
	v_add_u32_e32 v78, 0xc00, v78
	v_mov_b32_e32 v68, v39
	v_mov_b32_e32 v69, 0
	v_mov_b32_e32 v70, 0
	v_mov_b32_e32 v71, 0
	s_waitcnt lgkmcnt(8)
	v_pk_fma_f32 v[68:69], v[164:165], v[4:5], v[68:69] neg_lo:[1,0,0] neg_hi:[1,0,0]
	v_pk_fma_f32 v[70:71], v[166:167], v[6:7], v[70:71] neg_lo:[1,0,0] neg_hi:[1,0,0]
	s_waitcnt lgkmcnt(7)
	v_pk_fma_f32 v[68:69], v[168:169], v[8:9], v[68:69] neg_lo:[1,0,0] neg_hi:[1,0,0]
	v_pk_fma_f32 v[70:71], v[170:171], v[10:11], v[70:71] neg_lo:[1,0,0] neg_hi:[1,0,0]
	ds_read_b128 v[164:167], v1 offset:9792
	s_waitcnt lgkmcnt(7)
	v_pk_fma_f32 v[68:69], v[172:173], v[12:13], v[68:69] neg_lo:[1,0,0] neg_hi:[1,0,0]
	v_pk_fma_f32 v[70:71], v[174:175], v[14:15], v[70:71] neg_lo:[1,0,0] neg_hi:[1,0,0]
	ds_read_b128 v[168:171], v1 offset:9808
	s_waitcnt lgkmcnt(7)
	v_pk_fma_f32 v[68:69], v[176:177], v[16:17], v[68:69] neg_lo:[1,0,0] neg_hi:[1,0,0]
	v_pk_fma_f32 v[70:71], v[178:179], v[18:19], v[70:71] neg_lo:[1,0,0] neg_hi:[1,0,0]
	ds_read_b128 v[172:175], v1 offset:9824
	s_waitcnt lgkmcnt(7)
	v_pk_fma_f32 v[68:69], v[180:181], v[20:21], v[68:69] neg_lo:[1,0,0] neg_hi:[1,0,0]
	v_pk_fma_f32 v[70:71], v[182:183], v[22:23], v[70:71] neg_lo:[1,0,0] neg_hi:[1,0,0]
	ds_read_b128 v[176:179], v1 offset:9840
	s_waitcnt lgkmcnt(7)
	v_pk_fma_f32 v[68:69], v[184:185], v[24:25], v[68:69] neg_lo:[1,0,0] neg_hi:[1,0,0]
	v_pk_fma_f32 v[70:71], v[186:187], v[26:27], v[70:71] neg_lo:[1,0,0] neg_hi:[1,0,0]
	ds_read_b128 v[180:183], v1 offset:9856
	s_waitcnt lgkmcnt(7)
	v_pk_fma_f32 v[68:69], v[188:189], v[28:29], v[68:69] neg_lo:[1,0,0] neg_hi:[1,0,0]
	v_pk_fma_f32 v[70:71], v[190:191], v[30:31], v[70:71] neg_lo:[1,0,0] neg_hi:[1,0,0]
	ds_read_b128 v[184:187], v1 offset:9872
	s_waitcnt lgkmcnt(7)
	v_pk_fma_f32 v[68:69], v[192:193], v[32:33], v[68:69] neg_lo:[1,0,0] neg_hi:[1,0,0]
	v_pk_fma_f32 v[70:71], v[194:195], v[34:35], v[70:71] neg_lo:[1,0,0] neg_hi:[1,0,0]
	ds_read_b128 v[188:191], v1 offset:9888
	s_waitcnt lgkmcnt(7)
	v_pk_fma_f32 v[68:69], v[196:197], v[36:37], v[68:69] neg_lo:[1,0,0] neg_hi:[1,0,0]
	v_fma_f32 v70, -v198, v38, v70
	ds_read_b128 v[192:195], v1 offset:9904
	ds_read_b128 v[196:199], v1 offset:9920
	v_add_f32_e32 v68, v68, v69
	v_add_f32_e32 v70, v70, v71
	v_add_f32_e32 v39, v68, v70
	v_mul_f32_e32 v72, v79, v39
	v_cvt_pk_bf16_f32 v72, v72, v72
	global_store_short v78, v72, s[38:39]
	v_add_u32_e32 v78, 0xc00, v78
	v_mov_b32_e32 v68, v40
	v_mov_b32_e32 v69, 0
	v_mov_b32_e32 v70, 0
	v_mov_b32_e32 v71, 0
	s_waitcnt lgkmcnt(8)
	v_pk_fma_f32 v[68:69], v[164:165], v[4:5], v[68:69] neg_lo:[1,0,0] neg_hi:[1,0,0]
	v_pk_fma_f32 v[70:71], v[166:167], v[6:7], v[70:71] neg_lo:[1,0,0] neg_hi:[1,0,0]
	s_waitcnt lgkmcnt(7)
	v_pk_fma_f32 v[68:69], v[168:169], v[8:9], v[68:69] neg_lo:[1,0,0] neg_hi:[1,0,0]
	v_pk_fma_f32 v[70:71], v[170:171], v[10:11], v[70:71] neg_lo:[1,0,0] neg_hi:[1,0,0]
	ds_read_b128 v[164:167], v1 offset:10064
	s_waitcnt lgkmcnt(7)
	v_pk_fma_f32 v[68:69], v[172:173], v[12:13], v[68:69] neg_lo:[1,0,0] neg_hi:[1,0,0]
	v_pk_fma_f32 v[70:71], v[174:175], v[14:15], v[70:71] neg_lo:[1,0,0] neg_hi:[1,0,0]
	ds_read_b128 v[168:171], v1 offset:10080
	s_waitcnt lgkmcnt(7)
	v_pk_fma_f32 v[68:69], v[176:177], v[16:17], v[68:69] neg_lo:[1,0,0] neg_hi:[1,0,0]
	v_pk_fma_f32 v[70:71], v[178:179], v[18:19], v[70:71] neg_lo:[1,0,0] neg_hi:[1,0,0]
	ds_read_b128 v[172:175], v1 offset:10096
	s_waitcnt lgkmcnt(7)
	v_pk_fma_f32 v[68:69], v[180:181], v[20:21], v[68:69] neg_lo:[1,0,0] neg_hi:[1,0,0]
	v_pk_fma_f32 v[70:71], v[182:183], v[22:23], v[70:71] neg_lo:[1,0,0] neg_hi:[1,0,0]
	ds_read_b128 v[176:179], v1 offset:10112
	s_waitcnt lgkmcnt(7)
	v_pk_fma_f32 v[68:69], v[184:185], v[24:25], v[68:69] neg_lo:[1,0,0] neg_hi:[1,0,0]
	v_pk_fma_f32 v[70:71], v[186:187], v[26:27], v[70:71] neg_lo:[1,0,0] neg_hi:[1,0,0]
	ds_read_b128 v[180:183], v1 offset:10128
	s_waitcnt lgkmcnt(7)
	v_pk_fma_f32 v[68:69], v[188:189], v[28:29], v[68:69] neg_lo:[1,0,0] neg_hi:[1,0,0]
	v_pk_fma_f32 v[70:71], v[190:191], v[30:31], v[70:71] neg_lo:[1,0,0] neg_hi:[1,0,0]
	ds_read_b128 v[184:187], v1 offset:10144
	s_waitcnt lgkmcnt(7)
	v_pk_fma_f32 v[68:69], v[192:193], v[32:33], v[68:69] neg_lo:[1,0,0] neg_hi:[1,0,0]
	v_pk_fma_f32 v[70:71], v[194:195], v[34:35], v[70:71] neg_lo:[1,0,0] neg_hi:[1,0,0]
	ds_read_b128 v[188:191], v1 offset:10160
	s_waitcnt lgkmcnt(7)
	v_pk_fma_f32 v[68:69], v[196:197], v[36:37], v[68:69] neg_lo:[1,0,0] neg_hi:[1,0,0]
	v_pk_fma_f32 v[70:71], v[198:199], v[38:39], v[70:71] neg_lo:[1,0,0] neg_hi:[1,0,0]
	ds_read_b128 v[192:195], v1 offset:10176
	ds_read_b128 v[196:199], v1 offset:10192
	ds_read_b128 v[200:203], v1 offset:10208
	v_add_f32_e32 v68, v68, v69
	v_add_f32_e32 v70, v70, v71
	v_add_f32_e32 v40, v68, v70
	v_mul_f32_e32 v72, v79, v40
	v_cvt_pk_bf16_f32 v72, v72, v72
	global_store_short v78, v72, s[38:39]
	v_add_u32_e32 v78, 0xc00, v78
	v_mov_b32_e32 v68, v41
	v_mov_b32_e32 v69, 0
	v_mov_b32_e32 v70, 0
	v_mov_b32_e32 v71, 0
	s_waitcnt lgkmcnt(9)
	v_pk_fma_f32 v[68:69], v[164:165], v[4:5], v[68:69] neg_lo:[1,0,0] neg_hi:[1,0,0]
	v_pk_fma_f32 v[70:71], v[166:167], v[6:7], v[70:71] neg_lo:[1,0,0] neg_hi:[1,0,0]
	s_waitcnt lgkmcnt(8)
	v_pk_fma_f32 v[68:69], v[168:169], v[8:9], v[68:69] neg_lo:[1,0,0] neg_hi:[1,0,0]
	v_pk_fma_f32 v[70:71], v[170:171], v[10:11], v[70:71] neg_lo:[1,0,0] neg_hi:[1,0,0]
	ds_read_b128 v[164:167], v1 offset:10336
	s_waitcnt lgkmcnt(8)
	v_pk_fma_f32 v[68:69], v[172:173], v[12:13], v[68:69] neg_lo:[1,0,0] neg_hi:[1,0,0]
	v_pk_fma_f32 v[70:71], v[174:175], v[14:15], v[70:71] neg_lo:[1,0,0] neg_hi:[1,0,0]
	ds_read_b128 v[168:171], v1 offset:10352
	s_waitcnt lgkmcnt(8)
	v_pk_fma_f32 v[68:69], v[176:177], v[16:17], v[68:69] neg_lo:[1,0,0] neg_hi:[1,0,0]
	v_pk_fma_f32 v[70:71], v[178:179], v[18:19], v[70:71] neg_lo:[1,0,0] neg_hi:[1,0,0]
	ds_read_b128 v[172:175], v1 offset:10368
	s_waitcnt lgkmcnt(8)
	v_pk_fma_f32 v[68:69], v[180:181], v[20:21], v[68:69] neg_lo:[1,0,0] neg_hi:[1,0,0]
	v_pk_fma_f32 v[70:71], v[182:183], v[22:23], v[70:71] neg_lo:[1,0,0] neg_hi:[1,0,0]
	ds_read_b128 v[176:179], v1 offset:10384
	s_waitcnt lgkmcnt(8)
	v_pk_fma_f32 v[68:69], v[184:185], v[24:25], v[68:69] neg_lo:[1,0,0] neg_hi:[1,0,0]
	v_pk_fma_f32 v[70:71], v[186:187], v[26:27], v[70:71] neg_lo:[1,0,0] neg_hi:[1,0,0]
	ds_read_b128 v[180:183], v1 offset:10400
	s_waitcnt lgkmcnt(8)
	v_pk_fma_f32 v[68:69], v[188:189], v[28:29], v[68:69] neg_lo:[1,0,0] neg_hi:[1,0,0]
	v_pk_fma_f32 v[70:71], v[190:191], v[30:31], v[70:71] neg_lo:[1,0,0] neg_hi:[1,0,0]
	ds_read_b128 v[184:187], v1 offset:10416
	s_waitcnt lgkmcnt(8)
	v_pk_fma_f32 v[68:69], v[192:193], v[32:33], v[68:69] neg_lo:[1,0,0] neg_hi:[1,0,0]
	v_pk_fma_f32 v[70:71], v[194:195], v[34:35], v[70:71] neg_lo:[1,0,0] neg_hi:[1,0,0]
	ds_read_b128 v[188:191], v1 offset:10432
	s_waitcnt lgkmcnt(8)
	v_pk_fma_f32 v[68:69], v[196:197], v[36:37], v[68:69] neg_lo:[1,0,0] neg_hi:[1,0,0]
	v_pk_fma_f32 v[70:71], v[198:199], v[38:39], v[70:71] neg_lo:[1,0,0] neg_hi:[1,0,0]
	ds_read_b128 v[192:195], v1 offset:10448
	s_waitcnt lgkmcnt(8)
	v_fma_f32 v68, -v200, v40, v68
	ds_read_b128 v[196:199], v1 offset:10464
	ds_read_b128 v[200:203], v1 offset:10480
	v_add_f32_e32 v68, v68, v69
	v_add_f32_e32 v70, v70, v71
	v_add_f32_e32 v41, v68, v70
	v_mul_f32_e32 v72, v79, v41
	v_cvt_pk_bf16_f32 v72, v72, v72
	global_store_short v78, v72, s[38:39]
	v_add_u32_e32 v78, 0xc00, v78
	v_mov_b32_e32 v68, v42
	v_mov_b32_e32 v69, 0
	v_mov_b32_e32 v70, 0
	v_mov_b32_e32 v71, 0
	s_waitcnt lgkmcnt(9)
	v_pk_fma_f32 v[68:69], v[164:165], v[4:5], v[68:69] neg_lo:[1,0,0] neg_hi:[1,0,0]
	v_pk_fma_f32 v[70:71], v[166:167], v[6:7], v[70:71] neg_lo:[1,0,0] neg_hi:[1,0,0]
	s_waitcnt lgkmcnt(8)
	v_pk_fma_f32 v[68:69], v[168:169], v[8:9], v[68:69] neg_lo:[1,0,0] neg_hi:[1,0,0]
	v_pk_fma_f32 v[70:71], v[170:171], v[10:11], v[70:71] neg_lo:[1,0,0] neg_hi:[1,0,0]
	ds_read_b128 v[164:167], v1 offset:10608
	s_waitcnt lgkmcnt(8)
	v_pk_fma_f32 v[68:69], v[172:173], v[12:13], v[68:69] neg_lo:[1,0,0] neg_hi:[1,0,0]
	v_pk_fma_f32 v[70:71], v[174:175], v[14:15], v[70:71] neg_lo:[1,0,0] neg_hi:[1,0,0]
	ds_read_b128 v[168:171], v1 offset:10624
	s_waitcnt lgkmcnt(8)
	v_pk_fma_f32 v[68:69], v[176:177], v[16:17], v[68:69] neg_lo:[1,0,0] neg_hi:[1,0,0]
	v_pk_fma_f32 v[70:71], v[178:179], v[18:19], v[70:71] neg_lo:[1,0,0] neg_hi:[1,0,0]
	ds_read_b128 v[172:175], v1 offset:10640
	s_waitcnt lgkmcnt(8)
	v_pk_fma_f32 v[68:69], v[180:181], v[20:21], v[68:69] neg_lo:[1,0,0] neg_hi:[1,0,0]
	v_pk_fma_f32 v[70:71], v[182:183], v[22:23], v[70:71] neg_lo:[1,0,0] neg_hi:[1,0,0]
	ds_read_b128 v[176:179], v1 offset:10656
	s_waitcnt lgkmcnt(8)
	v_pk_fma_f32 v[68:69], v[184:185], v[24:25], v[68:69] neg_lo:[1,0,0] neg_hi:[1,0,0]
	v_pk_fma_f32 v[70:71], v[186:187], v[26:27], v[70:71] neg_lo:[1,0,0] neg_hi:[1,0,0]
	ds_read_b128 v[180:183], v1 offset:10672
	s_waitcnt lgkmcnt(8)
	v_pk_fma_f32 v[68:69], v[188:189], v[28:29], v[68:69] neg_lo:[1,0,0] neg_hi:[1,0,0]
	v_pk_fma_f32 v[70:71], v[190:191], v[30:31], v[70:71] neg_lo:[1,0,0] neg_hi:[1,0,0]
	ds_read_b128 v[184:187], v1 offset:10688
	s_waitcnt lgkmcnt(8)
	v_pk_fma_f32 v[68:69], v[192:193], v[32:33], v[68:69] neg_lo:[1,0,0] neg_hi:[1,0,0]
	v_pk_fma_f32 v[70:71], v[194:195], v[34:35], v[70:71] neg_lo:[1,0,0] neg_hi:[1,0,0]
	ds_read_b128 v[188:191], v1 offset:10704
	s_waitcnt lgkmcnt(8)
	v_pk_fma_f32 v[68:69], v[196:197], v[36:37], v[68:69] neg_lo:[1,0,0] neg_hi:[1,0,0]
	v_pk_fma_f32 v[70:71], v[198:199], v[38:39], v[70:71] neg_lo:[1,0,0] neg_hi:[1,0,0]
	ds_read_b128 v[192:195], v1 offset:10720
	s_waitcnt lgkmcnt(8)
	v_pk_fma_f32 v[68:69], v[200:201], v[40:41], v[68:69] neg_lo:[1,0,0] neg_hi:[1,0,0]
	ds_read_b128 v[196:199], v1 offset:10736
	ds_read_b128 v[200:203], v1 offset:10752
	v_add_f32_e32 v68, v68, v69
	v_add_f32_e32 v70, v70, v71
	v_add_f32_e32 v42, v68, v70
	v_mul_f32_e32 v72, v79, v42
	v_cvt_pk_bf16_f32 v72, v72, v72
	global_store_short v78, v72, s[38:39]
	v_add_u32_e32 v78, 0xc00, v78
	v_mov_b32_e32 v68, v43
	v_mov_b32_e32 v69, 0
	v_mov_b32_e32 v70, 0
	v_mov_b32_e32 v71, 0
	s_waitcnt lgkmcnt(9)
	v_pk_fma_f32 v[68:69], v[164:165], v[4:5], v[68:69] neg_lo:[1,0,0] neg_hi:[1,0,0]
	v_pk_fma_f32 v[70:71], v[166:167], v[6:7], v[70:71] neg_lo:[1,0,0] neg_hi:[1,0,0]
	s_waitcnt lgkmcnt(8)
	v_pk_fma_f32 v[68:69], v[168:169], v[8:9], v[68:69] neg_lo:[1,0,0] neg_hi:[1,0,0]
	v_pk_fma_f32 v[70:71], v[170:171], v[10:11], v[70:71] neg_lo:[1,0,0] neg_hi:[1,0,0]
	ds_read_b128 v[164:167], v1 offset:10880
	s_waitcnt lgkmcnt(8)
	v_pk_fma_f32 v[68:69], v[172:173], v[12:13], v[68:69] neg_lo:[1,0,0] neg_hi:[1,0,0]
	v_pk_fma_f32 v[70:71], v[174:175], v[14:15], v[70:71] neg_lo:[1,0,0] neg_hi:[1,0,0]
	ds_read_b128 v[168:171], v1 offset:10896
	s_waitcnt lgkmcnt(8)
	v_pk_fma_f32 v[68:69], v[176:177], v[16:17], v[68:69] neg_lo:[1,0,0] neg_hi:[1,0,0]
	v_pk_fma_f32 v[70:71], v[178:179], v[18:19], v[70:71] neg_lo:[1,0,0] neg_hi:[1,0,0]
	ds_read_b128 v[172:175], v1 offset:10912
	s_waitcnt lgkmcnt(8)
	v_pk_fma_f32 v[68:69], v[180:181], v[20:21], v[68:69] neg_lo:[1,0,0] neg_hi:[1,0,0]
	v_pk_fma_f32 v[70:71], v[182:183], v[22:23], v[70:71] neg_lo:[1,0,0] neg_hi:[1,0,0]
	ds_read_b128 v[176:179], v1 offset:10928
	s_waitcnt lgkmcnt(8)
	v_pk_fma_f32 v[68:69], v[184:185], v[24:25], v[68:69] neg_lo:[1,0,0] neg_hi:[1,0,0]
	v_pk_fma_f32 v[70:71], v[186:187], v[26:27], v[70:71] neg_lo:[1,0,0] neg_hi:[1,0,0]
	ds_read_b128 v[180:183], v1 offset:10944
	s_waitcnt lgkmcnt(8)
	v_pk_fma_f32 v[68:69], v[188:189], v[28:29], v[68:69] neg_lo:[1,0,0] neg_hi:[1,0,0]
	v_pk_fma_f32 v[70:71], v[190:191], v[30:31], v[70:71] neg_lo:[1,0,0] neg_hi:[1,0,0]
	ds_read_b128 v[184:187], v1 offset:10960
	s_waitcnt lgkmcnt(8)
	v_pk_fma_f32 v[68:69], v[192:193], v[32:33], v[68:69] neg_lo:[1,0,0] neg_hi:[1,0,0]
	v_pk_fma_f32 v[70:71], v[194:195], v[34:35], v[70:71] neg_lo:[1,0,0] neg_hi:[1,0,0]
	ds_read_b128 v[188:191], v1 offset:10976
	s_waitcnt lgkmcnt(8)
	v_pk_fma_f32 v[68:69], v[196:197], v[36:37], v[68:69] neg_lo:[1,0,0] neg_hi:[1,0,0]
	v_pk_fma_f32 v[70:71], v[198:199], v[38:39], v[70:71] neg_lo:[1,0,0] neg_hi:[1,0,0]
	ds_read_b128 v[192:195], v1 offset:10992
	s_waitcnt lgkmcnt(8)
	v_pk_fma_f32 v[68:69], v[200:201], v[40:41], v[68:69] neg_lo:[1,0,0] neg_hi:[1,0,0]
	v_fma_f32 v70, -v202, v42, v70
	ds_read_b128 v[196:199], v1 offset:11008
	ds_read_b128 v[200:203], v1 offset:11024
	v_add_f32_e32 v68, v68, v69
	v_add_f32_e32 v70, v70, v71
	v_add_f32_e32 v43, v68, v70
	v_mul_f32_e32 v72, v79, v43
	v_cvt_pk_bf16_f32 v72, v72, v72
	global_store_short v78, v72, s[38:39]
	v_add_u32_e32 v78, 0xc00, v78
	v_mov_b32_e32 v68, v44
	v_mov_b32_e32 v69, 0
	v_mov_b32_e32 v70, 0
	v_mov_b32_e32 v71, 0
	s_waitcnt lgkmcnt(9)
	v_pk_fma_f32 v[68:69], v[164:165], v[4:5], v[68:69] neg_lo:[1,0,0] neg_hi:[1,0,0]
	v_pk_fma_f32 v[70:71], v[166:167], v[6:7], v[70:71] neg_lo:[1,0,0] neg_hi:[1,0,0]
	s_waitcnt lgkmcnt(8)
	v_pk_fma_f32 v[68:69], v[168:169], v[8:9], v[68:69] neg_lo:[1,0,0] neg_hi:[1,0,0]
	v_pk_fma_f32 v[70:71], v[170:171], v[10:11], v[70:71] neg_lo:[1,0,0] neg_hi:[1,0,0]
	ds_read_b128 v[164:167], v1 offset:11152
	s_waitcnt lgkmcnt(8)
	v_pk_fma_f32 v[68:69], v[172:173], v[12:13], v[68:69] neg_lo:[1,0,0] neg_hi:[1,0,0]
	v_pk_fma_f32 v[70:71], v[174:175], v[14:15], v[70:71] neg_lo:[1,0,0] neg_hi:[1,0,0]
	ds_read_b128 v[168:171], v1 offset:11168
	s_waitcnt lgkmcnt(8)
	v_pk_fma_f32 v[68:69], v[176:177], v[16:17], v[68:69] neg_lo:[1,0,0] neg_hi:[1,0,0]
	v_pk_fma_f32 v[70:71], v[178:179], v[18:19], v[70:71] neg_lo:[1,0,0] neg_hi:[1,0,0]
	ds_read_b128 v[172:175], v1 offset:11184
	s_waitcnt lgkmcnt(8)
	v_pk_fma_f32 v[68:69], v[180:181], v[20:21], v[68:69] neg_lo:[1,0,0] neg_hi:[1,0,0]
	v_pk_fma_f32 v[70:71], v[182:183], v[22:23], v[70:71] neg_lo:[1,0,0] neg_hi:[1,0,0]
	ds_read_b128 v[176:179], v1 offset:11200
	s_waitcnt lgkmcnt(8)
	v_pk_fma_f32 v[68:69], v[184:185], v[24:25], v[68:69] neg_lo:[1,0,0] neg_hi:[1,0,0]
	v_pk_fma_f32 v[70:71], v[186:187], v[26:27], v[70:71] neg_lo:[1,0,0] neg_hi:[1,0,0]
	ds_read_b128 v[180:183], v1 offset:11216
	s_waitcnt lgkmcnt(8)
	v_pk_fma_f32 v[68:69], v[188:189], v[28:29], v[68:69] neg_lo:[1,0,0] neg_hi:[1,0,0]
	v_pk_fma_f32 v[70:71], v[190:191], v[30:31], v[70:71] neg_lo:[1,0,0] neg_hi:[1,0,0]
	ds_read_b128 v[184:187], v1 offset:11232
	s_waitcnt lgkmcnt(8)
	v_pk_fma_f32 v[68:69], v[192:193], v[32:33], v[68:69] neg_lo:[1,0,0] neg_hi:[1,0,0]
	v_pk_fma_f32 v[70:71], v[194:195], v[34:35], v[70:71] neg_lo:[1,0,0] neg_hi:[1,0,0]
	ds_read_b128 v[188:191], v1 offset:11248
	s_waitcnt lgkmcnt(8)
	v_pk_fma_f32 v[68:69], v[196:197], v[36:37], v[68:69] neg_lo:[1,0,0] neg_hi:[1,0,0]
	v_pk_fma_f32 v[70:71], v[198:199], v[38:39], v[70:71] neg_lo:[1,0,0] neg_hi:[1,0,0]
	ds_read_b128 v[192:195], v1 offset:11264
	s_waitcnt lgkmcnt(8)
	v_pk_fma_f32 v[68:69], v[200:201], v[40:41], v[68:69] neg_lo:[1,0,0] neg_hi:[1,0,0]
	v_pk_fma_f32 v[70:71], v[202:203], v[42:43], v[70:71] neg_lo:[1,0,0] neg_hi:[1,0,0]
	ds_read_b128 v[196:199], v1 offset:11280
	ds_read_b128 v[200:203], v1 offset:11296
	ds_read_b128 v[204:207], v1 offset:11312
	v_add_f32_e32 v68, v68, v69
	v_add_f32_e32 v70, v70, v71
	v_add_f32_e32 v44, v68, v70
	v_mul_f32_e32 v72, v79, v44
	v_cvt_pk_bf16_f32 v72, v72, v72
	global_store_short v78, v72, s[38:39]
	v_add_u32_e32 v78, 0xc00, v78
	v_mov_b32_e32 v68, v45
	v_mov_b32_e32 v69, 0
	v_mov_b32_e32 v70, 0
	v_mov_b32_e32 v71, 0
	s_waitcnt lgkmcnt(10)
	v_pk_fma_f32 v[68:69], v[164:165], v[4:5], v[68:69] neg_lo:[1,0,0] neg_hi:[1,0,0]
	v_pk_fma_f32 v[70:71], v[166:167], v[6:7], v[70:71] neg_lo:[1,0,0] neg_hi:[1,0,0]
	s_waitcnt lgkmcnt(9)
	v_pk_fma_f32 v[68:69], v[168:169], v[8:9], v[68:69] neg_lo:[1,0,0] neg_hi:[1,0,0]
	v_pk_fma_f32 v[70:71], v[170:171], v[10:11], v[70:71] neg_lo:[1,0,0] neg_hi:[1,0,0]
	ds_read_b128 v[164:167], v1 offset:11424
	s_waitcnt lgkmcnt(9)
	v_pk_fma_f32 v[68:69], v[172:173], v[12:13], v[68:69] neg_lo:[1,0,0] neg_hi:[1,0,0]
	v_pk_fma_f32 v[70:71], v[174:175], v[14:15], v[70:71] neg_lo:[1,0,0] neg_hi:[1,0,0]
	ds_read_b128 v[168:171], v1 offset:11440
	s_waitcnt lgkmcnt(9)
	v_pk_fma_f32 v[68:69], v[176:177], v[16:17], v[68:69] neg_lo:[1,0,0] neg_hi:[1,0,0]
	v_pk_fma_f32 v[70:71], v[178:179], v[18:19], v[70:71] neg_lo:[1,0,0] neg_hi:[1,0,0]
	ds_read_b128 v[172:175], v1 offset:11456
	s_waitcnt lgkmcnt(9)
	v_pk_fma_f32 v[68:69], v[180:181], v[20:21], v[68:69] neg_lo:[1,0,0] neg_hi:[1,0,0]
	v_pk_fma_f32 v[70:71], v[182:183], v[22:23], v[70:71] neg_lo:[1,0,0] neg_hi:[1,0,0]
	ds_read_b128 v[176:179], v1 offset:11472
	s_waitcnt lgkmcnt(9)
	v_pk_fma_f32 v[68:69], v[184:185], v[24:25], v[68:69] neg_lo:[1,0,0] neg_hi:[1,0,0]
	v_pk_fma_f32 v[70:71], v[186:187], v[26:27], v[70:71] neg_lo:[1,0,0] neg_hi:[1,0,0]
	ds_read_b128 v[180:183], v1 offset:11488
	s_waitcnt lgkmcnt(9)
	v_pk_fma_f32 v[68:69], v[188:189], v[28:29], v[68:69] neg_lo:[1,0,0] neg_hi:[1,0,0]
	v_pk_fma_f32 v[70:71], v[190:191], v[30:31], v[70:71] neg_lo:[1,0,0] neg_hi:[1,0,0]
	ds_read_b128 v[184:187], v1 offset:11504
	s_waitcnt lgkmcnt(9)
	v_pk_fma_f32 v[68:69], v[192:193], v[32:33], v[68:69] neg_lo:[1,0,0] neg_hi:[1,0,0]
	v_pk_fma_f32 v[70:71], v[194:195], v[34:35], v[70:71] neg_lo:[1,0,0] neg_hi:[1,0,0]
	ds_read_b128 v[188:191], v1 offset:11520
	s_waitcnt lgkmcnt(9)
	v_pk_fma_f32 v[68:69], v[196:197], v[36:37], v[68:69] neg_lo:[1,0,0] neg_hi:[1,0,0]
	v_pk_fma_f32 v[70:71], v[198:199], v[38:39], v[70:71] neg_lo:[1,0,0] neg_hi:[1,0,0]
	ds_read_b128 v[192:195], v1 offset:11536
	s_waitcnt lgkmcnt(9)
	v_pk_fma_f32 v[68:69], v[200:201], v[40:41], v[68:69] neg_lo:[1,0,0] neg_hi:[1,0,0]
	v_pk_fma_f32 v[70:71], v[202:203], v[42:43], v[70:71] neg_lo:[1,0,0] neg_hi:[1,0,0]
	ds_read_b128 v[196:199], v1 offset:11552
	s_waitcnt lgkmcnt(9)
	v_fma_f32 v68, -v204, v44, v68
	ds_read_b128 v[200:203], v1 offset:11568
	ds_read_b128 v[204:207], v1 offset:11584
	v_add_f32_e32 v68, v68, v69
	v_add_f32_e32 v70, v70, v71
	v_add_f32_e32 v45, v68, v70
	v_mul_f32_e32 v72, v79, v45
	v_cvt_pk_bf16_f32 v72, v72, v72
	global_store_short v78, v72, s[38:39]
	v_add_u32_e32 v78, 0xc00, v78
	v_mov_b32_e32 v68, v46
	v_mov_b32_e32 v69, 0
	v_mov_b32_e32 v70, 0
	v_mov_b32_e32 v71, 0
	s_waitcnt lgkmcnt(10)
	v_pk_fma_f32 v[68:69], v[164:165], v[4:5], v[68:69] neg_lo:[1,0,0] neg_hi:[1,0,0]
	v_pk_fma_f32 v[70:71], v[166:167], v[6:7], v[70:71] neg_lo:[1,0,0] neg_hi:[1,0,0]
	s_waitcnt lgkmcnt(9)
	v_pk_fma_f32 v[68:69], v[168:169], v[8:9], v[68:69] neg_lo:[1,0,0] neg_hi:[1,0,0]
	v_pk_fma_f32 v[70:71], v[170:171], v[10:11], v[70:71] neg_lo:[1,0,0] neg_hi:[1,0,0]
	ds_read_b128 v[164:167], v1 offset:11696
	s_waitcnt lgkmcnt(9)
	v_pk_fma_f32 v[68:69], v[172:173], v[12:13], v[68:69] neg_lo:[1,0,0] neg_hi:[1,0,0]
	v_pk_fma_f32 v[70:71], v[174:175], v[14:15], v[70:71] neg_lo:[1,0,0] neg_hi:[1,0,0]
	ds_read_b128 v[168:171], v1 offset:11712
	s_waitcnt lgkmcnt(9)
	v_pk_fma_f32 v[68:69], v[176:177], v[16:17], v[68:69] neg_lo:[1,0,0] neg_hi:[1,0,0]
	v_pk_fma_f32 v[70:71], v[178:179], v[18:19], v[70:71] neg_lo:[1,0,0] neg_hi:[1,0,0]
	ds_read_b128 v[172:175], v1 offset:11728
	s_waitcnt lgkmcnt(9)
	v_pk_fma_f32 v[68:69], v[180:181], v[20:21], v[68:69] neg_lo:[1,0,0] neg_hi:[1,0,0]
	v_pk_fma_f32 v[70:71], v[182:183], v[22:23], v[70:71] neg_lo:[1,0,0] neg_hi:[1,0,0]
	ds_read_b128 v[176:179], v1 offset:11744
	s_waitcnt lgkmcnt(9)
	v_pk_fma_f32 v[68:69], v[184:185], v[24:25], v[68:69] neg_lo:[1,0,0] neg_hi:[1,0,0]
	v_pk_fma_f32 v[70:71], v[186:187], v[26:27], v[70:71] neg_lo:[1,0,0] neg_hi:[1,0,0]
	ds_read_b128 v[180:183], v1 offset:11760
	s_waitcnt lgkmcnt(9)
	v_pk_fma_f32 v[68:69], v[188:189], v[28:29], v[68:69] neg_lo:[1,0,0] neg_hi:[1,0,0]
	v_pk_fma_f32 v[70:71], v[190:191], v[30:31], v[70:71] neg_lo:[1,0,0] neg_hi:[1,0,0]
	ds_read_b128 v[184:187], v1 offset:11776
	s_waitcnt lgkmcnt(9)
	v_pk_fma_f32 v[68:69], v[192:193], v[32:33], v[68:69] neg_lo:[1,0,0] neg_hi:[1,0,0]
	v_pk_fma_f32 v[70:71], v[194:195], v[34:35], v[70:71] neg_lo:[1,0,0] neg_hi:[1,0,0]
	ds_read_b128 v[188:191], v1 offset:11792
	s_waitcnt lgkmcnt(9)
	v_pk_fma_f32 v[68:69], v[196:197], v[36:37], v[68:69] neg_lo:[1,0,0] neg_hi:[1,0,0]
	v_pk_fma_f32 v[70:71], v[198:199], v[38:39], v[70:71] neg_lo:[1,0,0] neg_hi:[1,0,0]
	ds_read_b128 v[192:195], v1 offset:11808
	s_waitcnt lgkmcnt(9)
	v_pk_fma_f32 v[68:69], v[200:201], v[40:41], v[68:69] neg_lo:[1,0,0] neg_hi:[1,0,0]
	v_pk_fma_f32 v[70:71], v[202:203], v[42:43], v[70:71] neg_lo:[1,0,0] neg_hi:[1,0,0]
	ds_read_b128 v[196:199], v1 offset:11824
	s_waitcnt lgkmcnt(9)
	v_pk_fma_f32 v[68:69], v[204:205], v[44:45], v[68:69] neg_lo:[1,0,0] neg_hi:[1,0,0]
	ds_read_b128 v[200:203], v1 offset:11840
	ds_read_b128 v[204:207], v1 offset:11856
	v_add_f32_e32 v68, v68, v69
	v_add_f32_e32 v70, v70, v71
	v_add_f32_e32 v46, v68, v70
	v_mul_f32_e32 v72, v79, v46
	v_cvt_pk_bf16_f32 v72, v72, v72
	global_store_short v78, v72, s[38:39]
	v_add_u32_e32 v78, 0xc00, v78
	v_mov_b32_e32 v68, v47
	v_mov_b32_e32 v69, 0
	v_mov_b32_e32 v70, 0
	v_mov_b32_e32 v71, 0
	s_waitcnt lgkmcnt(10)
	v_pk_fma_f32 v[68:69], v[164:165], v[4:5], v[68:69] neg_lo:[1,0,0] neg_hi:[1,0,0]
	v_pk_fma_f32 v[70:71], v[166:167], v[6:7], v[70:71] neg_lo:[1,0,0] neg_hi:[1,0,0]
	s_waitcnt lgkmcnt(9)
	v_pk_fma_f32 v[68:69], v[168:169], v[8:9], v[68:69] neg_lo:[1,0,0] neg_hi:[1,0,0]
	v_pk_fma_f32 v[70:71], v[170:171], v[10:11], v[70:71] neg_lo:[1,0,0] neg_hi:[1,0,0]
	ds_read_b128 v[164:167], v1 offset:11968
	s_waitcnt lgkmcnt(9)
	v_pk_fma_f32 v[68:69], v[172:173], v[12:13], v[68:69] neg_lo:[1,0,0] neg_hi:[1,0,0]
	v_pk_fma_f32 v[70:71], v[174:175], v[14:15], v[70:71] neg_lo:[1,0,0] neg_hi:[1,0,0]
	ds_read_b128 v[168:171], v1 offset:11984
	s_waitcnt lgkmcnt(9)
	v_pk_fma_f32 v[68:69], v[176:177], v[16:17], v[68:69] neg_lo:[1,0,0] neg_hi:[1,0,0]
	v_pk_fma_f32 v[70:71], v[178:179], v[18:19], v[70:71] neg_lo:[1,0,0] neg_hi:[1,0,0]
	ds_read_b128 v[172:175], v1 offset:12000
	s_waitcnt lgkmcnt(9)
	v_pk_fma_f32 v[68:69], v[180:181], v[20:21], v[68:69] neg_lo:[1,0,0] neg_hi:[1,0,0]
	v_pk_fma_f32 v[70:71], v[182:183], v[22:23], v[70:71] neg_lo:[1,0,0] neg_hi:[1,0,0]
	ds_read_b128 v[176:179], v1 offset:12016
	s_waitcnt lgkmcnt(9)
	v_pk_fma_f32 v[68:69], v[184:185], v[24:25], v[68:69] neg_lo:[1,0,0] neg_hi:[1,0,0]
	v_pk_fma_f32 v[70:71], v[186:187], v[26:27], v[70:71] neg_lo:[1,0,0] neg_hi:[1,0,0]
	ds_read_b128 v[180:183], v1 offset:12032
	s_waitcnt lgkmcnt(9)
	v_pk_fma_f32 v[68:69], v[188:189], v[28:29], v[68:69] neg_lo:[1,0,0] neg_hi:[1,0,0]
	v_pk_fma_f32 v[70:71], v[190:191], v[30:31], v[70:71] neg_lo:[1,0,0] neg_hi:[1,0,0]
	ds_read_b128 v[184:187], v1 offset:12048
	s_waitcnt lgkmcnt(9)
	v_pk_fma_f32 v[68:69], v[192:193], v[32:33], v[68:69] neg_lo:[1,0,0] neg_hi:[1,0,0]
	v_pk_fma_f32 v[70:71], v[194:195], v[34:35], v[70:71] neg_lo:[1,0,0] neg_hi:[1,0,0]
	ds_read_b128 v[188:191], v1 offset:12064
	s_waitcnt lgkmcnt(9)
	v_pk_fma_f32 v[68:69], v[196:197], v[36:37], v[68:69] neg_lo:[1,0,0] neg_hi:[1,0,0]
	v_pk_fma_f32 v[70:71], v[198:199], v[38:39], v[70:71] neg_lo:[1,0,0] neg_hi:[1,0,0]
	ds_read_b128 v[192:195], v1 offset:12080
	s_waitcnt lgkmcnt(9)
	v_pk_fma_f32 v[68:69], v[200:201], v[40:41], v[68:69] neg_lo:[1,0,0] neg_hi:[1,0,0]
	v_pk_fma_f32 v[70:71], v[202:203], v[42:43], v[70:71] neg_lo:[1,0,0] neg_hi:[1,0,0]
	ds_read_b128 v[196:199], v1 offset:12096
	s_waitcnt lgkmcnt(9)
	v_pk_fma_f32 v[68:69], v[204:205], v[44:45], v[68:69] neg_lo:[1,0,0] neg_hi:[1,0,0]
	v_fma_f32 v70, -v206, v46, v70
	ds_read_b128 v[200:203], v1 offset:12112
	ds_read_b128 v[204:207], v1 offset:12128
	v_add_f32_e32 v68, v68, v69
	v_add_f32_e32 v70, v70, v71
	v_add_f32_e32 v47, v68, v70
	v_mul_f32_e32 v72, v79, v47
	v_cvt_pk_bf16_f32 v72, v72, v72
	global_store_short v78, v72, s[38:39]
	v_add_u32_e32 v78, 0xc00, v78
	v_mov_b32_e32 v68, v48
	v_mov_b32_e32 v69, 0
	v_mov_b32_e32 v70, 0
	v_mov_b32_e32 v71, 0
	s_waitcnt lgkmcnt(10)
	v_pk_fma_f32 v[68:69], v[164:165], v[4:5], v[68:69] neg_lo:[1,0,0] neg_hi:[1,0,0]
	v_pk_fma_f32 v[70:71], v[166:167], v[6:7], v[70:71] neg_lo:[1,0,0] neg_hi:[1,0,0]
	s_waitcnt lgkmcnt(9)
	v_pk_fma_f32 v[68:69], v[168:169], v[8:9], v[68:69] neg_lo:[1,0,0] neg_hi:[1,0,0]
	v_pk_fma_f32 v[70:71], v[170:171], v[10:11], v[70:71] neg_lo:[1,0,0] neg_hi:[1,0,0]
	ds_read_b128 v[164:167], v1 offset:12240
	s_waitcnt lgkmcnt(9)
	v_pk_fma_f32 v[68:69], v[172:173], v[12:13], v[68:69] neg_lo:[1,0,0] neg_hi:[1,0,0]
	v_pk_fma_f32 v[70:71], v[174:175], v[14:15], v[70:71] neg_lo:[1,0,0] neg_hi:[1,0,0]
	ds_read_b128 v[168:171], v1 offset:12256
	s_waitcnt lgkmcnt(9)
	v_pk_fma_f32 v[68:69], v[176:177], v[16:17], v[68:69] neg_lo:[1,0,0] neg_hi:[1,0,0]
	v_pk_fma_f32 v[70:71], v[178:179], v[18:19], v[70:71] neg_lo:[1,0,0] neg_hi:[1,0,0]
	ds_read_b128 v[172:175], v1 offset:12272
	s_waitcnt lgkmcnt(9)
	v_pk_fma_f32 v[68:69], v[180:181], v[20:21], v[68:69] neg_lo:[1,0,0] neg_hi:[1,0,0]
	v_pk_fma_f32 v[70:71], v[182:183], v[22:23], v[70:71] neg_lo:[1,0,0] neg_hi:[1,0,0]
	ds_read_b128 v[176:179], v1 offset:12288
	s_waitcnt lgkmcnt(9)
	v_pk_fma_f32 v[68:69], v[184:185], v[24:25], v[68:69] neg_lo:[1,0,0] neg_hi:[1,0,0]
	v_pk_fma_f32 v[70:71], v[186:187], v[26:27], v[70:71] neg_lo:[1,0,0] neg_hi:[1,0,0]
	ds_read_b128 v[180:183], v1 offset:12304
	s_waitcnt lgkmcnt(9)
	v_pk_fma_f32 v[68:69], v[188:189], v[28:29], v[68:69] neg_lo:[1,0,0] neg_hi:[1,0,0]
	v_pk_fma_f32 v[70:71], v[190:191], v[30:31], v[70:71] neg_lo:[1,0,0] neg_hi:[1,0,0]
	ds_read_b128 v[184:187], v1 offset:12320
	s_waitcnt lgkmcnt(9)
	v_pk_fma_f32 v[68:69], v[192:193], v[32:33], v[68:69] neg_lo:[1,0,0] neg_hi:[1,0,0]
	v_pk_fma_f32 v[70:71], v[194:195], v[34:35], v[70:71] neg_lo:[1,0,0] neg_hi:[1,0,0]
	ds_read_b128 v[188:191], v1 offset:12336
	s_waitcnt lgkmcnt(9)
	v_pk_fma_f32 v[68:69], v[196:197], v[36:37], v[68:69] neg_lo:[1,0,0] neg_hi:[1,0,0]
	v_pk_fma_f32 v[70:71], v[198:199], v[38:39], v[70:71] neg_lo:[1,0,0] neg_hi:[1,0,0]
	ds_read_b128 v[192:195], v1 offset:12352
	s_waitcnt lgkmcnt(9)
	v_pk_fma_f32 v[68:69], v[200:201], v[40:41], v[68:69] neg_lo:[1,0,0] neg_hi:[1,0,0]
	v_pk_fma_f32 v[70:71], v[202:203], v[42:43], v[70:71] neg_lo:[1,0,0] neg_hi:[1,0,0]
	ds_read_b128 v[196:199], v1 offset:12368
	s_waitcnt lgkmcnt(9)
	v_pk_fma_f32 v[68:69], v[204:205], v[44:45], v[68:69] neg_lo:[1,0,0] neg_hi:[1,0,0]
	v_pk_fma_f32 v[70:71], v[206:207], v[46:47], v[70:71] neg_lo:[1,0,0] neg_hi:[1,0,0]
	ds_read_b128 v[200:203], v1 offset:12384
	ds_read_b128 v[204:207], v1 offset:12400
	ds_read_b128 v[208:211], v1 offset:12416
	v_add_f32_e32 v68, v68, v69
	v_add_f32_e32 v70, v70, v71
	v_add_f32_e32 v48, v68, v70
	v_mul_f32_e32 v72, v79, v48
	v_cvt_pk_bf16_f32 v72, v72, v72
	global_store_short v78, v72, s[38:39]
	v_add_u32_e32 v78, 0xc00, v78
	v_mov_b32_e32 v68, v49
	v_mov_b32_e32 v69, 0
	v_mov_b32_e32 v70, 0
	v_mov_b32_e32 v71, 0
	s_waitcnt lgkmcnt(11)
	v_pk_fma_f32 v[68:69], v[164:165], v[4:5], v[68:69] neg_lo:[1,0,0] neg_hi:[1,0,0]
	v_pk_fma_f32 v[70:71], v[166:167], v[6:7], v[70:71] neg_lo:[1,0,0] neg_hi:[1,0,0]
	s_waitcnt lgkmcnt(10)
	v_pk_fma_f32 v[68:69], v[168:169], v[8:9], v[68:69] neg_lo:[1,0,0] neg_hi:[1,0,0]
	v_pk_fma_f32 v[70:71], v[170:171], v[10:11], v[70:71] neg_lo:[1,0,0] neg_hi:[1,0,0]
	ds_read_b128 v[164:167], v1 offset:12512
	s_waitcnt lgkmcnt(10)
	v_pk_fma_f32 v[68:69], v[172:173], v[12:13], v[68:69] neg_lo:[1,0,0] neg_hi:[1,0,0]
	v_pk_fma_f32 v[70:71], v[174:175], v[14:15], v[70:71] neg_lo:[1,0,0] neg_hi:[1,0,0]
	ds_read_b128 v[168:171], v1 offset:12528
	s_waitcnt lgkmcnt(10)
	v_pk_fma_f32 v[68:69], v[176:177], v[16:17], v[68:69] neg_lo:[1,0,0] neg_hi:[1,0,0]
	v_pk_fma_f32 v[70:71], v[178:179], v[18:19], v[70:71] neg_lo:[1,0,0] neg_hi:[1,0,0]
	ds_read_b128 v[172:175], v1 offset:12544
	s_waitcnt lgkmcnt(10)
	v_pk_fma_f32 v[68:69], v[180:181], v[20:21], v[68:69] neg_lo:[1,0,0] neg_hi:[1,0,0]
	v_pk_fma_f32 v[70:71], v[182:183], v[22:23], v[70:71] neg_lo:[1,0,0] neg_hi:[1,0,0]
	ds_read_b128 v[176:179], v1 offset:12560
	s_waitcnt lgkmcnt(10)
	v_pk_fma_f32 v[68:69], v[184:185], v[24:25], v[68:69] neg_lo:[1,0,0] neg_hi:[1,0,0]
	v_pk_fma_f32 v[70:71], v[186:187], v[26:27], v[70:71] neg_lo:[1,0,0] neg_hi:[1,0,0]
	ds_read_b128 v[180:183], v1 offset:12576
	s_waitcnt lgkmcnt(10)
	v_pk_fma_f32 v[68:69], v[188:189], v[28:29], v[68:69] neg_lo:[1,0,0] neg_hi:[1,0,0]
	v_pk_fma_f32 v[70:71], v[190:191], v[30:31], v[70:71] neg_lo:[1,0,0] neg_hi:[1,0,0]
	ds_read_b128 v[184:187], v1 offset:12592
	s_waitcnt lgkmcnt(10)
	v_pk_fma_f32 v[68:69], v[192:193], v[32:33], v[68:69] neg_lo:[1,0,0] neg_hi:[1,0,0]
	v_pk_fma_f32 v[70:71], v[194:195], v[34:35], v[70:71] neg_lo:[1,0,0] neg_hi:[1,0,0]
	ds_read_b128 v[188:191], v1 offset:12608
	s_waitcnt lgkmcnt(10)
	v_pk_fma_f32 v[68:69], v[196:197], v[36:37], v[68:69] neg_lo:[1,0,0] neg_hi:[1,0,0]
	v_pk_fma_f32 v[70:71], v[198:199], v[38:39], v[70:71] neg_lo:[1,0,0] neg_hi:[1,0,0]
	ds_read_b128 v[192:195], v1 offset:12624
	s_waitcnt lgkmcnt(10)
	v_pk_fma_f32 v[68:69], v[200:201], v[40:41], v[68:69] neg_lo:[1,0,0] neg_hi:[1,0,0]
	v_pk_fma_f32 v[70:71], v[202:203], v[42:43], v[70:71] neg_lo:[1,0,0] neg_hi:[1,0,0]
	ds_read_b128 v[196:199], v1 offset:12640
	s_waitcnt lgkmcnt(10)
	v_pk_fma_f32 v[68:69], v[204:205], v[44:45], v[68:69] neg_lo:[1,0,0] neg_hi:[1,0,0]
	v_pk_fma_f32 v[70:71], v[206:207], v[46:47], v[70:71] neg_lo:[1,0,0] neg_hi:[1,0,0]
	ds_read_b128 v[200:203], v1 offset:12656
	s_waitcnt lgkmcnt(10)
	v_fma_f32 v68, -v208, v48, v68
	ds_read_b128 v[204:207], v1 offset:12672
	ds_read_b128 v[208:211], v1 offset:12688
	v_add_f32_e32 v68, v68, v69
	v_add_f32_e32 v70, v70, v71
	v_add_f32_e32 v49, v68, v70
	v_mul_f32_e32 v72, v79, v49
	v_cvt_pk_bf16_f32 v72, v72, v72
	global_store_short v78, v72, s[38:39]
	v_add_u32_e32 v78, 0xc00, v78
	v_mov_b32_e32 v68, v50
	v_mov_b32_e32 v69, 0
	v_mov_b32_e32 v70, 0
	v_mov_b32_e32 v71, 0
	s_waitcnt lgkmcnt(11)
	v_pk_fma_f32 v[68:69], v[164:165], v[4:5], v[68:69] neg_lo:[1,0,0] neg_hi:[1,0,0]
	v_pk_fma_f32 v[70:71], v[166:167], v[6:7], v[70:71] neg_lo:[1,0,0] neg_hi:[1,0,0]
	s_waitcnt lgkmcnt(10)
	v_pk_fma_f32 v[68:69], v[168:169], v[8:9], v[68:69] neg_lo:[1,0,0] neg_hi:[1,0,0]
	v_pk_fma_f32 v[70:71], v[170:171], v[10:11], v[70:71] neg_lo:[1,0,0] neg_hi:[1,0,0]
	ds_read_b128 v[164:167], v1 offset:12784
	s_waitcnt lgkmcnt(10)
	v_pk_fma_f32 v[68:69], v[172:173], v[12:13], v[68:69] neg_lo:[1,0,0] neg_hi:[1,0,0]
	v_pk_fma_f32 v[70:71], v[174:175], v[14:15], v[70:71] neg_lo:[1,0,0] neg_hi:[1,0,0]
	ds_read_b128 v[168:171], v1 offset:12800
	s_waitcnt lgkmcnt(10)
	v_pk_fma_f32 v[68:69], v[176:177], v[16:17], v[68:69] neg_lo:[1,0,0] neg_hi:[1,0,0]
	v_pk_fma_f32 v[70:71], v[178:179], v[18:19], v[70:71] neg_lo:[1,0,0] neg_hi:[1,0,0]
	ds_read_b128 v[172:175], v1 offset:12816
	s_waitcnt lgkmcnt(10)
	v_pk_fma_f32 v[68:69], v[180:181], v[20:21], v[68:69] neg_lo:[1,0,0] neg_hi:[1,0,0]
	v_pk_fma_f32 v[70:71], v[182:183], v[22:23], v[70:71] neg_lo:[1,0,0] neg_hi:[1,0,0]
	ds_read_b128 v[176:179], v1 offset:12832
	s_waitcnt lgkmcnt(10)
	v_pk_fma_f32 v[68:69], v[184:185], v[24:25], v[68:69] neg_lo:[1,0,0] neg_hi:[1,0,0]
	v_pk_fma_f32 v[70:71], v[186:187], v[26:27], v[70:71] neg_lo:[1,0,0] neg_hi:[1,0,0]
	ds_read_b128 v[180:183], v1 offset:12848
	s_waitcnt lgkmcnt(10)
	v_pk_fma_f32 v[68:69], v[188:189], v[28:29], v[68:69] neg_lo:[1,0,0] neg_hi:[1,0,0]
	v_pk_fma_f32 v[70:71], v[190:191], v[30:31], v[70:71] neg_lo:[1,0,0] neg_hi:[1,0,0]
	ds_read_b128 v[184:187], v1 offset:12864
	s_waitcnt lgkmcnt(10)
	v_pk_fma_f32 v[68:69], v[192:193], v[32:33], v[68:69] neg_lo:[1,0,0] neg_hi:[1,0,0]
	v_pk_fma_f32 v[70:71], v[194:195], v[34:35], v[70:71] neg_lo:[1,0,0] neg_hi:[1,0,0]
	ds_read_b128 v[188:191], v1 offset:12880
	s_waitcnt lgkmcnt(10)
	v_pk_fma_f32 v[68:69], v[196:197], v[36:37], v[68:69] neg_lo:[1,0,0] neg_hi:[1,0,0]
	v_pk_fma_f32 v[70:71], v[198:199], v[38:39], v[70:71] neg_lo:[1,0,0] neg_hi:[1,0,0]
	ds_read_b128 v[192:195], v1 offset:12896
	s_waitcnt lgkmcnt(10)
	v_pk_fma_f32 v[68:69], v[200:201], v[40:41], v[68:69] neg_lo:[1,0,0] neg_hi:[1,0,0]
	v_pk_fma_f32 v[70:71], v[202:203], v[42:43], v[70:71] neg_lo:[1,0,0] neg_hi:[1,0,0]
	ds_read_b128 v[196:199], v1 offset:12912
	s_waitcnt lgkmcnt(10)
	v_pk_fma_f32 v[68:69], v[204:205], v[44:45], v[68:69] neg_lo:[1,0,0] neg_hi:[1,0,0]
	v_pk_fma_f32 v[70:71], v[206:207], v[46:47], v[70:71] neg_lo:[1,0,0] neg_hi:[1,0,0]
	ds_read_b128 v[200:203], v1 offset:12928
	s_waitcnt lgkmcnt(10)
	v_pk_fma_f32 v[68:69], v[208:209], v[48:49], v[68:69] neg_lo:[1,0,0] neg_hi:[1,0,0]
	ds_read_b128 v[204:207], v1 offset:12944
	ds_read_b128 v[208:211], v1 offset:12960
	v_add_f32_e32 v68, v68, v69
	v_add_f32_e32 v70, v70, v71
	v_add_f32_e32 v50, v68, v70
	v_mul_f32_e32 v72, v79, v50
	v_cvt_pk_bf16_f32 v72, v72, v72
	global_store_short v78, v72, s[38:39]
	v_add_u32_e32 v78, 0xc00, v78
	v_mov_b32_e32 v68, v51
	v_mov_b32_e32 v69, 0
	v_mov_b32_e32 v70, 0
	v_mov_b32_e32 v71, 0
	s_waitcnt lgkmcnt(11)
	v_pk_fma_f32 v[68:69], v[164:165], v[4:5], v[68:69] neg_lo:[1,0,0] neg_hi:[1,0,0]
	v_pk_fma_f32 v[70:71], v[166:167], v[6:7], v[70:71] neg_lo:[1,0,0] neg_hi:[1,0,0]
	s_waitcnt lgkmcnt(10)
	v_pk_fma_f32 v[68:69], v[168:169], v[8:9], v[68:69] neg_lo:[1,0,0] neg_hi:[1,0,0]
	v_pk_fma_f32 v[70:71], v[170:171], v[10:11], v[70:71] neg_lo:[1,0,0] neg_hi:[1,0,0]
	ds_read_b128 v[164:167], v1 offset:13056
	s_waitcnt lgkmcnt(10)
	v_pk_fma_f32 v[68:69], v[172:173], v[12:13], v[68:69] neg_lo:[1,0,0] neg_hi:[1,0,0]
	v_pk_fma_f32 v[70:71], v[174:175], v[14:15], v[70:71] neg_lo:[1,0,0] neg_hi:[1,0,0]
	ds_read_b128 v[168:171], v1 offset:13072
	s_waitcnt lgkmcnt(10)
	v_pk_fma_f32 v[68:69], v[176:177], v[16:17], v[68:69] neg_lo:[1,0,0] neg_hi:[1,0,0]
	v_pk_fma_f32 v[70:71], v[178:179], v[18:19], v[70:71] neg_lo:[1,0,0] neg_hi:[1,0,0]
	ds_read_b128 v[172:175], v1 offset:13088
	s_waitcnt lgkmcnt(10)
	v_pk_fma_f32 v[68:69], v[180:181], v[20:21], v[68:69] neg_lo:[1,0,0] neg_hi:[1,0,0]
	v_pk_fma_f32 v[70:71], v[182:183], v[22:23], v[70:71] neg_lo:[1,0,0] neg_hi:[1,0,0]
	ds_read_b128 v[176:179], v1 offset:13104
	s_waitcnt lgkmcnt(10)
	v_pk_fma_f32 v[68:69], v[184:185], v[24:25], v[68:69] neg_lo:[1,0,0] neg_hi:[1,0,0]
	v_pk_fma_f32 v[70:71], v[186:187], v[26:27], v[70:71] neg_lo:[1,0,0] neg_hi:[1,0,0]
	ds_read_b128 v[180:183], v1 offset:13120
	s_waitcnt lgkmcnt(10)
	v_pk_fma_f32 v[68:69], v[188:189], v[28:29], v[68:69] neg_lo:[1,0,0] neg_hi:[1,0,0]
	v_pk_fma_f32 v[70:71], v[190:191], v[30:31], v[70:71] neg_lo:[1,0,0] neg_hi:[1,0,0]
	ds_read_b128 v[184:187], v1 offset:13136
	s_waitcnt lgkmcnt(10)
	v_pk_fma_f32 v[68:69], v[192:193], v[32:33], v[68:69] neg_lo:[1,0,0] neg_hi:[1,0,0]
	v_pk_fma_f32 v[70:71], v[194:195], v[34:35], v[70:71] neg_lo:[1,0,0] neg_hi:[1,0,0]
	ds_read_b128 v[188:191], v1 offset:13152
	s_waitcnt lgkmcnt(10)
	v_pk_fma_f32 v[68:69], v[196:197], v[36:37], v[68:69] neg_lo:[1,0,0] neg_hi:[1,0,0]
	v_pk_fma_f32 v[70:71], v[198:199], v[38:39], v[70:71] neg_lo:[1,0,0] neg_hi:[1,0,0]
	ds_read_b128 v[192:195], v1 offset:13168
	s_waitcnt lgkmcnt(10)
	v_pk_fma_f32 v[68:69], v[200:201], v[40:41], v[68:69] neg_lo:[1,0,0] neg_hi:[1,0,0]
	v_pk_fma_f32 v[70:71], v[202:203], v[42:43], v[70:71] neg_lo:[1,0,0] neg_hi:[1,0,0]
	ds_read_b128 v[196:199], v1 offset:13184
	s_waitcnt lgkmcnt(10)
	v_pk_fma_f32 v[68:69], v[204:205], v[44:45], v[68:69] neg_lo:[1,0,0] neg_hi:[1,0,0]
	v_pk_fma_f32 v[70:71], v[206:207], v[46:47], v[70:71] neg_lo:[1,0,0] neg_hi:[1,0,0]
	ds_read_b128 v[200:203], v1 offset:13200
	s_waitcnt lgkmcnt(10)
	v_pk_fma_f32 v[68:69], v[208:209], v[48:49], v[68:69] neg_lo:[1,0,0] neg_hi:[1,0,0]
	v_fma_f32 v70, -v210, v50, v70
	ds_read_b128 v[204:207], v1 offset:13216
	ds_read_b128 v[208:211], v1 offset:13232
	v_add_f32_e32 v68, v68, v69
	v_add_f32_e32 v70, v70, v71
	v_add_f32_e32 v51, v68, v70
	v_mul_f32_e32 v72, v79, v51
	v_cvt_pk_bf16_f32 v72, v72, v72
	global_store_short v78, v72, s[38:39]
	v_add_u32_e32 v78, 0xc00, v78
	v_mov_b32_e32 v68, v52
	v_mov_b32_e32 v69, 0
	v_mov_b32_e32 v70, 0
	v_mov_b32_e32 v71, 0
	s_waitcnt lgkmcnt(11)
	v_pk_fma_f32 v[68:69], v[164:165], v[4:5], v[68:69] neg_lo:[1,0,0] neg_hi:[1,0,0]
	v_pk_fma_f32 v[70:71], v[166:167], v[6:7], v[70:71] neg_lo:[1,0,0] neg_hi:[1,0,0]
	s_waitcnt lgkmcnt(10)
	v_pk_fma_f32 v[68:69], v[168:169], v[8:9], v[68:69] neg_lo:[1,0,0] neg_hi:[1,0,0]
	v_pk_fma_f32 v[70:71], v[170:171], v[10:11], v[70:71] neg_lo:[1,0,0] neg_hi:[1,0,0]
	ds_read_b128 v[164:167], v1 offset:13328
	s_waitcnt lgkmcnt(10)
	v_pk_fma_f32 v[68:69], v[172:173], v[12:13], v[68:69] neg_lo:[1,0,0] neg_hi:[1,0,0]
	v_pk_fma_f32 v[70:71], v[174:175], v[14:15], v[70:71] neg_lo:[1,0,0] neg_hi:[1,0,0]
	ds_read_b128 v[168:171], v1 offset:13344
	s_waitcnt lgkmcnt(10)
	v_pk_fma_f32 v[68:69], v[176:177], v[16:17], v[68:69] neg_lo:[1,0,0] neg_hi:[1,0,0]
	v_pk_fma_f32 v[70:71], v[178:179], v[18:19], v[70:71] neg_lo:[1,0,0] neg_hi:[1,0,0]
	ds_read_b128 v[172:175], v1 offset:13360
	s_waitcnt lgkmcnt(10)
	v_pk_fma_f32 v[68:69], v[180:181], v[20:21], v[68:69] neg_lo:[1,0,0] neg_hi:[1,0,0]
	v_pk_fma_f32 v[70:71], v[182:183], v[22:23], v[70:71] neg_lo:[1,0,0] neg_hi:[1,0,0]
	ds_read_b128 v[176:179], v1 offset:13376
	s_waitcnt lgkmcnt(10)
	v_pk_fma_f32 v[68:69], v[184:185], v[24:25], v[68:69] neg_lo:[1,0,0] neg_hi:[1,0,0]
	v_pk_fma_f32 v[70:71], v[186:187], v[26:27], v[70:71] neg_lo:[1,0,0] neg_hi:[1,0,0]
	ds_read_b128 v[180:183], v1 offset:13392
	s_waitcnt lgkmcnt(10)
	v_pk_fma_f32 v[68:69], v[188:189], v[28:29], v[68:69] neg_lo:[1,0,0] neg_hi:[1,0,0]
	v_pk_fma_f32 v[70:71], v[190:191], v[30:31], v[70:71] neg_lo:[1,0,0] neg_hi:[1,0,0]
	ds_read_b128 v[184:187], v1 offset:13408
	s_waitcnt lgkmcnt(10)
	v_pk_fma_f32 v[68:69], v[192:193], v[32:33], v[68:69] neg_lo:[1,0,0] neg_hi:[1,0,0]
	v_pk_fma_f32 v[70:71], v[194:195], v[34:35], v[70:71] neg_lo:[1,0,0] neg_hi:[1,0,0]
	ds_read_b128 v[188:191], v1 offset:13424
	s_waitcnt lgkmcnt(10)
	v_pk_fma_f32 v[68:69], v[196:197], v[36:37], v[68:69] neg_lo:[1,0,0] neg_hi:[1,0,0]
	v_pk_fma_f32 v[70:71], v[198:199], v[38:39], v[70:71] neg_lo:[1,0,0] neg_hi:[1,0,0]
	ds_read_b128 v[192:195], v1 offset:13440
	s_waitcnt lgkmcnt(10)
	v_pk_fma_f32 v[68:69], v[200:201], v[40:41], v[68:69] neg_lo:[1,0,0] neg_hi:[1,0,0]
	v_pk_fma_f32 v[70:71], v[202:203], v[42:43], v[70:71] neg_lo:[1,0,0] neg_hi:[1,0,0]
	ds_read_b128 v[196:199], v1 offset:13456
	s_waitcnt lgkmcnt(10)
	v_pk_fma_f32 v[68:69], v[204:205], v[44:45], v[68:69] neg_lo:[1,0,0] neg_hi:[1,0,0]
	v_pk_fma_f32 v[70:71], v[206:207], v[46:47], v[70:71] neg_lo:[1,0,0] neg_hi:[1,0,0]
	ds_read_b128 v[200:203], v1 offset:13472
	s_waitcnt lgkmcnt(10)
	v_pk_fma_f32 v[68:69], v[208:209], v[48:49], v[68:69] neg_lo:[1,0,0] neg_hi:[1,0,0]
	v_pk_fma_f32 v[70:71], v[210:211], v[50:51], v[70:71] neg_lo:[1,0,0] neg_hi:[1,0,0]
	ds_read_b128 v[204:207], v1 offset:13488
	ds_read_b128 v[208:211], v1 offset:13504
	ds_read_b128 v[212:215], v1 offset:13520
	v_add_f32_e32 v68, v68, v69
	v_add_f32_e32 v70, v70, v71
	v_add_f32_e32 v52, v68, v70
	v_mul_f32_e32 v72, v79, v52
	v_cvt_pk_bf16_f32 v72, v72, v72
	global_store_short v78, v72, s[38:39]
	v_add_u32_e32 v78, 0xc00, v78
	v_mov_b32_e32 v68, v53
	v_mov_b32_e32 v69, 0
	v_mov_b32_e32 v70, 0
	v_mov_b32_e32 v71, 0
	s_waitcnt lgkmcnt(12)
	v_pk_fma_f32 v[68:69], v[164:165], v[4:5], v[68:69] neg_lo:[1,0,0] neg_hi:[1,0,0]
	v_pk_fma_f32 v[70:71], v[166:167], v[6:7], v[70:71] neg_lo:[1,0,0] neg_hi:[1,0,0]
	s_waitcnt lgkmcnt(11)
	v_pk_fma_f32 v[68:69], v[168:169], v[8:9], v[68:69] neg_lo:[1,0,0] neg_hi:[1,0,0]
	v_pk_fma_f32 v[70:71], v[170:171], v[10:11], v[70:71] neg_lo:[1,0,0] neg_hi:[1,0,0]
	ds_read_b128 v[164:167], v1 offset:13600
	s_waitcnt lgkmcnt(11)
	v_pk_fma_f32 v[68:69], v[172:173], v[12:13], v[68:69] neg_lo:[1,0,0] neg_hi:[1,0,0]
	v_pk_fma_f32 v[70:71], v[174:175], v[14:15], v[70:71] neg_lo:[1,0,0] neg_hi:[1,0,0]
	ds_read_b128 v[168:171], v1 offset:13616
	s_waitcnt lgkmcnt(11)
	v_pk_fma_f32 v[68:69], v[176:177], v[16:17], v[68:69] neg_lo:[1,0,0] neg_hi:[1,0,0]
	v_pk_fma_f32 v[70:71], v[178:179], v[18:19], v[70:71] neg_lo:[1,0,0] neg_hi:[1,0,0]
	ds_read_b128 v[172:175], v1 offset:13632
	s_waitcnt lgkmcnt(11)
	v_pk_fma_f32 v[68:69], v[180:181], v[20:21], v[68:69] neg_lo:[1,0,0] neg_hi:[1,0,0]
	v_pk_fma_f32 v[70:71], v[182:183], v[22:23], v[70:71] neg_lo:[1,0,0] neg_hi:[1,0,0]
	ds_read_b128 v[176:179], v1 offset:13648
	s_waitcnt lgkmcnt(11)
	v_pk_fma_f32 v[68:69], v[184:185], v[24:25], v[68:69] neg_lo:[1,0,0] neg_hi:[1,0,0]
	v_pk_fma_f32 v[70:71], v[186:187], v[26:27], v[70:71] neg_lo:[1,0,0] neg_hi:[1,0,0]
	ds_read_b128 v[180:183], v1 offset:13664
	s_waitcnt lgkmcnt(11)
	v_pk_fma_f32 v[68:69], v[188:189], v[28:29], v[68:69] neg_lo:[1,0,0] neg_hi:[1,0,0]
	v_pk_fma_f32 v[70:71], v[190:191], v[30:31], v[70:71] neg_lo:[1,0,0] neg_hi:[1,0,0]
	ds_read_b128 v[184:187], v1 offset:13680
	s_waitcnt lgkmcnt(11)
	v_pk_fma_f32 v[68:69], v[192:193], v[32:33], v[68:69] neg_lo:[1,0,0] neg_hi:[1,0,0]
	v_pk_fma_f32 v[70:71], v[194:195], v[34:35], v[70:71] neg_lo:[1,0,0] neg_hi:[1,0,0]
	ds_read_b128 v[188:191], v1 offset:13696
	s_waitcnt lgkmcnt(11)
	v_pk_fma_f32 v[68:69], v[196:197], v[36:37], v[68:69] neg_lo:[1,0,0] neg_hi:[1,0,0]
	v_pk_fma_f32 v[70:71], v[198:199], v[38:39], v[70:71] neg_lo:[1,0,0] neg_hi:[1,0,0]
	ds_read_b128 v[192:195], v1 offset:13712
	s_waitcnt lgkmcnt(11)
	v_pk_fma_f32 v[68:69], v[200:201], v[40:41], v[68:69] neg_lo:[1,0,0] neg_hi:[1,0,0]
	v_pk_fma_f32 v[70:71], v[202:203], v[42:43], v[70:71] neg_lo:[1,0,0] neg_hi:[1,0,0]
	ds_read_b128 v[196:199], v1 offset:13728
	s_waitcnt lgkmcnt(11)
	v_pk_fma_f32 v[68:69], v[204:205], v[44:45], v[68:69] neg_lo:[1,0,0] neg_hi:[1,0,0]
	v_pk_fma_f32 v[70:71], v[206:207], v[46:47], v[70:71] neg_lo:[1,0,0] neg_hi:[1,0,0]
	ds_read_b128 v[200:203], v1 offset:13744
	s_waitcnt lgkmcnt(11)
	v_pk_fma_f32 v[68:69], v[208:209], v[48:49], v[68:69] neg_lo:[1,0,0] neg_hi:[1,0,0]
	v_pk_fma_f32 v[70:71], v[210:211], v[50:51], v[70:71] neg_lo:[1,0,0] neg_hi:[1,0,0]
	ds_read_b128 v[204:207], v1 offset:13760
	s_waitcnt lgkmcnt(11)
	v_fma_f32 v68, -v212, v52, v68
	ds_read_b128 v[208:211], v1 offset:13776
	ds_read_b128 v[212:215], v1 offset:13792
	v_add_f32_e32 v68, v68, v69
	v_add_f32_e32 v70, v70, v71
	v_add_f32_e32 v53, v68, v70
	v_mul_f32_e32 v72, v79, v53
	v_cvt_pk_bf16_f32 v72, v72, v72
	global_store_short v78, v72, s[38:39]
	v_add_u32_e32 v78, 0xc00, v78
	v_mov_b32_e32 v68, v54
	v_mov_b32_e32 v69, 0
	v_mov_b32_e32 v70, 0
	v_mov_b32_e32 v71, 0
	s_waitcnt lgkmcnt(12)
	v_pk_fma_f32 v[68:69], v[164:165], v[4:5], v[68:69] neg_lo:[1,0,0] neg_hi:[1,0,0]
	v_pk_fma_f32 v[70:71], v[166:167], v[6:7], v[70:71] neg_lo:[1,0,0] neg_hi:[1,0,0]
	s_waitcnt lgkmcnt(11)
	v_pk_fma_f32 v[68:69], v[168:169], v[8:9], v[68:69] neg_lo:[1,0,0] neg_hi:[1,0,0]
	v_pk_fma_f32 v[70:71], v[170:171], v[10:11], v[70:71] neg_lo:[1,0,0] neg_hi:[1,0,0]
	ds_read_b128 v[164:167], v1 offset:13872
	s_waitcnt lgkmcnt(11)
	v_pk_fma_f32 v[68:69], v[172:173], v[12:13], v[68:69] neg_lo:[1,0,0] neg_hi:[1,0,0]
	v_pk_fma_f32 v[70:71], v[174:175], v[14:15], v[70:71] neg_lo:[1,0,0] neg_hi:[1,0,0]
	ds_read_b128 v[168:171], v1 offset:13888
	s_waitcnt lgkmcnt(11)
	v_pk_fma_f32 v[68:69], v[176:177], v[16:17], v[68:69] neg_lo:[1,0,0] neg_hi:[1,0,0]
	v_pk_fma_f32 v[70:71], v[178:179], v[18:19], v[70:71] neg_lo:[1,0,0] neg_hi:[1,0,0]
	ds_read_b128 v[172:175], v1 offset:13904
	s_waitcnt lgkmcnt(11)
	v_pk_fma_f32 v[68:69], v[180:181], v[20:21], v[68:69] neg_lo:[1,0,0] neg_hi:[1,0,0]
	v_pk_fma_f32 v[70:71], v[182:183], v[22:23], v[70:71] neg_lo:[1,0,0] neg_hi:[1,0,0]
	ds_read_b128 v[176:179], v1 offset:13920
	s_waitcnt lgkmcnt(11)
	v_pk_fma_f32 v[68:69], v[184:185], v[24:25], v[68:69] neg_lo:[1,0,0] neg_hi:[1,0,0]
	v_pk_fma_f32 v[70:71], v[186:187], v[26:27], v[70:71] neg_lo:[1,0,0] neg_hi:[1,0,0]
	ds_read_b128 v[180:183], v1 offset:13936
	s_waitcnt lgkmcnt(11)
	v_pk_fma_f32 v[68:69], v[188:189], v[28:29], v[68:69] neg_lo:[1,0,0] neg_hi:[1,0,0]
	v_pk_fma_f32 v[70:71], v[190:191], v[30:31], v[70:71] neg_lo:[1,0,0] neg_hi:[1,0,0]
	ds_read_b128 v[184:187], v1 offset:13952
	s_waitcnt lgkmcnt(11)
	v_pk_fma_f32 v[68:69], v[192:193], v[32:33], v[68:69] neg_lo:[1,0,0] neg_hi:[1,0,0]
	v_pk_fma_f32 v[70:71], v[194:195], v[34:35], v[70:71] neg_lo:[1,0,0] neg_hi:[1,0,0]
	ds_read_b128 v[188:191], v1 offset:13968
	s_waitcnt lgkmcnt(11)
	v_pk_fma_f32 v[68:69], v[196:197], v[36:37], v[68:69] neg_lo:[1,0,0] neg_hi:[1,0,0]
	v_pk_fma_f32 v[70:71], v[198:199], v[38:39], v[70:71] neg_lo:[1,0,0] neg_hi:[1,0,0]
	ds_read_b128 v[192:195], v1 offset:13984
	s_waitcnt lgkmcnt(11)
	v_pk_fma_f32 v[68:69], v[200:201], v[40:41], v[68:69] neg_lo:[1,0,0] neg_hi:[1,0,0]
	v_pk_fma_f32 v[70:71], v[202:203], v[42:43], v[70:71] neg_lo:[1,0,0] neg_hi:[1,0,0]
	ds_read_b128 v[196:199], v1 offset:14000
	s_waitcnt lgkmcnt(11)
	v_pk_fma_f32 v[68:69], v[204:205], v[44:45], v[68:69] neg_lo:[1,0,0] neg_hi:[1,0,0]
	v_pk_fma_f32 v[70:71], v[206:207], v[46:47], v[70:71] neg_lo:[1,0,0] neg_hi:[1,0,0]
	ds_read_b128 v[200:203], v1 offset:14016
	s_waitcnt lgkmcnt(11)
	v_pk_fma_f32 v[68:69], v[208:209], v[48:49], v[68:69] neg_lo:[1,0,0] neg_hi:[1,0,0]
	v_pk_fma_f32 v[70:71], v[210:211], v[50:51], v[70:71] neg_lo:[1,0,0] neg_hi:[1,0,0]
	ds_read_b128 v[204:207], v1 offset:14032
	s_waitcnt lgkmcnt(11)
	v_pk_fma_f32 v[68:69], v[212:213], v[52:53], v[68:69] neg_lo:[1,0,0] neg_hi:[1,0,0]
	ds_read_b128 v[208:211], v1 offset:14048
	ds_read_b128 v[212:215], v1 offset:14064
	v_add_f32_e32 v68, v68, v69
	v_add_f32_e32 v70, v70, v71
	v_add_f32_e32 v54, v68, v70
	v_mul_f32_e32 v72, v79, v54
	v_cvt_pk_bf16_f32 v72, v72, v72
	global_store_short v78, v72, s[38:39]
	v_add_u32_e32 v78, 0xc00, v78
	v_mov_b32_e32 v68, v55
	v_mov_b32_e32 v69, 0
	v_mov_b32_e32 v70, 0
	v_mov_b32_e32 v71, 0
	s_waitcnt lgkmcnt(12)
	v_pk_fma_f32 v[68:69], v[164:165], v[4:5], v[68:69] neg_lo:[1,0,0] neg_hi:[1,0,0]
	v_pk_fma_f32 v[70:71], v[166:167], v[6:7], v[70:71] neg_lo:[1,0,0] neg_hi:[1,0,0]
	s_waitcnt lgkmcnt(11)
	v_pk_fma_f32 v[68:69], v[168:169], v[8:9], v[68:69] neg_lo:[1,0,0] neg_hi:[1,0,0]
	v_pk_fma_f32 v[70:71], v[170:171], v[10:11], v[70:71] neg_lo:[1,0,0] neg_hi:[1,0,0]
	ds_read_b128 v[164:167], v1 offset:14144
	s_waitcnt lgkmcnt(11)
	v_pk_fma_f32 v[68:69], v[172:173], v[12:13], v[68:69] neg_lo:[1,0,0] neg_hi:[1,0,0]
	v_pk_fma_f32 v[70:71], v[174:175], v[14:15], v[70:71] neg_lo:[1,0,0] neg_hi:[1,0,0]
	ds_read_b128 v[168:171], v1 offset:14160
	s_waitcnt lgkmcnt(11)
	v_pk_fma_f32 v[68:69], v[176:177], v[16:17], v[68:69] neg_lo:[1,0,0] neg_hi:[1,0,0]
	v_pk_fma_f32 v[70:71], v[178:179], v[18:19], v[70:71] neg_lo:[1,0,0] neg_hi:[1,0,0]
	ds_read_b128 v[172:175], v1 offset:14176
	s_waitcnt lgkmcnt(11)
	v_pk_fma_f32 v[68:69], v[180:181], v[20:21], v[68:69] neg_lo:[1,0,0] neg_hi:[1,0,0]
	v_pk_fma_f32 v[70:71], v[182:183], v[22:23], v[70:71] neg_lo:[1,0,0] neg_hi:[1,0,0]
	ds_read_b128 v[176:179], v1 offset:14192
	s_waitcnt lgkmcnt(11)
	v_pk_fma_f32 v[68:69], v[184:185], v[24:25], v[68:69] neg_lo:[1,0,0] neg_hi:[1,0,0]
	v_pk_fma_f32 v[70:71], v[186:187], v[26:27], v[70:71] neg_lo:[1,0,0] neg_hi:[1,0,0]
	ds_read_b128 v[180:183], v1 offset:14208
	s_waitcnt lgkmcnt(11)
	v_pk_fma_f32 v[68:69], v[188:189], v[28:29], v[68:69] neg_lo:[1,0,0] neg_hi:[1,0,0]
	v_pk_fma_f32 v[70:71], v[190:191], v[30:31], v[70:71] neg_lo:[1,0,0] neg_hi:[1,0,0]
	ds_read_b128 v[184:187], v1 offset:14224
	s_waitcnt lgkmcnt(11)
	v_pk_fma_f32 v[68:69], v[192:193], v[32:33], v[68:69] neg_lo:[1,0,0] neg_hi:[1,0,0]
	v_pk_fma_f32 v[70:71], v[194:195], v[34:35], v[70:71] neg_lo:[1,0,0] neg_hi:[1,0,0]
	ds_read_b128 v[188:191], v1 offset:14240
	s_waitcnt lgkmcnt(11)
	v_pk_fma_f32 v[68:69], v[196:197], v[36:37], v[68:69] neg_lo:[1,0,0] neg_hi:[1,0,0]
	v_pk_fma_f32 v[70:71], v[198:199], v[38:39], v[70:71] neg_lo:[1,0,0] neg_hi:[1,0,0]
	ds_read_b128 v[192:195], v1 offset:14256
	s_waitcnt lgkmcnt(11)
	v_pk_fma_f32 v[68:69], v[200:201], v[40:41], v[68:69] neg_lo:[1,0,0] neg_hi:[1,0,0]
	v_pk_fma_f32 v[70:71], v[202:203], v[42:43], v[70:71] neg_lo:[1,0,0] neg_hi:[1,0,0]
	ds_read_b128 v[196:199], v1 offset:14272
	s_waitcnt lgkmcnt(11)
	v_pk_fma_f32 v[68:69], v[204:205], v[44:45], v[68:69] neg_lo:[1,0,0] neg_hi:[1,0,0]
	v_pk_fma_f32 v[70:71], v[206:207], v[46:47], v[70:71] neg_lo:[1,0,0] neg_hi:[1,0,0]
	ds_read_b128 v[200:203], v1 offset:14288
	s_waitcnt lgkmcnt(11)
	v_pk_fma_f32 v[68:69], v[208:209], v[48:49], v[68:69] neg_lo:[1,0,0] neg_hi:[1,0,0]
	v_pk_fma_f32 v[70:71], v[210:211], v[50:51], v[70:71] neg_lo:[1,0,0] neg_hi:[1,0,0]
	ds_read_b128 v[204:207], v1 offset:14304
	s_waitcnt lgkmcnt(11)
	v_pk_fma_f32 v[68:69], v[212:213], v[52:53], v[68:69] neg_lo:[1,0,0] neg_hi:[1,0,0]
	v_fma_f32 v70, -v214, v54, v70
	ds_read_b128 v[208:211], v1 offset:14320
	ds_read_b128 v[212:215], v1 offset:14336
	v_add_f32_e32 v68, v68, v69
	v_add_f32_e32 v70, v70, v71
	v_add_f32_e32 v55, v68, v70
	v_mul_f32_e32 v72, v79, v55
	v_cvt_pk_bf16_f32 v72, v72, v72
	global_store_short v78, v72, s[38:39]
	v_add_u32_e32 v78, 0xc00, v78
	v_mov_b32_e32 v68, v56
	v_mov_b32_e32 v69, 0
	v_mov_b32_e32 v70, 0
	v_mov_b32_e32 v71, 0
	s_waitcnt lgkmcnt(12)
	v_pk_fma_f32 v[68:69], v[164:165], v[4:5], v[68:69] neg_lo:[1,0,0] neg_hi:[1,0,0]
	v_pk_fma_f32 v[70:71], v[166:167], v[6:7], v[70:71] neg_lo:[1,0,0] neg_hi:[1,0,0]
	s_waitcnt lgkmcnt(11)
	v_pk_fma_f32 v[68:69], v[168:169], v[8:9], v[68:69] neg_lo:[1,0,0] neg_hi:[1,0,0]
	v_pk_fma_f32 v[70:71], v[170:171], v[10:11], v[70:71] neg_lo:[1,0,0] neg_hi:[1,0,0]
	ds_read_b128 v[164:167], v1 offset:14416
	s_waitcnt lgkmcnt(11)
	v_pk_fma_f32 v[68:69], v[172:173], v[12:13], v[68:69] neg_lo:[1,0,0] neg_hi:[1,0,0]
	v_pk_fma_f32 v[70:71], v[174:175], v[14:15], v[70:71] neg_lo:[1,0,0] neg_hi:[1,0,0]
	ds_read_b128 v[168:171], v1 offset:14432
	s_waitcnt lgkmcnt(11)
	v_pk_fma_f32 v[68:69], v[176:177], v[16:17], v[68:69] neg_lo:[1,0,0] neg_hi:[1,0,0]
	v_pk_fma_f32 v[70:71], v[178:179], v[18:19], v[70:71] neg_lo:[1,0,0] neg_hi:[1,0,0]
	ds_read_b128 v[172:175], v1 offset:14448
	s_waitcnt lgkmcnt(11)
	v_pk_fma_f32 v[68:69], v[180:181], v[20:21], v[68:69] neg_lo:[1,0,0] neg_hi:[1,0,0]
	v_pk_fma_f32 v[70:71], v[182:183], v[22:23], v[70:71] neg_lo:[1,0,0] neg_hi:[1,0,0]
	ds_read_b128 v[176:179], v1 offset:14464
	s_waitcnt lgkmcnt(11)
	v_pk_fma_f32 v[68:69], v[184:185], v[24:25], v[68:69] neg_lo:[1,0,0] neg_hi:[1,0,0]
	v_pk_fma_f32 v[70:71], v[186:187], v[26:27], v[70:71] neg_lo:[1,0,0] neg_hi:[1,0,0]
	ds_read_b128 v[180:183], v1 offset:14480
	s_waitcnt lgkmcnt(11)
	v_pk_fma_f32 v[68:69], v[188:189], v[28:29], v[68:69] neg_lo:[1,0,0] neg_hi:[1,0,0]
	v_pk_fma_f32 v[70:71], v[190:191], v[30:31], v[70:71] neg_lo:[1,0,0] neg_hi:[1,0,0]
	ds_read_b128 v[184:187], v1 offset:14496
	s_waitcnt lgkmcnt(11)
	v_pk_fma_f32 v[68:69], v[192:193], v[32:33], v[68:69] neg_lo:[1,0,0] neg_hi:[1,0,0]
	v_pk_fma_f32 v[70:71], v[194:195], v[34:35], v[70:71] neg_lo:[1,0,0] neg_hi:[1,0,0]
	ds_read_b128 v[188:191], v1 offset:14512
	s_waitcnt lgkmcnt(11)
	v_pk_fma_f32 v[68:69], v[196:197], v[36:37], v[68:69] neg_lo:[1,0,0] neg_hi:[1,0,0]
	v_pk_fma_f32 v[70:71], v[198:199], v[38:39], v[70:71] neg_lo:[1,0,0] neg_hi:[1,0,0]
	ds_read_b128 v[192:195], v1 offset:14528
	s_waitcnt lgkmcnt(11)
	v_pk_fma_f32 v[68:69], v[200:201], v[40:41], v[68:69] neg_lo:[1,0,0] neg_hi:[1,0,0]
	v_pk_fma_f32 v[70:71], v[202:203], v[42:43], v[70:71] neg_lo:[1,0,0] neg_hi:[1,0,0]
	ds_read_b128 v[196:199], v1 offset:14544
	s_waitcnt lgkmcnt(11)
	v_pk_fma_f32 v[68:69], v[204:205], v[44:45], v[68:69] neg_lo:[1,0,0] neg_hi:[1,0,0]
	v_pk_fma_f32 v[70:71], v[206:207], v[46:47], v[70:71] neg_lo:[1,0,0] neg_hi:[1,0,0]
	ds_read_b128 v[200:203], v1 offset:14560
	s_waitcnt lgkmcnt(11)
	v_pk_fma_f32 v[68:69], v[208:209], v[48:49], v[68:69] neg_lo:[1,0,0] neg_hi:[1,0,0]
	v_pk_fma_f32 v[70:71], v[210:211], v[50:51], v[70:71] neg_lo:[1,0,0] neg_hi:[1,0,0]
	ds_read_b128 v[204:207], v1 offset:14576
	s_waitcnt lgkmcnt(11)
	v_pk_fma_f32 v[68:69], v[212:213], v[52:53], v[68:69] neg_lo:[1,0,0] neg_hi:[1,0,0]
	v_pk_fma_f32 v[70:71], v[214:215], v[54:55], v[70:71] neg_lo:[1,0,0] neg_hi:[1,0,0]
	ds_read_b128 v[208:211], v1 offset:14592
	ds_read_b128 v[212:215], v1 offset:14608
	ds_read_b128 v[216:219], v1 offset:14624
	v_add_f32_e32 v68, v68, v69
	v_add_f32_e32 v70, v70, v71
	v_add_f32_e32 v56, v68, v70
	v_mul_f32_e32 v72, v79, v56
	v_cvt_pk_bf16_f32 v72, v72, v72
	global_store_short v78, v72, s[38:39]
	v_add_u32_e32 v78, 0xc00, v78
	v_mov_b32_e32 v68, v57
	v_mov_b32_e32 v69, 0
	v_mov_b32_e32 v70, 0
	v_mov_b32_e32 v71, 0
	s_waitcnt lgkmcnt(13)
	v_pk_fma_f32 v[68:69], v[164:165], v[4:5], v[68:69] neg_lo:[1,0,0] neg_hi:[1,0,0]
	v_pk_fma_f32 v[70:71], v[166:167], v[6:7], v[70:71] neg_lo:[1,0,0] neg_hi:[1,0,0]
	s_waitcnt lgkmcnt(12)
	v_pk_fma_f32 v[68:69], v[168:169], v[8:9], v[68:69] neg_lo:[1,0,0] neg_hi:[1,0,0]
	v_pk_fma_f32 v[70:71], v[170:171], v[10:11], v[70:71] neg_lo:[1,0,0] neg_hi:[1,0,0]
	ds_read_b128 v[164:167], v1 offset:14688
	s_waitcnt lgkmcnt(12)
	v_pk_fma_f32 v[68:69], v[172:173], v[12:13], v[68:69] neg_lo:[1,0,0] neg_hi:[1,0,0]
	v_pk_fma_f32 v[70:71], v[174:175], v[14:15], v[70:71] neg_lo:[1,0,0] neg_hi:[1,0,0]
	ds_read_b128 v[168:171], v1 offset:14704
	s_waitcnt lgkmcnt(12)
	v_pk_fma_f32 v[68:69], v[176:177], v[16:17], v[68:69] neg_lo:[1,0,0] neg_hi:[1,0,0]
	v_pk_fma_f32 v[70:71], v[178:179], v[18:19], v[70:71] neg_lo:[1,0,0] neg_hi:[1,0,0]
	ds_read_b128 v[172:175], v1 offset:14720
	s_waitcnt lgkmcnt(12)
	v_pk_fma_f32 v[68:69], v[180:181], v[20:21], v[68:69] neg_lo:[1,0,0] neg_hi:[1,0,0]
	v_pk_fma_f32 v[70:71], v[182:183], v[22:23], v[70:71] neg_lo:[1,0,0] neg_hi:[1,0,0]
	ds_read_b128 v[176:179], v1 offset:14736
	s_waitcnt lgkmcnt(12)
	v_pk_fma_f32 v[68:69], v[184:185], v[24:25], v[68:69] neg_lo:[1,0,0] neg_hi:[1,0,0]
	v_pk_fma_f32 v[70:71], v[186:187], v[26:27], v[70:71] neg_lo:[1,0,0] neg_hi:[1,0,0]
	ds_read_b128 v[180:183], v1 offset:14752
	s_waitcnt lgkmcnt(12)
	v_pk_fma_f32 v[68:69], v[188:189], v[28:29], v[68:69] neg_lo:[1,0,0] neg_hi:[1,0,0]
	v_pk_fma_f32 v[70:71], v[190:191], v[30:31], v[70:71] neg_lo:[1,0,0] neg_hi:[1,0,0]
	ds_read_b128 v[184:187], v1 offset:14768
	s_waitcnt lgkmcnt(12)
	v_pk_fma_f32 v[68:69], v[192:193], v[32:33], v[68:69] neg_lo:[1,0,0] neg_hi:[1,0,0]
	v_pk_fma_f32 v[70:71], v[194:195], v[34:35], v[70:71] neg_lo:[1,0,0] neg_hi:[1,0,0]
	ds_read_b128 v[188:191], v1 offset:14784
	s_waitcnt lgkmcnt(12)
	v_pk_fma_f32 v[68:69], v[196:197], v[36:37], v[68:69] neg_lo:[1,0,0] neg_hi:[1,0,0]
	v_pk_fma_f32 v[70:71], v[198:199], v[38:39], v[70:71] neg_lo:[1,0,0] neg_hi:[1,0,0]
	ds_read_b128 v[192:195], v1 offset:14800
	s_waitcnt lgkmcnt(12)
	v_pk_fma_f32 v[68:69], v[200:201], v[40:41], v[68:69] neg_lo:[1,0,0] neg_hi:[1,0,0]
	v_pk_fma_f32 v[70:71], v[202:203], v[42:43], v[70:71] neg_lo:[1,0,0] neg_hi:[1,0,0]
	ds_read_b128 v[196:199], v1 offset:14816
	s_waitcnt lgkmcnt(12)
	v_pk_fma_f32 v[68:69], v[204:205], v[44:45], v[68:69] neg_lo:[1,0,0] neg_hi:[1,0,0]
	v_pk_fma_f32 v[70:71], v[206:207], v[46:47], v[70:71] neg_lo:[1,0,0] neg_hi:[1,0,0]
	ds_read_b128 v[200:203], v1 offset:14832
	s_waitcnt lgkmcnt(12)
	v_pk_fma_f32 v[68:69], v[208:209], v[48:49], v[68:69] neg_lo:[1,0,0] neg_hi:[1,0,0]
	v_pk_fma_f32 v[70:71], v[210:211], v[50:51], v[70:71] neg_lo:[1,0,0] neg_hi:[1,0,0]
	ds_read_b128 v[204:207], v1 offset:14848
	s_waitcnt lgkmcnt(12)
	v_pk_fma_f32 v[68:69], v[212:213], v[52:53], v[68:69] neg_lo:[1,0,0] neg_hi:[1,0,0]
	v_pk_fma_f32 v[70:71], v[214:215], v[54:55], v[70:71] neg_lo:[1,0,0] neg_hi:[1,0,0]
	ds_read_b128 v[208:211], v1 offset:14864
	s_waitcnt lgkmcnt(12)
	v_fma_f32 v68, -v216, v56, v68
	ds_read_b128 v[212:215], v1 offset:14880
	ds_read_b128 v[216:219], v1 offset:14896
	v_add_f32_e32 v68, v68, v69
	v_add_f32_e32 v70, v70, v71
	v_add_f32_e32 v57, v68, v70
	v_mul_f32_e32 v72, v79, v57
	v_cvt_pk_bf16_f32 v72, v72, v72
	global_store_short v78, v72, s[38:39]
	v_add_u32_e32 v78, 0xc00, v78
	v_mov_b32_e32 v68, v58
	v_mov_b32_e32 v69, 0
	v_mov_b32_e32 v70, 0
	v_mov_b32_e32 v71, 0
	s_waitcnt lgkmcnt(13)
	v_pk_fma_f32 v[68:69], v[164:165], v[4:5], v[68:69] neg_lo:[1,0,0] neg_hi:[1,0,0]
	v_pk_fma_f32 v[70:71], v[166:167], v[6:7], v[70:71] neg_lo:[1,0,0] neg_hi:[1,0,0]
	s_waitcnt lgkmcnt(12)
	v_pk_fma_f32 v[68:69], v[168:169], v[8:9], v[68:69] neg_lo:[1,0,0] neg_hi:[1,0,0]
	v_pk_fma_f32 v[70:71], v[170:171], v[10:11], v[70:71] neg_lo:[1,0,0] neg_hi:[1,0,0]
	ds_read_b128 v[164:167], v1 offset:14960
	s_waitcnt lgkmcnt(12)
	v_pk_fma_f32 v[68:69], v[172:173], v[12:13], v[68:69] neg_lo:[1,0,0] neg_hi:[1,0,0]
	v_pk_fma_f32 v[70:71], v[174:175], v[14:15], v[70:71] neg_lo:[1,0,0] neg_hi:[1,0,0]
	ds_read_b128 v[168:171], v1 offset:14976
	s_waitcnt lgkmcnt(12)
	v_pk_fma_f32 v[68:69], v[176:177], v[16:17], v[68:69] neg_lo:[1,0,0] neg_hi:[1,0,0]
	v_pk_fma_f32 v[70:71], v[178:179], v[18:19], v[70:71] neg_lo:[1,0,0] neg_hi:[1,0,0]
	ds_read_b128 v[172:175], v1 offset:14992
	s_waitcnt lgkmcnt(12)
	v_pk_fma_f32 v[68:69], v[180:181], v[20:21], v[68:69] neg_lo:[1,0,0] neg_hi:[1,0,0]
	v_pk_fma_f32 v[70:71], v[182:183], v[22:23], v[70:71] neg_lo:[1,0,0] neg_hi:[1,0,0]
	ds_read_b128 v[176:179], v1 offset:15008
	s_waitcnt lgkmcnt(12)
	v_pk_fma_f32 v[68:69], v[184:185], v[24:25], v[68:69] neg_lo:[1,0,0] neg_hi:[1,0,0]
	v_pk_fma_f32 v[70:71], v[186:187], v[26:27], v[70:71] neg_lo:[1,0,0] neg_hi:[1,0,0]
	ds_read_b128 v[180:183], v1 offset:15024
	s_waitcnt lgkmcnt(12)
	v_pk_fma_f32 v[68:69], v[188:189], v[28:29], v[68:69] neg_lo:[1,0,0] neg_hi:[1,0,0]
	v_pk_fma_f32 v[70:71], v[190:191], v[30:31], v[70:71] neg_lo:[1,0,0] neg_hi:[1,0,0]
	ds_read_b128 v[184:187], v1 offset:15040
	s_waitcnt lgkmcnt(12)
	v_pk_fma_f32 v[68:69], v[192:193], v[32:33], v[68:69] neg_lo:[1,0,0] neg_hi:[1,0,0]
	v_pk_fma_f32 v[70:71], v[194:195], v[34:35], v[70:71] neg_lo:[1,0,0] neg_hi:[1,0,0]
	ds_read_b128 v[188:191], v1 offset:15056
	s_waitcnt lgkmcnt(12)
	v_pk_fma_f32 v[68:69], v[196:197], v[36:37], v[68:69] neg_lo:[1,0,0] neg_hi:[1,0,0]
	v_pk_fma_f32 v[70:71], v[198:199], v[38:39], v[70:71] neg_lo:[1,0,0] neg_hi:[1,0,0]
	ds_read_b128 v[192:195], v1 offset:15072
	s_waitcnt lgkmcnt(12)
	v_pk_fma_f32 v[68:69], v[200:201], v[40:41], v[68:69] neg_lo:[1,0,0] neg_hi:[1,0,0]
	v_pk_fma_f32 v[70:71], v[202:203], v[42:43], v[70:71] neg_lo:[1,0,0] neg_hi:[1,0,0]
	ds_read_b128 v[196:199], v1 offset:15088
	s_waitcnt lgkmcnt(12)
	v_pk_fma_f32 v[68:69], v[204:205], v[44:45], v[68:69] neg_lo:[1,0,0] neg_hi:[1,0,0]
	v_pk_fma_f32 v[70:71], v[206:207], v[46:47], v[70:71] neg_lo:[1,0,0] neg_hi:[1,0,0]
	ds_read_b128 v[200:203], v1 offset:15104
	s_waitcnt lgkmcnt(12)
	v_pk_fma_f32 v[68:69], v[208:209], v[48:49], v[68:69] neg_lo:[1,0,0] neg_hi:[1,0,0]
	v_pk_fma_f32 v[70:71], v[210:211], v[50:51], v[70:71] neg_lo:[1,0,0] neg_hi:[1,0,0]
	ds_read_b128 v[204:207], v1 offset:15120
	s_waitcnt lgkmcnt(12)
	v_pk_fma_f32 v[68:69], v[212:213], v[52:53], v[68:69] neg_lo:[1,0,0] neg_hi:[1,0,0]
	v_pk_fma_f32 v[70:71], v[214:215], v[54:55], v[70:71] neg_lo:[1,0,0] neg_hi:[1,0,0]
	ds_read_b128 v[208:211], v1 offset:15136
	s_waitcnt lgkmcnt(12)
	v_pk_fma_f32 v[68:69], v[216:217], v[56:57], v[68:69] neg_lo:[1,0,0] neg_hi:[1,0,0]
	ds_read_b128 v[212:215], v1 offset:15152
	ds_read_b128 v[216:219], v1 offset:15168
	v_add_f32_e32 v68, v68, v69
	v_add_f32_e32 v70, v70, v71
	v_add_f32_e32 v58, v68, v70
	v_mul_f32_e32 v72, v79, v58
	v_cvt_pk_bf16_f32 v72, v72, v72
	global_store_short v78, v72, s[38:39]
	v_add_u32_e32 v78, 0xc00, v78
	v_mov_b32_e32 v68, v59
	v_mov_b32_e32 v69, 0
	v_mov_b32_e32 v70, 0
	v_mov_b32_e32 v71, 0
	s_waitcnt lgkmcnt(13)
	v_pk_fma_f32 v[68:69], v[164:165], v[4:5], v[68:69] neg_lo:[1,0,0] neg_hi:[1,0,0]
	v_pk_fma_f32 v[70:71], v[166:167], v[6:7], v[70:71] neg_lo:[1,0,0] neg_hi:[1,0,0]
	s_waitcnt lgkmcnt(12)
	v_pk_fma_f32 v[68:69], v[168:169], v[8:9], v[68:69] neg_lo:[1,0,0] neg_hi:[1,0,0]
	v_pk_fma_f32 v[70:71], v[170:171], v[10:11], v[70:71] neg_lo:[1,0,0] neg_hi:[1,0,0]
	ds_read_b128 v[164:167], v1 offset:15232
	s_waitcnt lgkmcnt(12)
	v_pk_fma_f32 v[68:69], v[172:173], v[12:13], v[68:69] neg_lo:[1,0,0] neg_hi:[1,0,0]
	v_pk_fma_f32 v[70:71], v[174:175], v[14:15], v[70:71] neg_lo:[1,0,0] neg_hi:[1,0,0]
	ds_read_b128 v[168:171], v1 offset:15248
	s_waitcnt lgkmcnt(12)
	v_pk_fma_f32 v[68:69], v[176:177], v[16:17], v[68:69] neg_lo:[1,0,0] neg_hi:[1,0,0]
	v_pk_fma_f32 v[70:71], v[178:179], v[18:19], v[70:71] neg_lo:[1,0,0] neg_hi:[1,0,0]
	ds_read_b128 v[172:175], v1 offset:15264
	s_waitcnt lgkmcnt(12)
	v_pk_fma_f32 v[68:69], v[180:181], v[20:21], v[68:69] neg_lo:[1,0,0] neg_hi:[1,0,0]
	v_pk_fma_f32 v[70:71], v[182:183], v[22:23], v[70:71] neg_lo:[1,0,0] neg_hi:[1,0,0]
	ds_read_b128 v[176:179], v1 offset:15280
	s_waitcnt lgkmcnt(12)
	v_pk_fma_f32 v[68:69], v[184:185], v[24:25], v[68:69] neg_lo:[1,0,0] neg_hi:[1,0,0]
	v_pk_fma_f32 v[70:71], v[186:187], v[26:27], v[70:71] neg_lo:[1,0,0] neg_hi:[1,0,0]
	ds_read_b128 v[180:183], v1 offset:15296
	s_waitcnt lgkmcnt(12)
	v_pk_fma_f32 v[68:69], v[188:189], v[28:29], v[68:69] neg_lo:[1,0,0] neg_hi:[1,0,0]
	v_pk_fma_f32 v[70:71], v[190:191], v[30:31], v[70:71] neg_lo:[1,0,0] neg_hi:[1,0,0]
	ds_read_b128 v[184:187], v1 offset:15312
	s_waitcnt lgkmcnt(12)
	v_pk_fma_f32 v[68:69], v[192:193], v[32:33], v[68:69] neg_lo:[1,0,0] neg_hi:[1,0,0]
	v_pk_fma_f32 v[70:71], v[194:195], v[34:35], v[70:71] neg_lo:[1,0,0] neg_hi:[1,0,0]
	ds_read_b128 v[188:191], v1 offset:15328
	s_waitcnt lgkmcnt(12)
	v_pk_fma_f32 v[68:69], v[196:197], v[36:37], v[68:69] neg_lo:[1,0,0] neg_hi:[1,0,0]
	v_pk_fma_f32 v[70:71], v[198:199], v[38:39], v[70:71] neg_lo:[1,0,0] neg_hi:[1,0,0]
	ds_read_b128 v[192:195], v1 offset:15344
	s_waitcnt lgkmcnt(12)
	v_pk_fma_f32 v[68:69], v[200:201], v[40:41], v[68:69] neg_lo:[1,0,0] neg_hi:[1,0,0]
	v_pk_fma_f32 v[70:71], v[202:203], v[42:43], v[70:71] neg_lo:[1,0,0] neg_hi:[1,0,0]
	ds_read_b128 v[196:199], v1 offset:15360
	s_waitcnt lgkmcnt(12)
	v_pk_fma_f32 v[68:69], v[204:205], v[44:45], v[68:69] neg_lo:[1,0,0] neg_hi:[1,0,0]
	v_pk_fma_f32 v[70:71], v[206:207], v[46:47], v[70:71] neg_lo:[1,0,0] neg_hi:[1,0,0]
	ds_read_b128 v[200:203], v1 offset:15376
	s_waitcnt lgkmcnt(12)
	v_pk_fma_f32 v[68:69], v[208:209], v[48:49], v[68:69] neg_lo:[1,0,0] neg_hi:[1,0,0]
	v_pk_fma_f32 v[70:71], v[210:211], v[50:51], v[70:71] neg_lo:[1,0,0] neg_hi:[1,0,0]
	ds_read_b128 v[204:207], v1 offset:15392
	s_waitcnt lgkmcnt(12)
	v_pk_fma_f32 v[68:69], v[212:213], v[52:53], v[68:69] neg_lo:[1,0,0] neg_hi:[1,0,0]
	v_pk_fma_f32 v[70:71], v[214:215], v[54:55], v[70:71] neg_lo:[1,0,0] neg_hi:[1,0,0]
	ds_read_b128 v[208:211], v1 offset:15408
	s_waitcnt lgkmcnt(12)
	v_pk_fma_f32 v[68:69], v[216:217], v[56:57], v[68:69] neg_lo:[1,0,0] neg_hi:[1,0,0]
	v_fma_f32 v70, -v218, v58, v70
	ds_read_b128 v[212:215], v1 offset:15424
	ds_read_b128 v[216:219], v1 offset:15440
	v_add_f32_e32 v68, v68, v69
	v_add_f32_e32 v70, v70, v71
	v_add_f32_e32 v59, v68, v70
	v_mul_f32_e32 v72, v79, v59
	v_cvt_pk_bf16_f32 v72, v72, v72
	global_store_short v78, v72, s[38:39]
	v_add_u32_e32 v78, 0xc00, v78
	v_mov_b32_e32 v68, v60
	v_mov_b32_e32 v69, 0
	v_mov_b32_e32 v70, 0
	v_mov_b32_e32 v71, 0
	s_waitcnt lgkmcnt(13)
	v_pk_fma_f32 v[68:69], v[164:165], v[4:5], v[68:69] neg_lo:[1,0,0] neg_hi:[1,0,0]
	v_pk_fma_f32 v[70:71], v[166:167], v[6:7], v[70:71] neg_lo:[1,0,0] neg_hi:[1,0,0]
	s_waitcnt lgkmcnt(12)
	v_pk_fma_f32 v[68:69], v[168:169], v[8:9], v[68:69] neg_lo:[1,0,0] neg_hi:[1,0,0]
	v_pk_fma_f32 v[70:71], v[170:171], v[10:11], v[70:71] neg_lo:[1,0,0] neg_hi:[1,0,0]
	ds_read_b128 v[164:167], v1 offset:15504
	s_waitcnt lgkmcnt(12)
	v_pk_fma_f32 v[68:69], v[172:173], v[12:13], v[68:69] neg_lo:[1,0,0] neg_hi:[1,0,0]
	v_pk_fma_f32 v[70:71], v[174:175], v[14:15], v[70:71] neg_lo:[1,0,0] neg_hi:[1,0,0]
	ds_read_b128 v[168:171], v1 offset:15520
	s_waitcnt lgkmcnt(12)
	v_pk_fma_f32 v[68:69], v[176:177], v[16:17], v[68:69] neg_lo:[1,0,0] neg_hi:[1,0,0]
	v_pk_fma_f32 v[70:71], v[178:179], v[18:19], v[70:71] neg_lo:[1,0,0] neg_hi:[1,0,0]
	ds_read_b128 v[172:175], v1 offset:15536
	s_waitcnt lgkmcnt(12)
	v_pk_fma_f32 v[68:69], v[180:181], v[20:21], v[68:69] neg_lo:[1,0,0] neg_hi:[1,0,0]
	v_pk_fma_f32 v[70:71], v[182:183], v[22:23], v[70:71] neg_lo:[1,0,0] neg_hi:[1,0,0]
	ds_read_b128 v[176:179], v1 offset:15552
	s_waitcnt lgkmcnt(12)
	v_pk_fma_f32 v[68:69], v[184:185], v[24:25], v[68:69] neg_lo:[1,0,0] neg_hi:[1,0,0]
	v_pk_fma_f32 v[70:71], v[186:187], v[26:27], v[70:71] neg_lo:[1,0,0] neg_hi:[1,0,0]
	ds_read_b128 v[180:183], v1 offset:15568
	s_waitcnt lgkmcnt(12)
	v_pk_fma_f32 v[68:69], v[188:189], v[28:29], v[68:69] neg_lo:[1,0,0] neg_hi:[1,0,0]
	v_pk_fma_f32 v[70:71], v[190:191], v[30:31], v[70:71] neg_lo:[1,0,0] neg_hi:[1,0,0]
	ds_read_b128 v[184:187], v1 offset:15584
	s_waitcnt lgkmcnt(12)
	v_pk_fma_f32 v[68:69], v[192:193], v[32:33], v[68:69] neg_lo:[1,0,0] neg_hi:[1,0,0]
	v_pk_fma_f32 v[70:71], v[194:195], v[34:35], v[70:71] neg_lo:[1,0,0] neg_hi:[1,0,0]
	ds_read_b128 v[188:191], v1 offset:15600
	s_waitcnt lgkmcnt(12)
	v_pk_fma_f32 v[68:69], v[196:197], v[36:37], v[68:69] neg_lo:[1,0,0] neg_hi:[1,0,0]
	v_pk_fma_f32 v[70:71], v[198:199], v[38:39], v[70:71] neg_lo:[1,0,0] neg_hi:[1,0,0]
	ds_read_b128 v[192:195], v1 offset:15616
	s_waitcnt lgkmcnt(12)
	v_pk_fma_f32 v[68:69], v[200:201], v[40:41], v[68:69] neg_lo:[1,0,0] neg_hi:[1,0,0]
	v_pk_fma_f32 v[70:71], v[202:203], v[42:43], v[70:71] neg_lo:[1,0,0] neg_hi:[1,0,0]
	ds_read_b128 v[196:199], v1 offset:15632
	s_waitcnt lgkmcnt(12)
	v_pk_fma_f32 v[68:69], v[204:205], v[44:45], v[68:69] neg_lo:[1,0,0] neg_hi:[1,0,0]
	v_pk_fma_f32 v[70:71], v[206:207], v[46:47], v[70:71] neg_lo:[1,0,0] neg_hi:[1,0,0]
	ds_read_b128 v[200:203], v1 offset:15648
	s_waitcnt lgkmcnt(12)
	v_pk_fma_f32 v[68:69], v[208:209], v[48:49], v[68:69] neg_lo:[1,0,0] neg_hi:[1,0,0]
	v_pk_fma_f32 v[70:71], v[210:211], v[50:51], v[70:71] neg_lo:[1,0,0] neg_hi:[1,0,0]
	ds_read_b128 v[204:207], v1 offset:15664
	s_waitcnt lgkmcnt(12)
	v_pk_fma_f32 v[68:69], v[212:213], v[52:53], v[68:69] neg_lo:[1,0,0] neg_hi:[1,0,0]
	v_pk_fma_f32 v[70:71], v[214:215], v[54:55], v[70:71] neg_lo:[1,0,0] neg_hi:[1,0,0]
	ds_read_b128 v[208:211], v1 offset:15680
	s_waitcnt lgkmcnt(12)
	v_pk_fma_f32 v[68:69], v[216:217], v[56:57], v[68:69] neg_lo:[1,0,0] neg_hi:[1,0,0]
	v_pk_fma_f32 v[70:71], v[218:219], v[58:59], v[70:71] neg_lo:[1,0,0] neg_hi:[1,0,0]
	ds_read_b128 v[212:215], v1 offset:15696
	ds_read_b128 v[216:219], v1 offset:15712
	ds_read_b128 v[220:223], v1 offset:15728
	v_add_f32_e32 v68, v68, v69
	v_add_f32_e32 v70, v70, v71
	v_add_f32_e32 v60, v68, v70
	v_mul_f32_e32 v72, v79, v60
	v_cvt_pk_bf16_f32 v72, v72, v72
	global_store_short v78, v72, s[38:39]
	v_add_u32_e32 v78, 0xc00, v78
	v_mov_b32_e32 v68, v61
	v_mov_b32_e32 v69, 0
	v_mov_b32_e32 v70, 0
	v_mov_b32_e32 v71, 0
	s_waitcnt lgkmcnt(14)
	v_pk_fma_f32 v[68:69], v[164:165], v[4:5], v[68:69] neg_lo:[1,0,0] neg_hi:[1,0,0]
	v_pk_fma_f32 v[70:71], v[166:167], v[6:7], v[70:71] neg_lo:[1,0,0] neg_hi:[1,0,0]
	s_waitcnt lgkmcnt(13)
	v_pk_fma_f32 v[68:69], v[168:169], v[8:9], v[68:69] neg_lo:[1,0,0] neg_hi:[1,0,0]
	v_pk_fma_f32 v[70:71], v[170:171], v[10:11], v[70:71] neg_lo:[1,0,0] neg_hi:[1,0,0]
	ds_read_b128 v[164:167], v1 offset:15776
	s_waitcnt lgkmcnt(13)
	v_pk_fma_f32 v[68:69], v[172:173], v[12:13], v[68:69] neg_lo:[1,0,0] neg_hi:[1,0,0]
	v_pk_fma_f32 v[70:71], v[174:175], v[14:15], v[70:71] neg_lo:[1,0,0] neg_hi:[1,0,0]
	ds_read_b128 v[168:171], v1 offset:15792
	s_waitcnt lgkmcnt(13)
	v_pk_fma_f32 v[68:69], v[176:177], v[16:17], v[68:69] neg_lo:[1,0,0] neg_hi:[1,0,0]
	v_pk_fma_f32 v[70:71], v[178:179], v[18:19], v[70:71] neg_lo:[1,0,0] neg_hi:[1,0,0]
	ds_read_b128 v[172:175], v1 offset:15808
	s_waitcnt lgkmcnt(13)
	v_pk_fma_f32 v[68:69], v[180:181], v[20:21], v[68:69] neg_lo:[1,0,0] neg_hi:[1,0,0]
	v_pk_fma_f32 v[70:71], v[182:183], v[22:23], v[70:71] neg_lo:[1,0,0] neg_hi:[1,0,0]
	ds_read_b128 v[176:179], v1 offset:15824
	s_waitcnt lgkmcnt(13)
	v_pk_fma_f32 v[68:69], v[184:185], v[24:25], v[68:69] neg_lo:[1,0,0] neg_hi:[1,0,0]
	v_pk_fma_f32 v[70:71], v[186:187], v[26:27], v[70:71] neg_lo:[1,0,0] neg_hi:[1,0,0]
	ds_read_b128 v[180:183], v1 offset:15840
	s_waitcnt lgkmcnt(13)
	v_pk_fma_f32 v[68:69], v[188:189], v[28:29], v[68:69] neg_lo:[1,0,0] neg_hi:[1,0,0]
	v_pk_fma_f32 v[70:71], v[190:191], v[30:31], v[70:71] neg_lo:[1,0,0] neg_hi:[1,0,0]
	ds_read_b128 v[184:187], v1 offset:15856
	s_waitcnt lgkmcnt(13)
	v_pk_fma_f32 v[68:69], v[192:193], v[32:33], v[68:69] neg_lo:[1,0,0] neg_hi:[1,0,0]
	v_pk_fma_f32 v[70:71], v[194:195], v[34:35], v[70:71] neg_lo:[1,0,0] neg_hi:[1,0,0]
	ds_read_b128 v[188:191], v1 offset:15872
	s_waitcnt lgkmcnt(13)
	v_pk_fma_f32 v[68:69], v[196:197], v[36:37], v[68:69] neg_lo:[1,0,0] neg_hi:[1,0,0]
	v_pk_fma_f32 v[70:71], v[198:199], v[38:39], v[70:71] neg_lo:[1,0,0] neg_hi:[1,0,0]
	ds_read_b128 v[192:195], v1 offset:15888
	s_waitcnt lgkmcnt(13)
	v_pk_fma_f32 v[68:69], v[200:201], v[40:41], v[68:69] neg_lo:[1,0,0] neg_hi:[1,0,0]
	v_pk_fma_f32 v[70:71], v[202:203], v[42:43], v[70:71] neg_lo:[1,0,0] neg_hi:[1,0,0]
	ds_read_b128 v[196:199], v1 offset:15904
	s_waitcnt lgkmcnt(13)
	v_pk_fma_f32 v[68:69], v[204:205], v[44:45], v[68:69] neg_lo:[1,0,0] neg_hi:[1,0,0]
	v_pk_fma_f32 v[70:71], v[206:207], v[46:47], v[70:71] neg_lo:[1,0,0] neg_hi:[1,0,0]
	ds_read_b128 v[200:203], v1 offset:15920
	s_waitcnt lgkmcnt(13)
	v_pk_fma_f32 v[68:69], v[208:209], v[48:49], v[68:69] neg_lo:[1,0,0] neg_hi:[1,0,0]
	v_pk_fma_f32 v[70:71], v[210:211], v[50:51], v[70:71] neg_lo:[1,0,0] neg_hi:[1,0,0]
	ds_read_b128 v[204:207], v1 offset:15936
	s_waitcnt lgkmcnt(13)
	v_pk_fma_f32 v[68:69], v[212:213], v[52:53], v[68:69] neg_lo:[1,0,0] neg_hi:[1,0,0]
	v_pk_fma_f32 v[70:71], v[214:215], v[54:55], v[70:71] neg_lo:[1,0,0] neg_hi:[1,0,0]
	ds_read_b128 v[208:211], v1 offset:15952
	s_waitcnt lgkmcnt(13)
	v_pk_fma_f32 v[68:69], v[216:217], v[56:57], v[68:69] neg_lo:[1,0,0] neg_hi:[1,0,0]
	v_pk_fma_f32 v[70:71], v[218:219], v[58:59], v[70:71] neg_lo:[1,0,0] neg_hi:[1,0,0]
	ds_read_b128 v[212:215], v1 offset:15968
	s_waitcnt lgkmcnt(13)
	v_fma_f32 v68, -v220, v60, v68
	ds_read_b128 v[216:219], v1 offset:15984
	ds_read_b128 v[220:223], v1 offset:16000
	v_add_f32_e32 v68, v68, v69
	v_add_f32_e32 v70, v70, v71
	v_add_f32_e32 v61, v68, v70
	v_mul_f32_e32 v72, v79, v61
	v_cvt_pk_bf16_f32 v72, v72, v72
	global_store_short v78, v72, s[38:39]
	v_add_u32_e32 v78, 0xc00, v78
	v_mov_b32_e32 v68, v62
	v_mov_b32_e32 v69, 0
	v_mov_b32_e32 v70, 0
	v_mov_b32_e32 v71, 0
	s_waitcnt lgkmcnt(14)
	v_pk_fma_f32 v[68:69], v[164:165], v[4:5], v[68:69] neg_lo:[1,0,0] neg_hi:[1,0,0]
	v_pk_fma_f32 v[70:71], v[166:167], v[6:7], v[70:71] neg_lo:[1,0,0] neg_hi:[1,0,0]
	s_waitcnt lgkmcnt(13)
	v_pk_fma_f32 v[68:69], v[168:169], v[8:9], v[68:69] neg_lo:[1,0,0] neg_hi:[1,0,0]
	v_pk_fma_f32 v[70:71], v[170:171], v[10:11], v[70:71] neg_lo:[1,0,0] neg_hi:[1,0,0]
	ds_read_b128 v[164:167], v1 offset:16048
	s_waitcnt lgkmcnt(13)
	v_pk_fma_f32 v[68:69], v[172:173], v[12:13], v[68:69] neg_lo:[1,0,0] neg_hi:[1,0,0]
	v_pk_fma_f32 v[70:71], v[174:175], v[14:15], v[70:71] neg_lo:[1,0,0] neg_hi:[1,0,0]
	ds_read_b128 v[168:171], v1 offset:16064
	s_waitcnt lgkmcnt(13)
	v_pk_fma_f32 v[68:69], v[176:177], v[16:17], v[68:69] neg_lo:[1,0,0] neg_hi:[1,0,0]
	v_pk_fma_f32 v[70:71], v[178:179], v[18:19], v[70:71] neg_lo:[1,0,0] neg_hi:[1,0,0]
	ds_read_b128 v[172:175], v1 offset:16080
	s_waitcnt lgkmcnt(13)
	v_pk_fma_f32 v[68:69], v[180:181], v[20:21], v[68:69] neg_lo:[1,0,0] neg_hi:[1,0,0]
	v_pk_fma_f32 v[70:71], v[182:183], v[22:23], v[70:71] neg_lo:[1,0,0] neg_hi:[1,0,0]
	ds_read_b128 v[176:179], v1 offset:16096
	s_waitcnt lgkmcnt(13)
	v_pk_fma_f32 v[68:69], v[184:185], v[24:25], v[68:69] neg_lo:[1,0,0] neg_hi:[1,0,0]
	v_pk_fma_f32 v[70:71], v[186:187], v[26:27], v[70:71] neg_lo:[1,0,0] neg_hi:[1,0,0]
	ds_read_b128 v[180:183], v1 offset:16112
	s_waitcnt lgkmcnt(13)
	v_pk_fma_f32 v[68:69], v[188:189], v[28:29], v[68:69] neg_lo:[1,0,0] neg_hi:[1,0,0]
	v_pk_fma_f32 v[70:71], v[190:191], v[30:31], v[70:71] neg_lo:[1,0,0] neg_hi:[1,0,0]
	ds_read_b128 v[184:187], v1 offset:16128
	s_waitcnt lgkmcnt(13)
	v_pk_fma_f32 v[68:69], v[192:193], v[32:33], v[68:69] neg_lo:[1,0,0] neg_hi:[1,0,0]
	v_pk_fma_f32 v[70:71], v[194:195], v[34:35], v[70:71] neg_lo:[1,0,0] neg_hi:[1,0,0]
	ds_read_b128 v[188:191], v1 offset:16144
	s_waitcnt lgkmcnt(13)
	v_pk_fma_f32 v[68:69], v[196:197], v[36:37], v[68:69] neg_lo:[1,0,0] neg_hi:[1,0,0]
	v_pk_fma_f32 v[70:71], v[198:199], v[38:39], v[70:71] neg_lo:[1,0,0] neg_hi:[1,0,0]
	ds_read_b128 v[192:195], v1 offset:16160
	s_waitcnt lgkmcnt(13)
	v_pk_fma_f32 v[68:69], v[200:201], v[40:41], v[68:69] neg_lo:[1,0,0] neg_hi:[1,0,0]
	v_pk_fma_f32 v[70:71], v[202:203], v[42:43], v[70:71] neg_lo:[1,0,0] neg_hi:[1,0,0]
	ds_read_b128 v[196:199], v1 offset:16176
	s_waitcnt lgkmcnt(13)
	v_pk_fma_f32 v[68:69], v[204:205], v[44:45], v[68:69] neg_lo:[1,0,0] neg_hi:[1,0,0]
	v_pk_fma_f32 v[70:71], v[206:207], v[46:47], v[70:71] neg_lo:[1,0,0] neg_hi:[1,0,0]
	ds_read_b128 v[200:203], v1 offset:16192
	s_waitcnt lgkmcnt(13)
	v_pk_fma_f32 v[68:69], v[208:209], v[48:49], v[68:69] neg_lo:[1,0,0] neg_hi:[1,0,0]
	v_pk_fma_f32 v[70:71], v[210:211], v[50:51], v[70:71] neg_lo:[1,0,0] neg_hi:[1,0,0]
	ds_read_b128 v[204:207], v1 offset:16208
	s_waitcnt lgkmcnt(13)
	v_pk_fma_f32 v[68:69], v[212:213], v[52:53], v[68:69] neg_lo:[1,0,0] neg_hi:[1,0,0]
	v_pk_fma_f32 v[70:71], v[214:215], v[54:55], v[70:71] neg_lo:[1,0,0] neg_hi:[1,0,0]
	ds_read_b128 v[208:211], v1 offset:16224
	s_waitcnt lgkmcnt(13)
	v_pk_fma_f32 v[68:69], v[216:217], v[56:57], v[68:69] neg_lo:[1,0,0] neg_hi:[1,0,0]
	v_pk_fma_f32 v[70:71], v[218:219], v[58:59], v[70:71] neg_lo:[1,0,0] neg_hi:[1,0,0]
	ds_read_b128 v[212:215], v1 offset:16240
	s_waitcnt lgkmcnt(13)
	v_pk_fma_f32 v[68:69], v[220:221], v[60:61], v[68:69] neg_lo:[1,0,0] neg_hi:[1,0,0]
	ds_read_b128 v[216:219], v1 offset:16256
	ds_read_b128 v[220:223], v1 offset:16272
	v_add_f32_e32 v68, v68, v69
	v_add_f32_e32 v70, v70, v71
	v_add_f32_e32 v62, v68, v70
	v_mul_f32_e32 v72, v79, v62
	v_cvt_pk_bf16_f32 v72, v72, v72
	global_store_short v78, v72, s[38:39]
	v_add_u32_e32 v78, 0xc00, v78
	v_mov_b32_e32 v68, v63
	v_mov_b32_e32 v69, 0
	v_mov_b32_e32 v70, 0
	v_mov_b32_e32 v71, 0
	s_waitcnt lgkmcnt(14)
	v_pk_fma_f32 v[68:69], v[164:165], v[4:5], v[68:69] neg_lo:[1,0,0] neg_hi:[1,0,0]
	v_pk_fma_f32 v[70:71], v[166:167], v[6:7], v[70:71] neg_lo:[1,0,0] neg_hi:[1,0,0]
	s_waitcnt lgkmcnt(13)
	v_pk_fma_f32 v[68:69], v[168:169], v[8:9], v[68:69] neg_lo:[1,0,0] neg_hi:[1,0,0]
	v_pk_fma_f32 v[70:71], v[170:171], v[10:11], v[70:71] neg_lo:[1,0,0] neg_hi:[1,0,0]
	ds_read_b128 v[164:167], v1 offset:16320
	s_waitcnt lgkmcnt(13)
	v_pk_fma_f32 v[68:69], v[172:173], v[12:13], v[68:69] neg_lo:[1,0,0] neg_hi:[1,0,0]
	v_pk_fma_f32 v[70:71], v[174:175], v[14:15], v[70:71] neg_lo:[1,0,0] neg_hi:[1,0,0]
	ds_read_b128 v[168:171], v1 offset:16336
	s_waitcnt lgkmcnt(13)
	v_pk_fma_f32 v[68:69], v[176:177], v[16:17], v[68:69] neg_lo:[1,0,0] neg_hi:[1,0,0]
	v_pk_fma_f32 v[70:71], v[178:179], v[18:19], v[70:71] neg_lo:[1,0,0] neg_hi:[1,0,0]
	ds_read_b128 v[172:175], v1 offset:16352
	s_waitcnt lgkmcnt(13)
	v_pk_fma_f32 v[68:69], v[180:181], v[20:21], v[68:69] neg_lo:[1,0,0] neg_hi:[1,0,0]
	v_pk_fma_f32 v[70:71], v[182:183], v[22:23], v[70:71] neg_lo:[1,0,0] neg_hi:[1,0,0]
	ds_read_b128 v[176:179], v1 offset:16368
	s_waitcnt lgkmcnt(13)
	v_pk_fma_f32 v[68:69], v[184:185], v[24:25], v[68:69] neg_lo:[1,0,0] neg_hi:[1,0,0]
	v_pk_fma_f32 v[70:71], v[186:187], v[26:27], v[70:71] neg_lo:[1,0,0] neg_hi:[1,0,0]
	ds_read_b128 v[180:183], v1 offset:16384
	s_waitcnt lgkmcnt(13)
	v_pk_fma_f32 v[68:69], v[188:189], v[28:29], v[68:69] neg_lo:[1,0,0] neg_hi:[1,0,0]
	v_pk_fma_f32 v[70:71], v[190:191], v[30:31], v[70:71] neg_lo:[1,0,0] neg_hi:[1,0,0]
	ds_read_b128 v[184:187], v1 offset:16400
	s_waitcnt lgkmcnt(13)
	v_pk_fma_f32 v[68:69], v[192:193], v[32:33], v[68:69] neg_lo:[1,0,0] neg_hi:[1,0,0]
	v_pk_fma_f32 v[70:71], v[194:195], v[34:35], v[70:71] neg_lo:[1,0,0] neg_hi:[1,0,0]
	ds_read_b128 v[188:191], v1 offset:16416
	s_waitcnt lgkmcnt(13)
	v_pk_fma_f32 v[68:69], v[196:197], v[36:37], v[68:69] neg_lo:[1,0,0] neg_hi:[1,0,0]
	v_pk_fma_f32 v[70:71], v[198:199], v[38:39], v[70:71] neg_lo:[1,0,0] neg_hi:[1,0,0]
	ds_read_b128 v[192:195], v1 offset:16432
	s_waitcnt lgkmcnt(13)
	v_pk_fma_f32 v[68:69], v[200:201], v[40:41], v[68:69] neg_lo:[1,0,0] neg_hi:[1,0,0]
	v_pk_fma_f32 v[70:71], v[202:203], v[42:43], v[70:71] neg_lo:[1,0,0] neg_hi:[1,0,0]
	ds_read_b128 v[196:199], v1 offset:16448
	s_waitcnt lgkmcnt(13)
	v_pk_fma_f32 v[68:69], v[204:205], v[44:45], v[68:69] neg_lo:[1,0,0] neg_hi:[1,0,0]
	v_pk_fma_f32 v[70:71], v[206:207], v[46:47], v[70:71] neg_lo:[1,0,0] neg_hi:[1,0,0]
	ds_read_b128 v[200:203], v1 offset:16464
	s_waitcnt lgkmcnt(13)
	v_pk_fma_f32 v[68:69], v[208:209], v[48:49], v[68:69] neg_lo:[1,0,0] neg_hi:[1,0,0]
	v_pk_fma_f32 v[70:71], v[210:211], v[50:51], v[70:71] neg_lo:[1,0,0] neg_hi:[1,0,0]
	ds_read_b128 v[204:207], v1 offset:16480
	s_waitcnt lgkmcnt(13)
	v_pk_fma_f32 v[68:69], v[212:213], v[52:53], v[68:69] neg_lo:[1,0,0] neg_hi:[1,0,0]
	v_pk_fma_f32 v[70:71], v[214:215], v[54:55], v[70:71] neg_lo:[1,0,0] neg_hi:[1,0,0]
	ds_read_b128 v[208:211], v1 offset:16496
	s_waitcnt lgkmcnt(13)
	v_pk_fma_f32 v[68:69], v[216:217], v[56:57], v[68:69] neg_lo:[1,0,0] neg_hi:[1,0,0]
	v_pk_fma_f32 v[70:71], v[218:219], v[58:59], v[70:71] neg_lo:[1,0,0] neg_hi:[1,0,0]
	ds_read_b128 v[212:215], v1 offset:16512
	s_waitcnt lgkmcnt(13)
	v_pk_fma_f32 v[68:69], v[220:221], v[60:61], v[68:69] neg_lo:[1,0,0] neg_hi:[1,0,0]
	v_fma_f32 v70, -v222, v62, v70
	ds_read_b128 v[216:219], v1 offset:16528
	ds_read_b128 v[220:223], v1 offset:16544
	v_add_f32_e32 v68, v68, v69
	v_add_f32_e32 v70, v70, v71
	v_add_f32_e32 v63, v68, v70
	v_mul_f32_e32 v72, v79, v63
	v_cvt_pk_bf16_f32 v72, v72, v72
	global_store_short v78, v72, s[38:39]
	v_add_u32_e32 v78, 0xc00, v78
	v_mov_b32_e32 v68, v64
	v_mov_b32_e32 v69, 0
	v_mov_b32_e32 v70, 0
	v_mov_b32_e32 v71, 0
	s_waitcnt lgkmcnt(14)
	v_pk_fma_f32 v[68:69], v[164:165], v[4:5], v[68:69] neg_lo:[1,0,0] neg_hi:[1,0,0]
	v_pk_fma_f32 v[70:71], v[166:167], v[6:7], v[70:71] neg_lo:[1,0,0] neg_hi:[1,0,0]
	s_waitcnt lgkmcnt(13)
	v_pk_fma_f32 v[68:69], v[168:169], v[8:9], v[68:69] neg_lo:[1,0,0] neg_hi:[1,0,0]
	v_pk_fma_f32 v[70:71], v[170:171], v[10:11], v[70:71] neg_lo:[1,0,0] neg_hi:[1,0,0]
	ds_read_b128 v[164:167], v1 offset:16592
	s_waitcnt lgkmcnt(13)
	v_pk_fma_f32 v[68:69], v[172:173], v[12:13], v[68:69] neg_lo:[1,0,0] neg_hi:[1,0,0]
	v_pk_fma_f32 v[70:71], v[174:175], v[14:15], v[70:71] neg_lo:[1,0,0] neg_hi:[1,0,0]
	ds_read_b128 v[168:171], v1 offset:16608
	s_waitcnt lgkmcnt(13)
	v_pk_fma_f32 v[68:69], v[176:177], v[16:17], v[68:69] neg_lo:[1,0,0] neg_hi:[1,0,0]
	v_pk_fma_f32 v[70:71], v[178:179], v[18:19], v[70:71] neg_lo:[1,0,0] neg_hi:[1,0,0]
	ds_read_b128 v[172:175], v1 offset:16624
	s_waitcnt lgkmcnt(13)
	v_pk_fma_f32 v[68:69], v[180:181], v[20:21], v[68:69] neg_lo:[1,0,0] neg_hi:[1,0,0]
	v_pk_fma_f32 v[70:71], v[182:183], v[22:23], v[70:71] neg_lo:[1,0,0] neg_hi:[1,0,0]
	ds_read_b128 v[176:179], v1 offset:16640
	s_waitcnt lgkmcnt(13)
	v_pk_fma_f32 v[68:69], v[184:185], v[24:25], v[68:69] neg_lo:[1,0,0] neg_hi:[1,0,0]
	v_pk_fma_f32 v[70:71], v[186:187], v[26:27], v[70:71] neg_lo:[1,0,0] neg_hi:[1,0,0]
	ds_read_b128 v[180:183], v1 offset:16656
	s_waitcnt lgkmcnt(13)
	v_pk_fma_f32 v[68:69], v[188:189], v[28:29], v[68:69] neg_lo:[1,0,0] neg_hi:[1,0,0]
	v_pk_fma_f32 v[70:71], v[190:191], v[30:31], v[70:71] neg_lo:[1,0,0] neg_hi:[1,0,0]
	ds_read_b128 v[184:187], v1 offset:16672
	s_waitcnt lgkmcnt(13)
	v_pk_fma_f32 v[68:69], v[192:193], v[32:33], v[68:69] neg_lo:[1,0,0] neg_hi:[1,0,0]
	v_pk_fma_f32 v[70:71], v[194:195], v[34:35], v[70:71] neg_lo:[1,0,0] neg_hi:[1,0,0]
	ds_read_b128 v[188:191], v1 offset:16688
	s_waitcnt lgkmcnt(13)
	v_pk_fma_f32 v[68:69], v[196:197], v[36:37], v[68:69] neg_lo:[1,0,0] neg_hi:[1,0,0]
	v_pk_fma_f32 v[70:71], v[198:199], v[38:39], v[70:71] neg_lo:[1,0,0] neg_hi:[1,0,0]
	ds_read_b128 v[192:195], v1 offset:16704
	s_waitcnt lgkmcnt(13)
	v_pk_fma_f32 v[68:69], v[200:201], v[40:41], v[68:69] neg_lo:[1,0,0] neg_hi:[1,0,0]
	v_pk_fma_f32 v[70:71], v[202:203], v[42:43], v[70:71] neg_lo:[1,0,0] neg_hi:[1,0,0]
	ds_read_b128 v[196:199], v1 offset:16720
	s_waitcnt lgkmcnt(13)
	v_pk_fma_f32 v[68:69], v[204:205], v[44:45], v[68:69] neg_lo:[1,0,0] neg_hi:[1,0,0]
	v_pk_fma_f32 v[70:71], v[206:207], v[46:47], v[70:71] neg_lo:[1,0,0] neg_hi:[1,0,0]
	ds_read_b128 v[200:203], v1 offset:16736
	s_waitcnt lgkmcnt(13)
	v_pk_fma_f32 v[68:69], v[208:209], v[48:49], v[68:69] neg_lo:[1,0,0] neg_hi:[1,0,0]
	v_pk_fma_f32 v[70:71], v[210:211], v[50:51], v[70:71] neg_lo:[1,0,0] neg_hi:[1,0,0]
	ds_read_b128 v[204:207], v1 offset:16752
	s_waitcnt lgkmcnt(13)
	v_pk_fma_f32 v[68:69], v[212:213], v[52:53], v[68:69] neg_lo:[1,0,0] neg_hi:[1,0,0]
	v_pk_fma_f32 v[70:71], v[214:215], v[54:55], v[70:71] neg_lo:[1,0,0] neg_hi:[1,0,0]
	ds_read_b128 v[208:211], v1 offset:16768
	s_waitcnt lgkmcnt(13)
	v_pk_fma_f32 v[68:69], v[216:217], v[56:57], v[68:69] neg_lo:[1,0,0] neg_hi:[1,0,0]
	v_pk_fma_f32 v[70:71], v[218:219], v[58:59], v[70:71] neg_lo:[1,0,0] neg_hi:[1,0,0]
	ds_read_b128 v[212:215], v1 offset:16784
	s_waitcnt lgkmcnt(13)
	v_pk_fma_f32 v[68:69], v[220:221], v[60:61], v[68:69] neg_lo:[1,0,0] neg_hi:[1,0,0]
	v_pk_fma_f32 v[70:71], v[222:223], v[62:63], v[70:71] neg_lo:[1,0,0] neg_hi:[1,0,0]
	ds_read_b128 v[216:219], v1 offset:16800
	ds_read_b128 v[220:223], v1 offset:16816
	ds_read_b128 v[224:227], v1 offset:16832
	v_add_f32_e32 v68, v68, v69
	v_add_f32_e32 v70, v70, v71
	v_add_f32_e32 v64, v68, v70
	v_mul_f32_e32 v72, v79, v64
	v_cvt_pk_bf16_f32 v72, v72, v72
	global_store_short v78, v72, s[38:39]
	v_add_u32_e32 v78, 0xc00, v78
	v_mov_b32_e32 v68, v65
	v_mov_b32_e32 v69, 0
	v_mov_b32_e32 v70, 0
	v_mov_b32_e32 v71, 0
	s_waitcnt lgkmcnt(15)
	v_pk_fma_f32 v[68:69], v[164:165], v[4:5], v[68:69] neg_lo:[1,0,0] neg_hi:[1,0,0]
	v_pk_fma_f32 v[70:71], v[166:167], v[6:7], v[70:71] neg_lo:[1,0,0] neg_hi:[1,0,0]
	s_waitcnt lgkmcnt(14)
	v_pk_fma_f32 v[68:69], v[168:169], v[8:9], v[68:69] neg_lo:[1,0,0] neg_hi:[1,0,0]
	v_pk_fma_f32 v[70:71], v[170:171], v[10:11], v[70:71] neg_lo:[1,0,0] neg_hi:[1,0,0]
	ds_read_b128 v[164:167], v1 offset:16864
	s_waitcnt lgkmcnt(14)
	v_pk_fma_f32 v[68:69], v[172:173], v[12:13], v[68:69] neg_lo:[1,0,0] neg_hi:[1,0,0]
	v_pk_fma_f32 v[70:71], v[174:175], v[14:15], v[70:71] neg_lo:[1,0,0] neg_hi:[1,0,0]
	ds_read_b128 v[168:171], v1 offset:16880
	s_waitcnt lgkmcnt(14)
	v_pk_fma_f32 v[68:69], v[176:177], v[16:17], v[68:69] neg_lo:[1,0,0] neg_hi:[1,0,0]
	v_pk_fma_f32 v[70:71], v[178:179], v[18:19], v[70:71] neg_lo:[1,0,0] neg_hi:[1,0,0]
	ds_read_b128 v[172:175], v1 offset:16896
	s_waitcnt lgkmcnt(14)
	v_pk_fma_f32 v[68:69], v[180:181], v[20:21], v[68:69] neg_lo:[1,0,0] neg_hi:[1,0,0]
	v_pk_fma_f32 v[70:71], v[182:183], v[22:23], v[70:71] neg_lo:[1,0,0] neg_hi:[1,0,0]
	ds_read_b128 v[176:179], v1 offset:16912
	s_waitcnt lgkmcnt(14)
	v_pk_fma_f32 v[68:69], v[184:185], v[24:25], v[68:69] neg_lo:[1,0,0] neg_hi:[1,0,0]
	v_pk_fma_f32 v[70:71], v[186:187], v[26:27], v[70:71] neg_lo:[1,0,0] neg_hi:[1,0,0]
	ds_read_b128 v[180:183], v1 offset:16928
	s_waitcnt lgkmcnt(14)
	v_pk_fma_f32 v[68:69], v[188:189], v[28:29], v[68:69] neg_lo:[1,0,0] neg_hi:[1,0,0]
	v_pk_fma_f32 v[70:71], v[190:191], v[30:31], v[70:71] neg_lo:[1,0,0] neg_hi:[1,0,0]
	ds_read_b128 v[184:187], v1 offset:16944
	s_waitcnt lgkmcnt(14)
	v_pk_fma_f32 v[68:69], v[192:193], v[32:33], v[68:69] neg_lo:[1,0,0] neg_hi:[1,0,0]
	v_pk_fma_f32 v[70:71], v[194:195], v[34:35], v[70:71] neg_lo:[1,0,0] neg_hi:[1,0,0]
	ds_read_b128 v[188:191], v1 offset:16960
	s_waitcnt lgkmcnt(14)
	v_pk_fma_f32 v[68:69], v[196:197], v[36:37], v[68:69] neg_lo:[1,0,0] neg_hi:[1,0,0]
	v_pk_fma_f32 v[70:71], v[198:199], v[38:39], v[70:71] neg_lo:[1,0,0] neg_hi:[1,0,0]
	ds_read_b128 v[192:195], v1 offset:16976
	s_waitcnt lgkmcnt(14)
	v_pk_fma_f32 v[68:69], v[200:201], v[40:41], v[68:69] neg_lo:[1,0,0] neg_hi:[1,0,0]
	v_pk_fma_f32 v[70:71], v[202:203], v[42:43], v[70:71] neg_lo:[1,0,0] neg_hi:[1,0,0]
	ds_read_b128 v[196:199], v1 offset:16992
	s_waitcnt lgkmcnt(14)
	v_pk_fma_f32 v[68:69], v[204:205], v[44:45], v[68:69] neg_lo:[1,0,0] neg_hi:[1,0,0]
	v_pk_fma_f32 v[70:71], v[206:207], v[46:47], v[70:71] neg_lo:[1,0,0] neg_hi:[1,0,0]
	ds_read_b128 v[200:203], v1 offset:17008
	s_waitcnt lgkmcnt(14)
	v_pk_fma_f32 v[68:69], v[208:209], v[48:49], v[68:69] neg_lo:[1,0,0] neg_hi:[1,0,0]
	v_pk_fma_f32 v[70:71], v[210:211], v[50:51], v[70:71] neg_lo:[1,0,0] neg_hi:[1,0,0]
	ds_read_b128 v[204:207], v1 offset:17024
	s_waitcnt lgkmcnt(14)
	v_pk_fma_f32 v[68:69], v[212:213], v[52:53], v[68:69] neg_lo:[1,0,0] neg_hi:[1,0,0]
	v_pk_fma_f32 v[70:71], v[214:215], v[54:55], v[70:71] neg_lo:[1,0,0] neg_hi:[1,0,0]
	ds_read_b128 v[208:211], v1 offset:17040
	s_waitcnt lgkmcnt(14)
	v_pk_fma_f32 v[68:69], v[216:217], v[56:57], v[68:69] neg_lo:[1,0,0] neg_hi:[1,0,0]
	v_pk_fma_f32 v[70:71], v[218:219], v[58:59], v[70:71] neg_lo:[1,0,0] neg_hi:[1,0,0]
	ds_read_b128 v[212:215], v1 offset:17056
	s_waitcnt lgkmcnt(14)
	v_pk_fma_f32 v[68:69], v[220:221], v[60:61], v[68:69] neg_lo:[1,0,0] neg_hi:[1,0,0]
	v_pk_fma_f32 v[70:71], v[222:223], v[62:63], v[70:71] neg_lo:[1,0,0] neg_hi:[1,0,0]
	ds_read_b128 v[216:219], v1 offset:17072
	s_waitcnt lgkmcnt(14)
	v_fma_f32 v68, -v224, v64, v68
	ds_read_b128 v[220:223], v1 offset:17088
	ds_read_b128 v[224:227], v1 offset:17104
	v_add_f32_e32 v68, v68, v69
	v_add_f32_e32 v70, v70, v71
	v_add_f32_e32 v65, v68, v70
	v_mul_f32_e32 v72, v79, v65
	v_cvt_pk_bf16_f32 v72, v72, v72
	global_store_short v78, v72, s[38:39]
	v_add_u32_e32 v78, 0xc00, v78
	v_mov_b32_e32 v68, v66
	v_mov_b32_e32 v69, 0
	v_mov_b32_e32 v70, 0
	v_mov_b32_e32 v71, 0
	s_waitcnt lgkmcnt(15)
	v_pk_fma_f32 v[68:69], v[164:165], v[4:5], v[68:69] neg_lo:[1,0,0] neg_hi:[1,0,0]
	v_pk_fma_f32 v[70:71], v[166:167], v[6:7], v[70:71] neg_lo:[1,0,0] neg_hi:[1,0,0]
	s_waitcnt lgkmcnt(14)
	v_pk_fma_f32 v[68:69], v[168:169], v[8:9], v[68:69] neg_lo:[1,0,0] neg_hi:[1,0,0]
	v_pk_fma_f32 v[70:71], v[170:171], v[10:11], v[70:71] neg_lo:[1,0,0] neg_hi:[1,0,0]
	ds_read_b128 v[164:167], v1 offset:17136
	s_waitcnt lgkmcnt(14)
	v_pk_fma_f32 v[68:69], v[172:173], v[12:13], v[68:69] neg_lo:[1,0,0] neg_hi:[1,0,0]
	v_pk_fma_f32 v[70:71], v[174:175], v[14:15], v[70:71] neg_lo:[1,0,0] neg_hi:[1,0,0]
	ds_read_b128 v[168:171], v1 offset:17152
	s_waitcnt lgkmcnt(14)
	v_pk_fma_f32 v[68:69], v[176:177], v[16:17], v[68:69] neg_lo:[1,0,0] neg_hi:[1,0,0]
	v_pk_fma_f32 v[70:71], v[178:179], v[18:19], v[70:71] neg_lo:[1,0,0] neg_hi:[1,0,0]
	ds_read_b128 v[172:175], v1 offset:17168
	s_waitcnt lgkmcnt(14)
	v_pk_fma_f32 v[68:69], v[180:181], v[20:21], v[68:69] neg_lo:[1,0,0] neg_hi:[1,0,0]
	v_pk_fma_f32 v[70:71], v[182:183], v[22:23], v[70:71] neg_lo:[1,0,0] neg_hi:[1,0,0]
	ds_read_b128 v[176:179], v1 offset:17184
	s_waitcnt lgkmcnt(14)
	v_pk_fma_f32 v[68:69], v[184:185], v[24:25], v[68:69] neg_lo:[1,0,0] neg_hi:[1,0,0]
	v_pk_fma_f32 v[70:71], v[186:187], v[26:27], v[70:71] neg_lo:[1,0,0] neg_hi:[1,0,0]
	ds_read_b128 v[180:183], v1 offset:17200
	s_waitcnt lgkmcnt(14)
	v_pk_fma_f32 v[68:69], v[188:189], v[28:29], v[68:69] neg_lo:[1,0,0] neg_hi:[1,0,0]
	v_pk_fma_f32 v[70:71], v[190:191], v[30:31], v[70:71] neg_lo:[1,0,0] neg_hi:[1,0,0]
	ds_read_b128 v[184:187], v1 offset:17216
	s_waitcnt lgkmcnt(14)
	v_pk_fma_f32 v[68:69], v[192:193], v[32:33], v[68:69] neg_lo:[1,0,0] neg_hi:[1,0,0]
	v_pk_fma_f32 v[70:71], v[194:195], v[34:35], v[70:71] neg_lo:[1,0,0] neg_hi:[1,0,0]
	ds_read_b128 v[188:191], v1 offset:17232
	s_waitcnt lgkmcnt(14)
	v_pk_fma_f32 v[68:69], v[196:197], v[36:37], v[68:69] neg_lo:[1,0,0] neg_hi:[1,0,0]
	v_pk_fma_f32 v[70:71], v[198:199], v[38:39], v[70:71] neg_lo:[1,0,0] neg_hi:[1,0,0]
	ds_read_b128 v[192:195], v1 offset:17248
	s_waitcnt lgkmcnt(14)
	v_pk_fma_f32 v[68:69], v[200:201], v[40:41], v[68:69] neg_lo:[1,0,0] neg_hi:[1,0,0]
	v_pk_fma_f32 v[70:71], v[202:203], v[42:43], v[70:71] neg_lo:[1,0,0] neg_hi:[1,0,0]
	ds_read_b128 v[196:199], v1 offset:17264
	s_waitcnt lgkmcnt(14)
	v_pk_fma_f32 v[68:69], v[204:205], v[44:45], v[68:69] neg_lo:[1,0,0] neg_hi:[1,0,0]
	v_pk_fma_f32 v[70:71], v[206:207], v[46:47], v[70:71] neg_lo:[1,0,0] neg_hi:[1,0,0]
	ds_read_b128 v[200:203], v1 offset:17280
	s_waitcnt lgkmcnt(14)
	v_pk_fma_f32 v[68:69], v[208:209], v[48:49], v[68:69] neg_lo:[1,0,0] neg_hi:[1,0,0]
	v_pk_fma_f32 v[70:71], v[210:211], v[50:51], v[70:71] neg_lo:[1,0,0] neg_hi:[1,0,0]
	ds_read_b128 v[204:207], v1 offset:17296
	s_waitcnt lgkmcnt(14)
	v_pk_fma_f32 v[68:69], v[212:213], v[52:53], v[68:69] neg_lo:[1,0,0] neg_hi:[1,0,0]
	v_pk_fma_f32 v[70:71], v[214:215], v[54:55], v[70:71] neg_lo:[1,0,0] neg_hi:[1,0,0]
	ds_read_b128 v[208:211], v1 offset:17312
	s_waitcnt lgkmcnt(14)
	v_pk_fma_f32 v[68:69], v[216:217], v[56:57], v[68:69] neg_lo:[1,0,0] neg_hi:[1,0,0]
	v_pk_fma_f32 v[70:71], v[218:219], v[58:59], v[70:71] neg_lo:[1,0,0] neg_hi:[1,0,0]
	ds_read_b128 v[212:215], v1 offset:17328
	s_waitcnt lgkmcnt(14)
	v_pk_fma_f32 v[68:69], v[220:221], v[60:61], v[68:69] neg_lo:[1,0,0] neg_hi:[1,0,0]
	v_pk_fma_f32 v[70:71], v[222:223], v[62:63], v[70:71] neg_lo:[1,0,0] neg_hi:[1,0,0]
	ds_read_b128 v[216:219], v1 offset:17344
	s_waitcnt lgkmcnt(14)
	v_pk_fma_f32 v[68:69], v[224:225], v[64:65], v[68:69] neg_lo:[1,0,0] neg_hi:[1,0,0]
	ds_read_b128 v[220:223], v1 offset:17360
	ds_read_b128 v[224:227], v1 offset:17376
	v_add_f32_e32 v68, v68, v69
	v_add_f32_e32 v70, v70, v71
	v_add_f32_e32 v66, v68, v70
	v_mul_f32_e32 v72, v79, v66
	v_cvt_pk_bf16_f32 v72, v72, v72
	global_store_short v78, v72, s[38:39]
	v_add_u32_e32 v78, 0xc00, v78
	v_mov_b32_e32 v68, v67
	v_mov_b32_e32 v69, 0
	v_mov_b32_e32 v70, 0
	v_mov_b32_e32 v71, 0
	s_waitcnt lgkmcnt(15)
	v_pk_fma_f32 v[68:69], v[164:165], v[4:5], v[68:69] neg_lo:[1,0,0] neg_hi:[1,0,0]
	v_pk_fma_f32 v[70:71], v[166:167], v[6:7], v[70:71] neg_lo:[1,0,0] neg_hi:[1,0,0]
	s_waitcnt lgkmcnt(14)
	v_pk_fma_f32 v[68:69], v[168:169], v[8:9], v[68:69] neg_lo:[1,0,0] neg_hi:[1,0,0]
	v_pk_fma_f32 v[70:71], v[170:171], v[10:11], v[70:71] neg_lo:[1,0,0] neg_hi:[1,0,0]
	s_waitcnt lgkmcnt(13)
	v_pk_fma_f32 v[68:69], v[172:173], v[12:13], v[68:69] neg_lo:[1,0,0] neg_hi:[1,0,0]
	v_pk_fma_f32 v[70:71], v[174:175], v[14:15], v[70:71] neg_lo:[1,0,0] neg_hi:[1,0,0]
	s_waitcnt lgkmcnt(12)
	v_pk_fma_f32 v[68:69], v[176:177], v[16:17], v[68:69] neg_lo:[1,0,0] neg_hi:[1,0,0]
	v_pk_fma_f32 v[70:71], v[178:179], v[18:19], v[70:71] neg_lo:[1,0,0] neg_hi:[1,0,0]
	s_waitcnt lgkmcnt(11)
	v_pk_fma_f32 v[68:69], v[180:181], v[20:21], v[68:69] neg_lo:[1,0,0] neg_hi:[1,0,0]
	v_pk_fma_f32 v[70:71], v[182:183], v[22:23], v[70:71] neg_lo:[1,0,0] neg_hi:[1,0,0]
	s_waitcnt lgkmcnt(10)
	v_pk_fma_f32 v[68:69], v[184:185], v[24:25], v[68:69] neg_lo:[1,0,0] neg_hi:[1,0,0]
	v_pk_fma_f32 v[70:71], v[186:187], v[26:27], v[70:71] neg_lo:[1,0,0] neg_hi:[1,0,0]
	s_waitcnt lgkmcnt(9)
	v_pk_fma_f32 v[68:69], v[188:189], v[28:29], v[68:69] neg_lo:[1,0,0] neg_hi:[1,0,0]
	v_pk_fma_f32 v[70:71], v[190:191], v[30:31], v[70:71] neg_lo:[1,0,0] neg_hi:[1,0,0]
	s_waitcnt lgkmcnt(8)
	v_pk_fma_f32 v[68:69], v[192:193], v[32:33], v[68:69] neg_lo:[1,0,0] neg_hi:[1,0,0]
	v_pk_fma_f32 v[70:71], v[194:195], v[34:35], v[70:71] neg_lo:[1,0,0] neg_hi:[1,0,0]
	s_waitcnt lgkmcnt(7)
	v_pk_fma_f32 v[68:69], v[196:197], v[36:37], v[68:69] neg_lo:[1,0,0] neg_hi:[1,0,0]
	v_pk_fma_f32 v[70:71], v[198:199], v[38:39], v[70:71] neg_lo:[1,0,0] neg_hi:[1,0,0]
	s_waitcnt lgkmcnt(6)
	v_pk_fma_f32 v[68:69], v[200:201], v[40:41], v[68:69] neg_lo:[1,0,0] neg_hi:[1,0,0]
	v_pk_fma_f32 v[70:71], v[202:203], v[42:43], v[70:71] neg_lo:[1,0,0] neg_hi:[1,0,0]
	s_waitcnt lgkmcnt(5)
	v_pk_fma_f32 v[68:69], v[204:205], v[44:45], v[68:69] neg_lo:[1,0,0] neg_hi:[1,0,0]
	v_pk_fma_f32 v[70:71], v[206:207], v[46:47], v[70:71] neg_lo:[1,0,0] neg_hi:[1,0,0]
	s_waitcnt lgkmcnt(4)
	v_pk_fma_f32 v[68:69], v[208:209], v[48:49], v[68:69] neg_lo:[1,0,0] neg_hi:[1,0,0]
	v_pk_fma_f32 v[70:71], v[210:211], v[50:51], v[70:71] neg_lo:[1,0,0] neg_hi:[1,0,0]
	s_waitcnt lgkmcnt(3)
	v_pk_fma_f32 v[68:69], v[212:213], v[52:53], v[68:69] neg_lo:[1,0,0] neg_hi:[1,0,0]
	v_pk_fma_f32 v[70:71], v[214:215], v[54:55], v[70:71] neg_lo:[1,0,0] neg_hi:[1,0,0]
	s_waitcnt lgkmcnt(2)
	v_pk_fma_f32 v[68:69], v[216:217], v[56:57], v[68:69] neg_lo:[1,0,0] neg_hi:[1,0,0]
	v_pk_fma_f32 v[70:71], v[218:219], v[58:59], v[70:71] neg_lo:[1,0,0] neg_hi:[1,0,0]
	s_waitcnt lgkmcnt(1)
	v_pk_fma_f32 v[68:69], v[220:221], v[60:61], v[68:69] neg_lo:[1,0,0] neg_hi:[1,0,0]
	v_pk_fma_f32 v[70:71], v[222:223], v[62:63], v[70:71] neg_lo:[1,0,0] neg_hi:[1,0,0]
	s_waitcnt lgkmcnt(0)
	v_pk_fma_f32 v[68:69], v[224:225], v[64:65], v[68:69] neg_lo:[1,0,0] neg_hi:[1,0,0]
	v_fma_f32 v70, -v226, v66, v70
	v_add_f32_e32 v68, v68, v69
	v_add_f32_e32 v70, v70, v71
	v_add_f32_e32 v67, v68, v70
	v_mul_f32_e32 v72, v79, v67
	v_cvt_pk_bf16_f32 v72, v72, v72
	global_store_short v78, v72, s[38:39]
	v_add_u32_e32 v78, 0xc00, v78
	ds_read_b32 v0, v1 offset:52476
	s_mov_b64 s[0:1], exec
	v_cmp_eq_u32_e32 vcc, 0, v144
	s_waitcnt lgkmcnt(0)
	v_mul_f32_e32 v0, 0x3fb8aa3b, v0
	v_exp_f32_e32 v0, v0
	s_and_b64 exec, exec, vcc
	s_ashr_i32 s41, s40, 31
	s_lshl_b64 s[38:39], s[40:41], 2
	v_readlane_b32 s2, v239, 13
	s_add_u32 s38, s2, s38
	v_readlane_b32 s2, v239, 14
	s_addc_u32 s39, s2, s39
	s_nop 4
	global_store_dword v1, v0, s[38:39]
	s_branch .LBB0_477
